# row passes: also drop the per-row trailing vmcnt(0) (only the first in-row wait covers global loads)
# speedup vs baseline: 1.0223x; 1.0018x over previous
; DI unsigned pk2(float lo, float hi) { return f2bf(lo) | (f2bf(hi) << 16); }
; DI float lo_f(unsigned w) { return __uint_as_float(w << 16); }
; DI float hi_f(unsigned w) { return __uint_as_float(w & 0xffff0000u); }
; template <int MODE, bool FIRST, bool LAST>
; DI void phase_rowpass(const float* xin, const bf16_t* M, const float* gpost, float* outf, bf16_t* HB, bf16_t* XN, const float* gnext, int gw, int NGW, int lane) {
;     ...
;         f32x4 hv[8], mv[8]; float ss = 0.f;
; #pragma unroll
;         for (int j = 0; j < 8; ++j) { const u32x2 w = mw[j]; mv[j] = (f32x4){lo_f(w.x), hi_f(w.x), lo_f(w.y), hi_f(w.y)};
;             if constexpr (FIRST) hv[j] = hc.f[j]; else { const u32x2 hw = hc.f[j]; hv[j] = (f32x4){lo_f(hw.x), hi_f(hw.x), lo_f(hw.y), hi_f(hw.y)}; }
;             ss += (mv[j][0] * mv[j][0] + mv[j][1] * mv[j][1]) + (mv[j][2] * mv[j][2] + mv[j][3] * mv[j][3]); }
;         const float rs = rsqrtf(wave_sum(ss) * (1.f / D_) + EPS);
;         float s2 = 0.f;
; #pragma unroll
;         for (int j = 0; j < 8; ++j) { const f32x4 gv = ((const f32x4*)gpost)[lane + 64 * j]; hv[j] = hv[j] + mv[j] * rs * gv;
;             if constexpr (LAST) ((f32x4*)(outf + (size_t)row * D_) + lane)[64 * j] = hv[j];
;             else { u32x2 w; w.x = pk2(hv[j][0], hv[j][1]); w.y = pk2(hv[j][2], hv[j][3]); ((u32x2*)(HB + (size_t)row * D_) + lane)[64 * j] = w; }
.LBB0_435:
	ds_read_b128 v[144:147], v162 offset:0
	s_waitcnt vmcnt(0) lgkmcnt(0)
	v_and_b32_e32 v151, 0xffff0000, v124
	v_and_b32_e32 v150, 0xffff0000, v120
	v_and_b32_e32 v155, 0xffff0000, v125
	v_and_b32_e32 v154, 0xffff0000, v121
	v_and_b32_e32 v135, 0xffff0000, v119
	v_and_b32_e32 v134, 0xffff0000, v118
	v_lshlrev_b32_e32 v149, 16, v124
	v_lshlrev_b32_e32 v148, 16, v120
	v_lshlrev_b32_e32 v153, 16, v125
	v_lshlrev_b32_e32 v152, 16, v121
	v_pk_mul_f32 v[116:117], v[150:151], v[150:151]
	v_pk_mul_f32 v[120:121], v[154:155], v[154:155]
	v_lshlrev_b32_e32 v133, 16, v119
	v_lshlrev_b32_e32 v132, 16, v118
	v_pk_mul_f32 v[118:119], v[134:135], v[134:135]
	v_pk_fma_f32 v[116:117], v[148:149], v[148:149], v[116:117]
	v_pk_fma_f32 v[120:121], v[152:153], v[152:153], v[120:121]
	v_pk_fma_f32 v[118:119], v[132:133], v[132:133], v[118:119]
	v_pk_add_f32 v[116:117], v[116:117], v[120:121]
	v_pk_add_f32 v[120:121], v[118:119], v[118:119] op_sel_hi:[0,1]
	v_lshlrev_b32_e32 v128, 16, v114
	v_and_b32_e32 v129, 0xffff0000, v114
	v_lshlrev_b32_e32 v130, 16, v115
	v_lshlrev_b32_e32 v118, 16, v112
	v_mul_f32_e32 v119, v128, v128
	v_mul_f32_e32 v125, v129, v129
	v_and_b32_e32 v131, 0xffff0000, v115
	v_mul_f32_e32 v114, v130, v130
	v_mov_b32_e32 v124, v118
	v_pk_add_f32 v[116:117], v[116:117], v[116:117] op_sel_hi:[0,1]
	v_pk_fma_f32 v[114:115], v[130:131], v[130:131], v[114:115] op_sel_hi:[1,1,0]
	v_and_b32_e32 v160, 0xffff0000, v112
	v_lshlrev_b32_e32 v122, 16, v113
	v_and_b32_e32 v123, 0xffff0000, v113
	v_pk_add_f32 v[124:125], v[118:119], v[124:125]
	v_mul_f32_e32 v114, v160, v160
	v_mul_f32_e32 v120, v122, v122
	v_mul_f32_e32 v116, v123, v123
	v_mul_f32_e32 v112, v118, v118
	v_mov_b32_e32 v113, v125
	v_pk_add_f32 v[112:113], v[112:113], v[114:115]
	v_pk_add_f32 v[114:115], v[120:121], v[116:117]
	v_lshlrev_b32_e32 v124, 16, v108
	v_pk_add_f32 v[112:113], v[112:113], v[114:115]
	v_and_b32_e32 v115, 0xffff0000, v111
	v_and_b32_e32 v114, 0xffff0000, v110
	v_pk_add_f32 v[116:117], v[112:113], v[112:113] op_sel_hi:[0,1]
	v_lshlrev_b32_e32 v113, 16, v111
	v_lshlrev_b32_e32 v112, 16, v110
	v_pk_mul_f32 v[110:111], v[114:115], v[114:115]
	v_and_b32_e32 v125, 0xffff0000, v108
	v_pk_fma_f32 v[110:111], v[112:113], v[112:113], v[110:111]
	v_lshlrev_b32_e32 v126, 16, v109
	v_pk_add_f32 v[120:121], v[110:111], v[110:111] op_sel_hi:[0,1]
	v_lshlrev_b32_e32 v110, 16, v106
	v_mul_f32_e32 v111, v124, v124
	v_mul_f32_e32 v157, v125, v125
	v_and_b32_e32 v127, 0xffff0000, v109
	v_mul_f32_e32 v108, v126, v126
	v_mov_b32_e32 v156, v110
	v_pk_fma_f32 v[158:159], v[126:127], v[126:127], v[108:109] op_sel_hi:[1,1,0]
	v_and_b32_e32 v161, 0xffff0000, v106
	v_lshlrev_b32_e32 v108, 16, v107
	v_and_b32_e32 v109, 0xffff0000, v107
	v_pk_add_f32 v[156:157], v[110:111], v[156:157]
	v_mul_f32_e32 v158, v161, v161
	v_mul_f32_e32 v120, v108, v108
	v_mul_f32_e32 v116, v109, v109
	v_mul_f32_e32 v106, v110, v110
	v_mov_b32_e32 v107, v157
	v_pk_add_f32 v[106:107], v[106:107], v[158:159]
	v_pk_add_f32 v[116:117], v[120:121], v[116:117]
	v_mov_b32_e32 v156, v149
	v_pk_add_f32 v[106:107], v[106:107], v[116:117]
	v_mov_b32_e32 v157, v151
	v_add_f32_e32 v106, v106, v107
	ds_bpermute_b32 v107, v136, v106
	v_mov_b32_e32 v116, v153
	v_mov_b32_e32 v117, v155
	v_mov_b32_e32 v149, v150
	v_mov_b32_e32 v153, v154
	s_waitcnt lgkmcnt(0)
	v_add_f32_e32 v106, v106, v107
	ds_bpermute_b32 v107, v137, v106
	v_lshl_add_u64 v[88:89], v[88:89], 0, s[10:11]
	s_waitcnt lgkmcnt(0)
	v_add_f32_e32 v106, v106, v107
	ds_bpermute_b32 v107, v138, v106
	s_waitcnt lgkmcnt(0)
	v_add_f32_e32 v106, v106, v107
	ds_bpermute_b32 v107, v139, v106
	s_waitcnt lgkmcnt(0)
	v_add_f32_e32 v106, v106, v107
	ds_bpermute_b32 v107, v140, v106
	s_waitcnt lgkmcnt(0)
	v_add_f32_e32 v106, v106, v107
	ds_bpermute_b32 v107, v141, v106
	s_waitcnt lgkmcnt(0)
	v_add_f32_e32 v106, v106, v107
	v_fmamk_f32 v106, v106, 0x3a000000, v142
	v_mul_f32_e32 v107, 0x4b800000, v106
	v_cmp_gt_f32_e32 vcc, s3, v106
	s_nop 1
	v_cndmask_b32_e32 v106, v106, v107, vcc
	v_rsq_f32_e32 v106, v106
	s_nop 0
	v_mul_f32_e32 v107, 0x45800000, v106
	v_cndmask_b32_e32 v120, v106, v107, vcc
	v_pk_mul_f32 v[156:157], v[156:157], v[120:121] op_sel_hi:[1,0]
	v_pk_mul_f32 v[116:117], v[116:117], v[120:121] op_sel_hi:[1,0]
	v_pk_fma_f32 v[62:63], v[144:145], v[156:157], v[62:63]
	v_pk_fma_f32 v[64:65], v[146:147], v[116:117], v[64:65]
	v_and_b32_sdwa v119, v63, v143 dst_sel:DWORD dst_unused:UNUSED_PAD src0_sel:WORD_1 src1_sel:DWORD
	v_and_b32_sdwa v116, v62, v143 dst_sel:DWORD dst_unused:UNUSED_PAD src0_sel:WORD_1 src1_sel:DWORD
	v_and_b32_sdwa v117, v65, v143 dst_sel:DWORD dst_unused:UNUSED_PAD src0_sel:WORD_1 src1_sel:DWORD
	v_add3_u32 v119, v63, v119, s13
	v_lshl_add_u64 v[106:107], s[16:17], 0, v[66:67]
	v_and_b32_sdwa v111, v64, v143 dst_sel:DWORD dst_unused:UNUSED_PAD src0_sel:WORD_1 src1_sel:DWORD
	v_add3_u32 v116, v62, v116, s13
	v_add3_u32 v117, v65, v117, s13
	v_and_b32_e32 v119, 0xffff0000, v119
	v_add3_u32 v111, v64, v111, s13
	v_and_b32_e32 v117, 0xffff0000, v117
	v_or_b32_sdwa v144, v119, v116 dst_sel:DWORD dst_unused:UNUSED_PAD src0_sel:DWORD src1_sel:WORD_1
	v_add_co_u32_e32 v116, vcc, s15, v106
	v_or_b32_sdwa v145, v117, v111 dst_sel:DWORD dst_unused:UNUSED_PAD src0_sel:DWORD src1_sel:WORD_1
	s_nop 0
	v_addc_co_u32_e32 v117, vcc, 0, v107, vcc
	global_store_dwordx2 v[116:117], v[144:145], off
	s_nop 0
	ds_read_b128 v[144:147], v162 offset:1024
	v_pk_mul_f32 v[148:149], v[148:149], v[120:121] op_sel_hi:[1,0]
	v_pk_mul_f32 v[150:151], v[152:153], v[120:121] op_sel_hi:[1,0]
	s_add_u32 s16, s16, s8
	s_addc_u32 s17, s17, s9
	s_add_u32 s18, s18, s8
	s_addc_u32 s19, s19, s9
	s_waitcnt lgkmcnt(0)
; DI unsigned pk2(float lo, float hi) { return f2bf(lo) | (f2bf(hi) << 16); }
; template <int MODE, bool FIRST, bool LAST>
; DI void phase_rowpass(const float* xin, const bf16_t* M, const float* gpost, float* outf, bf16_t* HB, bf16_t* XN, const float* gnext, int gw, int NGW, int lane) {
;     ...
;         for (int j = 0; j < 8; ++j) { const f32x4 gv = ((const f32x4*)gpost)[lane + 64 * j]; hv[j] = hv[j] + mv[j] * rs * gv;
;             if constexpr (LAST) ((f32x4*)(outf + (size_t)row * D_) + lane)[64 * j] = hv[j];
;             else { u32x2 w; w.x = pk2(hv[j][0], hv[j][1]); w.y = pk2(hv[j][2], hv[j][3]); ((u32x2*)(HB + (size_t)row * D_) + lane)[64 * j] = w; }
;             s2 += (hv[j][0] * hv[j][0] + hv[j][1] * hv[j][1]) + (hv[j][2] * hv[j][2] + hv[j][3] * hv[j][3]); }
	v_pk_fma_f32 v[60:61], v[146:147], v[150:151], v[60:61]
	v_pk_fma_f32 v[58:59], v[144:145], v[148:149], v[58:59]
	v_and_b32_sdwa v121, v61, v143 dst_sel:DWORD dst_unused:UNUSED_PAD src0_sel:WORD_1 src1_sel:DWORD
	v_and_b32_sdwa v144, v59, v143 dst_sel:DWORD dst_unused:UNUSED_PAD src0_sel:WORD_1 src1_sel:DWORD
	v_and_b32_sdwa v111, v60, v143 dst_sel:DWORD dst_unused:UNUSED_PAD src0_sel:WORD_1 src1_sel:DWORD
	v_and_b32_sdwa v119, v58, v143 dst_sel:DWORD dst_unused:UNUSED_PAD src0_sel:WORD_1 src1_sel:DWORD
	v_add3_u32 v121, v61, v121, s13
	v_add3_u32 v144, v59, v144, s13
	v_add3_u32 v119, v58, v119, s13
	v_add3_u32 v111, v60, v111, s13
	v_and_b32_e32 v121, 0xffff0000, v121
	v_and_b32_e32 v144, 0xffff0000, v144
	v_or_b32_sdwa v145, v121, v111 dst_sel:DWORD dst_unused:UNUSED_PAD src0_sel:DWORD src1_sel:WORD_1
	v_or_b32_sdwa v144, v144, v119 dst_sel:DWORD dst_unused:UNUSED_PAD src0_sel:DWORD src1_sel:WORD_1
	global_store_dwordx2 v[116:117], v[144:145], off offset:512
	s_nop 0
	ds_read_b128 v[144:147], v162 offset:2048
	v_mov_b32_e32 v148, v132
	v_mov_b32_e32 v149, v134
	v_mov_b32_e32 v134, v133
	v_pk_mul_f32 v[132:133], v[120:121], v[148:149] op_sel_hi:[0,1]
	v_pk_mul_f32 v[134:135], v[120:121], v[134:135] op_sel_hi:[0,1]
	s_waitcnt lgkmcnt(0)
	v_pk_fma_f32 v[56:57], v[146:147], v[134:135], v[56:57]
	v_pk_fma_f32 v[54:55], v[144:145], v[132:133], v[54:55]
	v_and_b32_sdwa v121, v57, v143 dst_sel:DWORD dst_unused:UNUSED_PAD src0_sel:WORD_1 src1_sel:DWORD
	v_and_b32_sdwa v132, v55, v143 dst_sel:DWORD dst_unused:UNUSED_PAD src0_sel:WORD_1 src1_sel:DWORD
	v_and_b32_sdwa v111, v56, v143 dst_sel:DWORD dst_unused:UNUSED_PAD src0_sel:WORD_1 src1_sel:DWORD
	v_and_b32_sdwa v119, v54, v143 dst_sel:DWORD dst_unused:UNUSED_PAD src0_sel:WORD_1 src1_sel:DWORD
	v_add3_u32 v121, v57, v121, s13
	v_add3_u32 v132, v55, v132, s13
	v_add3_u32 v119, v54, v119, s13
	v_add3_u32 v111, v56, v111, s13
	v_and_b32_e32 v121, 0xffff0000, v121
	v_and_b32_e32 v132, 0xffff0000, v132
	v_or_b32_sdwa v133, v121, v111 dst_sel:DWORD dst_unused:UNUSED_PAD src0_sel:DWORD src1_sel:WORD_1
	v_or_b32_sdwa v132, v132, v119 dst_sel:DWORD dst_unused:UNUSED_PAD src0_sel:DWORD src1_sel:WORD_1
	global_store_dwordx2 v[116:117], v[132:133], off offset:1024
	s_nop 0
	ds_read_b128 v[132:135], v162 offset:3072
	v_pk_mul_f32 v[128:129], v[128:129], v[120:121] op_sel_hi:[1,0]
	v_pk_mul_f32 v[130:131], v[130:131], v[120:121] op_sel_hi:[1,0]
	s_waitcnt lgkmcnt(0)
	v_pk_fma_f32 v[50:51], v[132:133], v[128:129], v[50:51]
	v_pk_fma_f32 v[52:53], v[134:135], v[130:131], v[52:53]
	v_and_b32_sdwa v128, v51, v143 dst_sel:DWORD dst_unused:UNUSED_PAD src0_sel:WORD_1 src1_sel:DWORD
	v_and_b32_sdwa v121, v53, v143 dst_sel:DWORD dst_unused:UNUSED_PAD src0_sel:WORD_1 src1_sel:DWORD
	v_and_b32_sdwa v111, v52, v143 dst_sel:DWORD dst_unused:UNUSED_PAD src0_sel:WORD_1 src1_sel:DWORD
	v_and_b32_sdwa v119, v50, v143 dst_sel:DWORD dst_unused:UNUSED_PAD src0_sel:WORD_1 src1_sel:DWORD
	v_add3_u32 v121, v53, v121, s13
	v_add3_u32 v128, v51, v128, s13
	v_add3_u32 v119, v50, v119, s13
	v_add3_u32 v111, v52, v111, s13
	v_and_b32_e32 v121, 0xffff0000, v121
	v_and_b32_e32 v128, 0xffff0000, v128
	v_or_b32_sdwa v129, v121, v111 dst_sel:DWORD dst_unused:UNUSED_PAD src0_sel:DWORD src1_sel:WORD_1
	v_or_b32_sdwa v128, v128, v119 dst_sel:DWORD dst_unused:UNUSED_PAD src0_sel:DWORD src1_sel:WORD_1
	global_store_dwordx2 v[116:117], v[128:129], off offset:1536
	s_nop 0
	ds_read_b128 v[128:131], v162 offset:4096
	v_mov_b32_e32 v119, v160
	v_pk_mul_f32 v[118:119], v[118:119], v[120:121] op_sel_hi:[1,0]
	v_pk_mul_f32 v[122:123], v[122:123], v[120:121] op_sel_hi:[1,0]
	s_waitcnt lgkmcnt(0)
	v_pk_fma_f32 v[46:47], v[128:129], v[118:119], v[46:47]
	v_pk_fma_f32 v[48:49], v[130:131], v[122:123], v[48:49]
	v_and_b32_sdwa v121, v47, v143 dst_sel:DWORD dst_unused:UNUSED_PAD src0_sel:WORD_1 src1_sel:DWORD
	v_and_b32_sdwa v119, v49, v143 dst_sel:DWORD dst_unused:UNUSED_PAD src0_sel:WORD_1 src1_sel:DWORD
	v_and_b32_sdwa v111, v48, v143 dst_sel:DWORD dst_unused:UNUSED_PAD src0_sel:WORD_1 src1_sel:DWORD
	v_and_b32_sdwa v118, v46, v143 dst_sel:DWORD dst_unused:UNUSED_PAD src0_sel:WORD_1 src1_sel:DWORD
	v_add3_u32 v119, v49, v119, s13
	v_add3_u32 v121, v47, v121, s13
	v_add3_u32 v118, v46, v118, s13
	v_add3_u32 v111, v48, v111, s13
	v_and_b32_e32 v119, 0xffff0000, v119
	v_and_b32_e32 v121, 0xffff0000, v121
	v_or_b32_sdwa v119, v119, v111 dst_sel:DWORD dst_unused:UNUSED_PAD src0_sel:DWORD src1_sel:WORD_1
	v_or_b32_sdwa v118, v121, v118 dst_sel:DWORD dst_unused:UNUSED_PAD src0_sel:DWORD src1_sel:WORD_1
	global_store_dwordx2 v[116:117], v[118:119], off offset:2048
	s_nop 0
	ds_read_b128 v[128:131], v162 offset:5120
	v_mov_b32_e32 v118, v112
	v_mov_b32_e32 v119, v114
	v_mov_b32_e32 v114, v113
	v_pk_mul_f32 v[112:113], v[120:121], v[118:119] op_sel_hi:[0,1]
	v_pk_mul_f32 v[114:115], v[120:121], v[114:115] op_sel_hi:[0,1]
	v_pk_mul_f32 v[118:119], v[124:125], v[120:121] op_sel_hi:[1,0]
	v_pk_mul_f32 v[122:123], v[126:127], v[120:121] op_sel_hi:[1,0]
	v_pk_mul_f32 v[108:109], v[108:109], v[120:121] op_sel_hi:[1,0]
	v_mov_b32_e32 v124, v58
	v_mov_b32_e32 v125, v60
	s_waitcnt lgkmcnt(0)
; DI unsigned pk2(float lo, float hi) { return f2bf(lo) | (f2bf(hi) << 16); }
; template <int MODE, bool FIRST, bool LAST>
; DI void phase_rowpass(const float* xin, const bf16_t* M, const float* gpost, float* outf, bf16_t* HB, bf16_t* XN, const float* gnext, int gw, int NGW, int lane) {
;     ...
;         for (int j = 0; j < 8; ++j) { const f32x4 gv = ((const f32x4*)gpost)[lane + 64 * j]; hv[j] = hv[j] + mv[j] * rs * gv;
;             if constexpr (LAST) ((f32x4*)(outf + (size_t)row * D_) + lane)[64 * j] = hv[j];
;             else { u32x2 w; w.x = pk2(hv[j][0], hv[j][1]); w.y = pk2(hv[j][2], hv[j][3]); ((u32x2*)(HB + (size_t)row * D_) + lane)[64 * j] = w; }
;             s2 += (hv[j][0] * hv[j][0] + hv[j][1] * hv[j][1]) + (hv[j][2] * hv[j][2] + hv[j][3] * hv[j][3]); }
;         if (MODE == 1) { const float r2 = rsqrtf(wave_sum(s2) * (1.f / D_) + EPS); u32x2* o = (u32x2*)(XN + (size_t)row * D_) + lane;
	v_pk_fma_f32 v[44:45], v[130:131], v[114:115], v[44:45]
	v_pk_fma_f32 v[42:43], v[128:129], v[112:113], v[42:43]
	v_and_b32_sdwa v113, v45, v143 dst_sel:DWORD dst_unused:UNUSED_PAD src0_sel:WORD_1 src1_sel:DWORD
	v_and_b32_sdwa v114, v43, v143 dst_sel:DWORD dst_unused:UNUSED_PAD src0_sel:WORD_1 src1_sel:DWORD
	v_and_b32_sdwa v111, v44, v143 dst_sel:DWORD dst_unused:UNUSED_PAD src0_sel:WORD_1 src1_sel:DWORD
	v_and_b32_sdwa v112, v42, v143 dst_sel:DWORD dst_unused:UNUSED_PAD src0_sel:WORD_1 src1_sel:DWORD
	v_add3_u32 v113, v45, v113, s13
	v_add3_u32 v114, v43, v114, s13
	v_add3_u32 v112, v42, v112, s13
	v_add3_u32 v111, v44, v111, s13
	v_and_b32_e32 v113, 0xffff0000, v113
	v_and_b32_e32 v114, 0xffff0000, v114
	v_or_b32_sdwa v113, v113, v111 dst_sel:DWORD dst_unused:UNUSED_PAD src0_sel:DWORD src1_sel:WORD_1
	v_or_b32_sdwa v112, v114, v112 dst_sel:DWORD dst_unused:UNUSED_PAD src0_sel:DWORD src1_sel:WORD_1
	global_store_dwordx2 v[116:117], v[112:113], off offset:2560
	s_nop 0
	ds_read_b128 v[112:115], v162 offset:6144
	s_waitcnt lgkmcnt(0)
	v_pk_fma_f32 v[40:41], v[122:123], v[114:115], v[40:41]
	v_pk_fma_f32 v[38:39], v[118:119], v[112:113], v[38:39]
	v_and_b32_sdwa v113, v41, v143 dst_sel:DWORD dst_unused:UNUSED_PAD src0_sel:WORD_1 src1_sel:DWORD
	v_and_b32_sdwa v114, v39, v143 dst_sel:DWORD dst_unused:UNUSED_PAD src0_sel:WORD_1 src1_sel:DWORD
	v_and_b32_sdwa v111, v40, v143 dst_sel:DWORD dst_unused:UNUSED_PAD src0_sel:WORD_1 src1_sel:DWORD
	v_and_b32_sdwa v112, v38, v143 dst_sel:DWORD dst_unused:UNUSED_PAD src0_sel:WORD_1 src1_sel:DWORD
	v_add3_u32 v113, v41, v113, s13
	v_add3_u32 v114, v39, v114, s13
	v_add3_u32 v112, v38, v112, s13
	v_add3_u32 v111, v40, v111, s13
	v_and_b32_e32 v113, 0xffff0000, v113
	v_and_b32_e32 v114, 0xffff0000, v114
	v_or_b32_sdwa v113, v113, v111 dst_sel:DWORD dst_unused:UNUSED_PAD src0_sel:DWORD src1_sel:WORD_1
	v_or_b32_sdwa v112, v114, v112 dst_sel:DWORD dst_unused:UNUSED_PAD src0_sel:DWORD src1_sel:WORD_1
	global_store_dwordx2 v[116:117], v[112:113], off offset:3072
	s_nop 0
	ds_read_b128 v[112:115], v162 offset:7168
	v_mov_b32_e32 v111, v161
	v_pk_mul_f32 v[110:111], v[110:111], v[120:121] op_sel_hi:[1,0]
	v_mov_b32_e32 v120, v64
	v_mov_b32_e32 v121, v60
	v_mov_b32_e32 v119, v58
	v_mov_b32_e32 v58, v63
	v_pk_mul_f32 v[120:121], v[120:121], v[120:121]
	v_mov_b32_e32 v60, v65
	v_pk_mul_f32 v[122:123], v[58:59], v[58:59]
	v_pk_fma_f32 v[120:121], v[60:61], v[60:61], v[120:121]
	v_mov_b32_e32 v118, v62
	v_pk_fma_f32 v[118:119], v[118:119], v[118:119], v[122:123]
	v_pk_mul_f32 v[122:123], v[56:57], v[56:57]
	v_pk_add_f32 v[118:119], v[118:119], v[120:121]
	v_pk_mul_f32 v[120:121], v[54:55], v[54:55]
	v_pk_add_f32 v[118:119], v[118:119], v[118:119] op_sel_hi:[0,1]
	v_pk_mov_b32 v[126:127], v[120:121], v[122:123] op_sel:[1,0]
	v_mov_b32_e32 v121, v123
	v_pk_add_f32 v[120:121], v[120:121], v[126:127]
	v_mul_f32_e32 v118, v48, v48
	v_pk_add_f32 v[120:121], v[120:121], v[120:121] op_sel_hi:[0,1]
	v_mul_f32_e32 v120, v49, v49
	s_waitcnt lgkmcnt(0)
	v_pk_fma_f32 v[36:37], v[108:109], v[114:115], v[36:37]
	v_pk_fma_f32 v[34:35], v[110:111], v[112:113], v[34:35]
	v_and_b32_sdwa v108, v37, v143 dst_sel:DWORD dst_unused:UNUSED_PAD src0_sel:WORD_1 src1_sel:DWORD
	v_and_b32_sdwa v109, v35, v143 dst_sel:DWORD dst_unused:UNUSED_PAD src0_sel:WORD_1 src1_sel:DWORD
	v_and_b32_sdwa v58, v36, v143 dst_sel:DWORD dst_unused:UNUSED_PAD src0_sel:WORD_1 src1_sel:DWORD
	v_and_b32_sdwa v60, v34, v143 dst_sel:DWORD dst_unused:UNUSED_PAD src0_sel:WORD_1 src1_sel:DWORD
	v_add3_u32 v108, v37, v108, s13
	v_add3_u32 v109, v35, v109, s13
	v_add3_u32 v60, v34, v60, s13
	v_add3_u32 v58, v36, v58, s13
	v_and_b32_e32 v108, 0xffff0000, v108
	v_and_b32_e32 v110, 0xffff0000, v109
	v_or_b32_sdwa v109, v108, v58 dst_sel:DWORD dst_unused:UNUSED_PAD src0_sel:DWORD src1_sel:WORD_1
	v_or_b32_sdwa v108, v110, v60 dst_sel:DWORD dst_unused:UNUSED_PAD src0_sel:DWORD src1_sel:WORD_1
	global_store_dwordx2 v[116:117], v[108:109], off offset:3584
	s_nop 0
	ds_read_b128 v[108:111], v162 offset:8192
	v_mul_f32_e32 v58, v50, v50
	v_mul_f32_e32 v60, v52, v52
	v_pk_fma_f32 v[112:113], v[50:51], v[50:51], v[58:59] op_sel_hi:[1,1,0]
	v_pk_fma_f32 v[114:115], v[52:53], v[52:53], v[60:61] op_sel_hi:[1,1,0]
	v_mul_f32_e32 v112, v46, v46
	v_mul_f32_e32 v114, v47, v47
	v_pk_add_f32 v[112:113], v[112:113], v[114:115]
	v_pk_add_f32 v[114:115], v[120:121], v[118:119]
	v_pk_mul_f32 v[116:117], v[44:45], v[44:45]
	v_pk_add_f32 v[112:113], v[112:113], v[114:115]
	v_pk_mul_f32 v[114:115], v[42:43], v[42:43]
	v_mul_f32_e32 v58, v38, v38
	v_pk_mov_b32 v[118:119], v[114:115], v[116:117] op_sel:[1,0]
	v_mov_b32_e32 v115, v117
	v_pk_add_f32 v[114:115], v[114:115], v[118:119]
	v_mul_f32_e32 v60, v40, v40
	v_pk_add_f32 v[112:113], v[112:113], v[112:113] op_sel_hi:[0,1]
	v_pk_add_f32 v[114:115], v[114:115], v[114:115] op_sel_hi:[0,1]
	v_pk_fma_f32 v[116:117], v[38:39], v[38:39], v[58:59] op_sel_hi:[1,1,0]
	v_pk_fma_f32 v[118:119], v[40:41], v[40:41], v[60:61] op_sel_hi:[1,1,0]
	v_mul_f32_e32 v116, v34, v34
	v_mul_f32_e32 v118, v35, v35
	v_mul_f32_e32 v112, v36, v36
	v_mul_f32_e32 v114, v37, v37
	v_pk_add_f32 v[116:117], v[116:117], v[118:119]
	v_pk_add_f32 v[112:113], v[114:115], v[112:113]
	v_mov_b32_e32 v130, v34
	v_pk_add_f32 v[112:113], v[116:117], v[112:113]
	v_add_co_u32_e32 v116, vcc, s22, v106
	v_add_f32_e32 v58, v112, v113
	ds_bpermute_b32 v60, v136, v58
	v_addc_co_u32_e32 v117, vcc, 0, v107, vcc
	v_mov_b32_e32 v106, v62
	v_mov_b32_e32 v107, v64
	s_waitcnt lgkmcnt(0)
	v_add_f32_e32 v58, v58, v60
	ds_bpermute_b32 v60, v137, v58
	v_mov_b32_e32 v64, v63
	v_mov_b32_e32 v131, v36
	v_mov_b32_e32 v36, v35
	v_mov_b64_e32 v[112:113], v[104:105]
	s_waitcnt lgkmcnt(0)
; DI unsigned pk2(float lo, float hi) { return f2bf(lo) | (f2bf(hi) << 16); }
; template <int MODE, bool FIRST, bool LAST>
; DI void phase_rowpass(const float* xin, const bf16_t* M, const float* gpost, float* outf, bf16_t* HB, bf16_t* XN, const float* gnext, int gw, int NGW, int lane) {
;     ...
;         if (MODE == 1) { const float r2 = rsqrtf(wave_sum(s2) * (1.f / D_) + EPS); u32x2* o = (u32x2*)(XN + (size_t)row * D_) + lane;
; #pragma unroll
;             for (int j = 0; j < 8; ++j) { const f32x4 gv = ((const f32x4*)gnext)[lane + 64 * j]; u32x2 w; w.x = pk2(hv[j][0] * r2 * gv[0], hv[j][1] * r2 * gv[1]); w.y = pk2(hv[j][2] * r2 * gv[2], hv[j][3] * r2 * gv[3]); o[64 * j] = w; } }
	v_add_f32_e32 v58, v58, v60
	ds_bpermute_b32 v60, v138, v58
	v_mov_b64_e32 v[114:115], v[90:91]
	v_mov_b64_e32 v[118:119], v[92:93]
	v_mov_b64_e32 v[120:121], v[94:95]
	s_waitcnt lgkmcnt(0)
	v_add_f32_e32 v58, v58, v60
	ds_bpermute_b32 v60, v139, v58
	s_waitcnt lgkmcnt(0)
	v_add_f32_e32 v58, v58, v60
	ds_bpermute_b32 v60, v140, v58
	s_waitcnt lgkmcnt(0)
	v_add_f32_e32 v58, v58, v60
	ds_bpermute_b32 v60, v141, v58
	s_waitcnt lgkmcnt(0)
	v_add_f32_e32 v58, v58, v60
	v_fmamk_f32 v58, v58, 0x3a000000, v142
	v_mul_f32_e32 v60, 0x4b800000, v58
	v_cmp_gt_f32_e32 vcc, s3, v58
	s_nop 1
	v_cndmask_b32_e32 v58, v58, v60, vcc
	v_rsq_f32_e32 v58, v58
	s_nop 0
	v_mul_f32_e32 v60, 0x45800000, v58
	v_cndmask_b32_e32 v122, v58, v60, vcc
	v_pk_mul_f32 v[62:63], v[106:107], v[122:123] op_sel_hi:[1,0]
	v_pk_mul_f32 v[64:65], v[64:65], v[122:123] op_sel_hi:[1,0]
	s_waitcnt lgkmcnt(0)
	v_mov_b32_e32 v106, v108
	v_mov_b32_e32 v107, v110
	v_mov_b32_e32 v110, v109
	v_pk_mul_f32 v[62:63], v[106:107], v[62:63]
	v_pk_mul_f32 v[64:65], v[110:111], v[64:65]
	v_and_b32_sdwa v58, v63, v143 dst_sel:DWORD dst_unused:UNUSED_PAD src0_sel:WORD_1 src1_sel:DWORD
	v_and_b32_sdwa v60, v62, v143 dst_sel:DWORD dst_unused:UNUSED_PAD src0_sel:WORD_1 src1_sel:DWORD
	v_and_b32_sdwa v106, v65, v143 dst_sel:DWORD dst_unused:UNUSED_PAD src0_sel:WORD_1 src1_sel:DWORD
	v_and_b32_sdwa v107, v64, v143 dst_sel:DWORD dst_unused:UNUSED_PAD src0_sel:WORD_1 src1_sel:DWORD
	v_add3_u32 v60, v62, v60, s13
	v_add3_u32 v58, v63, v58, s13
	v_add3_u32 v62, v65, v106, s13
	v_add3_u32 v63, v64, v107, s13
	v_and_b32_e32 v62, 0xffff0000, v62
	v_and_b32_e32 v64, 0xffff0000, v63
	v_or_b32_sdwa v63, v62, v58 dst_sel:DWORD dst_unused:UNUSED_PAD src0_sel:DWORD src1_sel:WORD_1
	v_or_b32_sdwa v62, v64, v60 dst_sel:DWORD dst_unused:UNUSED_PAD src0_sel:DWORD src1_sel:WORD_1
	global_store_dwordx2 v[116:117], v[62:63], off
	s_nop 0
	ds_read_b128 v[62:65], v162 offset:9216
	v_mov_b32_e32 v60, v59
	v_pk_mul_f32 v[60:61], v[60:61], v[122:123] op_sel_hi:[1,0]
	v_pk_mul_f32 v[58:59], v[124:125], v[122:123] op_sel_hi:[1,0]
	v_pk_mul_f32 v[34:35], v[130:131], v[122:123] op_sel_hi:[1,0]
	v_pk_mul_f32 v[36:37], v[36:37], v[122:123] op_sel_hi:[1,0]
	v_mov_b64_e32 v[108:109], v[100:101]
	v_mov_b64_e32 v[110:111], v[102:103]
	v_mov_b64_e32 v[124:125], v[96:97]
	s_andn2_b64 vcc, exec, s[20:21]
	s_waitcnt lgkmcnt(0)
	v_mov_b32_e32 v107, v64
	v_mov_b32_e32 v64, v63
	v_mov_b32_e32 v106, v62
	v_pk_mul_f32 v[60:61], v[64:65], v[60:61]
	v_pk_mul_f32 v[58:59], v[106:107], v[58:59]
	v_and_b32_sdwa v64, v61, v143 dst_sel:DWORD dst_unused:UNUSED_PAD src0_sel:WORD_1 src1_sel:DWORD
	v_and_b32_sdwa v65, v60, v143 dst_sel:DWORD dst_unused:UNUSED_PAD src0_sel:WORD_1 src1_sel:DWORD
	v_and_b32_sdwa v62, v59, v143 dst_sel:DWORD dst_unused:UNUSED_PAD src0_sel:WORD_1 src1_sel:DWORD
	v_and_b32_sdwa v63, v58, v143 dst_sel:DWORD dst_unused:UNUSED_PAD src0_sel:WORD_1 src1_sel:DWORD
	v_add3_u32 v61, v61, v64, s13
	v_add3_u32 v60, v60, v65, s13
	v_add3_u32 v58, v58, v63, s13
	v_add3_u32 v59, v59, v62, s13
	v_and_b32_e32 v61, 0xffff0000, v61
	v_and_b32_e32 v60, 0xffff0000, v60
	v_or_b32_sdwa v59, v61, v59 dst_sel:DWORD dst_unused:UNUSED_PAD src0_sel:DWORD src1_sel:WORD_1
	v_or_b32_sdwa v58, v60, v58 dst_sel:DWORD dst_unused:UNUSED_PAD src0_sel:DWORD src1_sel:WORD_1
	global_store_dwordx2 v[116:117], v[58:59], off offset:512
	s_nop 0
	ds_read_b128 v[58:61], v162 offset:10240
	v_mov_b32_e32 v62, v54
	v_mov_b32_e32 v63, v56
	v_mov_b32_e32 v56, v55
	v_pk_mul_f32 v[54:55], v[62:63], v[122:123] op_sel_hi:[1,0]
	v_pk_mul_f32 v[56:57], v[56:57], v[122:123] op_sel_hi:[1,0]
	v_mov_b64_e32 v[106:107], v[98:99]
	s_waitcnt lgkmcnt(0)
	v_mov_b32_e32 v63, v60
	v_mov_b32_e32 v60, v59
	v_mov_b32_e32 v62, v58
	v_pk_mul_f32 v[56:57], v[60:61], v[56:57]
	v_pk_mul_f32 v[54:55], v[62:63], v[54:55]
	v_and_b32_sdwa v60, v57, v143 dst_sel:DWORD dst_unused:UNUSED_PAD src0_sel:WORD_1 src1_sel:DWORD
	v_and_b32_sdwa v61, v56, v143 dst_sel:DWORD dst_unused:UNUSED_PAD src0_sel:WORD_1 src1_sel:DWORD
	v_and_b32_sdwa v58, v55, v143 dst_sel:DWORD dst_unused:UNUSED_PAD src0_sel:WORD_1 src1_sel:DWORD
	v_and_b32_sdwa v59, v54, v143 dst_sel:DWORD dst_unused:UNUSED_PAD src0_sel:WORD_1 src1_sel:DWORD
	v_add3_u32 v57, v57, v60, s13
	v_add3_u32 v56, v56, v61, s13
	v_add3_u32 v54, v54, v59, s13
	v_add3_u32 v55, v55, v58, s13
	v_and_b32_e32 v57, 0xffff0000, v57
	v_and_b32_e32 v56, 0xffff0000, v56
	v_or_b32_sdwa v55, v57, v55 dst_sel:DWORD dst_unused:UNUSED_PAD src0_sel:DWORD src1_sel:WORD_1
	v_or_b32_sdwa v54, v56, v54 dst_sel:DWORD dst_unused:UNUSED_PAD src0_sel:DWORD src1_sel:WORD_1
	global_store_dwordx2 v[116:117], v[54:55], off offset:1024
	s_nop 0
	ds_read_b128 v[54:57], v162 offset:11264
	v_mov_b32_e32 v58, v50
	v_mov_b32_e32 v59, v52
	v_mov_b32_e32 v52, v51
	v_pk_mul_f32 v[50:51], v[58:59], v[122:123] op_sel_hi:[1,0]
	v_pk_mul_f32 v[52:53], v[52:53], v[122:123] op_sel_hi:[1,0]
	v_mov_b64_e32 v[64:65], v[4:5]
	v_mov_b64_e32 v[62:63], v[2:3]
	s_waitcnt lgkmcnt(0)
; DI unsigned pk2(float lo, float hi) { return f2bf(lo) | (f2bf(hi) << 16); }
; template <int MODE, bool FIRST, bool LAST>
; DI void phase_rowpass(const float* xin, const bf16_t* M, const float* gpost, float* outf, bf16_t* HB, bf16_t* XN, const float* gnext, int gw, int NGW, int lane) {
;     ...
;             for (int j = 0; j < 8; ++j) { const f32x4 gv = ((const f32x4*)gnext)[lane + 64 * j]; u32x2 w; w.x = pk2(hv[j][0] * r2 * gv[0], hv[j][1] * r2 * gv[1]); w.y = pk2(hv[j][2] * r2 * gv[2], hv[j][3] * r2 * gv[3]); o[64 * j] = w; } }
;         if (MODE == 2) { u32x2* o = (u32x2*)(XN + (size_t)row * D_) + lane;
; #pragma unroll
;             for (int j = 0; j < 8; ++j) { u32x2 w; w.x = pk2(hv[j][0], hv[j][1]); w.y = pk2(hv[j][2], hv[j][3]); o[64 * j] = w; } }
;         if (!has) break;
; #pragma unroll
;         for (int j = 0; j < 8; ++j) { hc.f[j] = hn.f[j]; mw[j] = mn[j]; }
;         row = nrow;
	v_mov_b32_e32 v59, v56
	v_mov_b32_e32 v56, v55
	v_mov_b32_e32 v58, v54
	v_pk_mul_f32 v[52:53], v[56:57], v[52:53]
	v_pk_mul_f32 v[50:51], v[58:59], v[50:51]
	v_and_b32_sdwa v56, v53, v143 dst_sel:DWORD dst_unused:UNUSED_PAD src0_sel:WORD_1 src1_sel:DWORD
	v_and_b32_sdwa v57, v52, v143 dst_sel:DWORD dst_unused:UNUSED_PAD src0_sel:WORD_1 src1_sel:DWORD
	v_and_b32_sdwa v54, v51, v143 dst_sel:DWORD dst_unused:UNUSED_PAD src0_sel:WORD_1 src1_sel:DWORD
	v_and_b32_sdwa v55, v50, v143 dst_sel:DWORD dst_unused:UNUSED_PAD src0_sel:WORD_1 src1_sel:DWORD
	v_add3_u32 v53, v53, v56, s13
	v_add3_u32 v52, v52, v57, s13
	v_add3_u32 v50, v50, v55, s13
	v_add3_u32 v51, v51, v54, s13
	v_and_b32_e32 v53, 0xffff0000, v53
	v_and_b32_e32 v52, 0xffff0000, v52
	v_or_b32_sdwa v51, v53, v51 dst_sel:DWORD dst_unused:UNUSED_PAD src0_sel:DWORD src1_sel:WORD_1
	v_or_b32_sdwa v50, v52, v50 dst_sel:DWORD dst_unused:UNUSED_PAD src0_sel:DWORD src1_sel:WORD_1
	global_store_dwordx2 v[116:117], v[50:51], off offset:1536
	s_nop 0
	ds_read_b128 v[50:53], v162 offset:12288
	v_mov_b32_e32 v54, v46
	v_mov_b32_e32 v55, v48
	v_mov_b32_e32 v48, v47
	v_pk_mul_f32 v[46:47], v[54:55], v[122:123] op_sel_hi:[1,0]
	v_pk_mul_f32 v[48:49], v[48:49], v[122:123] op_sel_hi:[1,0]
	v_mov_b64_e32 v[60:61], v[8:9]
	v_mov_b64_e32 v[58:59], v[6:7]
	s_waitcnt lgkmcnt(0)
	v_mov_b32_e32 v55, v52
	v_mov_b32_e32 v52, v51
	v_mov_b32_e32 v54, v50
	v_pk_mul_f32 v[48:49], v[52:53], v[48:49]
	v_pk_mul_f32 v[46:47], v[54:55], v[46:47]
	v_and_b32_sdwa v52, v49, v143 dst_sel:DWORD dst_unused:UNUSED_PAD src0_sel:WORD_1 src1_sel:DWORD
	v_and_b32_sdwa v53, v48, v143 dst_sel:DWORD dst_unused:UNUSED_PAD src0_sel:WORD_1 src1_sel:DWORD
	v_and_b32_sdwa v50, v47, v143 dst_sel:DWORD dst_unused:UNUSED_PAD src0_sel:WORD_1 src1_sel:DWORD
	v_and_b32_sdwa v51, v46, v143 dst_sel:DWORD dst_unused:UNUSED_PAD src0_sel:WORD_1 src1_sel:DWORD
	v_add3_u32 v49, v49, v52, s13
	v_add3_u32 v48, v48, v53, s13
	v_add3_u32 v46, v46, v51, s13
	v_add3_u32 v47, v47, v50, s13
	v_and_b32_e32 v49, 0xffff0000, v49
	v_and_b32_e32 v48, 0xffff0000, v48
	v_or_b32_sdwa v47, v49, v47 dst_sel:DWORD dst_unused:UNUSED_PAD src0_sel:DWORD src1_sel:WORD_1
	v_or_b32_sdwa v46, v48, v46 dst_sel:DWORD dst_unused:UNUSED_PAD src0_sel:DWORD src1_sel:WORD_1
	global_store_dwordx2 v[116:117], v[46:47], off offset:2048
	s_nop 0
	ds_read_b128 v[46:49], v162 offset:13312
	v_mov_b32_e32 v50, v42
	v_mov_b32_e32 v51, v44
	v_mov_b32_e32 v44, v43
	v_pk_mul_f32 v[42:43], v[50:51], v[122:123] op_sel_hi:[1,0]
	v_pk_mul_f32 v[44:45], v[44:45], v[122:123] op_sel_hi:[1,0]
	v_mov_b64_e32 v[56:57], v[12:13]
	v_mov_b64_e32 v[54:55], v[10:11]
	s_waitcnt lgkmcnt(0)
	v_mov_b32_e32 v51, v48
	v_mov_b32_e32 v48, v47
	v_mov_b32_e32 v50, v46
	v_pk_mul_f32 v[44:45], v[48:49], v[44:45]
	v_pk_mul_f32 v[42:43], v[50:51], v[42:43]
	v_and_b32_sdwa v48, v45, v143 dst_sel:DWORD dst_unused:UNUSED_PAD src0_sel:WORD_1 src1_sel:DWORD
	v_and_b32_sdwa v49, v44, v143 dst_sel:DWORD dst_unused:UNUSED_PAD src0_sel:WORD_1 src1_sel:DWORD
	v_and_b32_sdwa v46, v43, v143 dst_sel:DWORD dst_unused:UNUSED_PAD src0_sel:WORD_1 src1_sel:DWORD
	v_and_b32_sdwa v47, v42, v143 dst_sel:DWORD dst_unused:UNUSED_PAD src0_sel:WORD_1 src1_sel:DWORD
	v_add3_u32 v45, v45, v48, s13
	v_add3_u32 v44, v44, v49, s13
	v_add3_u32 v42, v42, v47, s13
	v_add3_u32 v43, v43, v46, s13
	v_and_b32_e32 v45, 0xffff0000, v45
	v_and_b32_e32 v44, 0xffff0000, v44
	v_or_b32_sdwa v43, v45, v43 dst_sel:DWORD dst_unused:UNUSED_PAD src0_sel:DWORD src1_sel:WORD_1
	v_or_b32_sdwa v42, v44, v42 dst_sel:DWORD dst_unused:UNUSED_PAD src0_sel:DWORD src1_sel:WORD_1
	global_store_dwordx2 v[116:117], v[42:43], off offset:2560
	s_nop 0
	ds_read_b128 v[42:45], v162 offset:14336
	v_mov_b32_e32 v46, v38
	v_mov_b32_e32 v47, v40
	v_mov_b32_e32 v40, v39
	v_pk_mul_f32 v[38:39], v[46:47], v[122:123] op_sel_hi:[1,0]
	v_pk_mul_f32 v[40:41], v[40:41], v[122:123] op_sel_hi:[1,0]
	v_mov_b64_e32 v[52:53], v[16:17]
	v_mov_b64_e32 v[50:51], v[14:15]
	s_waitcnt lgkmcnt(0)
	v_mov_b32_e32 v47, v44
	v_mov_b32_e32 v44, v43
	v_mov_b32_e32 v46, v42
	v_pk_mul_f32 v[40:41], v[44:45], v[40:41]
	v_pk_mul_f32 v[38:39], v[46:47], v[38:39]
	v_and_b32_sdwa v44, v41, v143 dst_sel:DWORD dst_unused:UNUSED_PAD src0_sel:WORD_1 src1_sel:DWORD
	v_and_b32_sdwa v45, v40, v143 dst_sel:DWORD dst_unused:UNUSED_PAD src0_sel:WORD_1 src1_sel:DWORD
	v_and_b32_sdwa v42, v39, v143 dst_sel:DWORD dst_unused:UNUSED_PAD src0_sel:WORD_1 src1_sel:DWORD
	v_and_b32_sdwa v43, v38, v143 dst_sel:DWORD dst_unused:UNUSED_PAD src0_sel:WORD_1 src1_sel:DWORD
	v_add3_u32 v41, v41, v44, s13
	v_add3_u32 v40, v40, v45, s13
	v_add3_u32 v38, v38, v43, s13
	v_add3_u32 v39, v39, v42, s13
	v_and_b32_e32 v41, 0xffff0000, v41
	v_and_b32_e32 v40, 0xffff0000, v40
	v_or_b32_sdwa v39, v41, v39 dst_sel:DWORD dst_unused:UNUSED_PAD src0_sel:DWORD src1_sel:WORD_1
	v_or_b32_sdwa v38, v40, v38 dst_sel:DWORD dst_unused:UNUSED_PAD src0_sel:DWORD src1_sel:WORD_1
	global_store_dwordx2 v[116:117], v[38:39], off offset:3072
	s_nop 0
	ds_read_b128 v[126:129], v162 offset:15360
	v_mov_b64_e32 v[48:49], v[20:21]
	v_mov_b64_e32 v[44:45], v[24:25]
	v_mov_b64_e32 v[40:41], v[28:29]
	v_mov_b64_e32 v[46:47], v[18:19]
	v_mov_b64_e32 v[42:43], v[22:23]
	v_mov_b64_e32 v[38:39], v[26:27]
	s_waitcnt lgkmcnt(0)
	v_mov_b32_e32 v123, v128
	v_mov_b32_e32 v128, v127
	v_mov_b32_e32 v122, v126
	v_pk_mul_f32 v[36:37], v[128:129], v[36:37]
	v_pk_mul_f32 v[34:35], v[122:123], v[34:35]
	v_and_b32_sdwa v126, v37, v143 dst_sel:DWORD dst_unused:UNUSED_PAD src0_sel:WORD_1 src1_sel:DWORD
	v_and_b32_sdwa v127, v36, v143 dst_sel:DWORD dst_unused:UNUSED_PAD src0_sel:WORD_1 src1_sel:DWORD
	v_and_b32_sdwa v122, v35, v143 dst_sel:DWORD dst_unused:UNUSED_PAD src0_sel:WORD_1 src1_sel:DWORD
	v_and_b32_sdwa v123, v34, v143 dst_sel:DWORD dst_unused:UNUSED_PAD src0_sel:WORD_1 src1_sel:DWORD
	v_add3_u32 v37, v37, v126, s13
	v_add3_u32 v36, v36, v127, s13
	v_add3_u32 v34, v34, v123, s13
	v_add3_u32 v35, v35, v122, s13
	v_and_b32_e32 v37, 0xffff0000, v37
	v_and_b32_e32 v36, 0xffff0000, v36
	v_or_b32_sdwa v35, v37, v35 dst_sel:DWORD dst_unused:UNUSED_PAD src0_sel:DWORD src1_sel:WORD_1
	v_or_b32_sdwa v34, v36, v34 dst_sel:DWORD dst_unused:UNUSED_PAD src0_sel:DWORD src1_sel:WORD_1
	global_store_dwordx2 v[116:117], v[34:35], off offset:3584
	v_mov_b64_e32 v[36:37], v[32:33]
	v_mov_b64_e32 v[34:35], v[30:31]
	s_cbranch_vccz .LBB0_438

; DI unsigned pk2(float lo, float hi) { return f2bf(lo) | (f2bf(hi) << 16); }
; DI float lo_f(unsigned w) { return __uint_as_float(w << 16); }
; DI float hi_f(unsigned w) { return __uint_as_float(w & 0xffff0000u); }
; template <int MODE, bool FIRST, bool LAST>
; DI void phase_rowpass(const float* xin, const bf16_t* M, const float* gpost, float* outf, bf16_t* HB, bf16_t* XN, const float* gnext, int gw, int NGW, int lane) {
;     ...
;         f32x4 hv[8], mv[8]; float ss = 0.f;
; #pragma unroll
;         for (int j = 0; j < 8; ++j) { const u32x2 w = mw[j]; mv[j] = (f32x4){lo_f(w.x), hi_f(w.x), lo_f(w.y), hi_f(w.y)};
;             if constexpr (FIRST) hv[j] = hc.f[j]; else { const u32x2 hw = hc.f[j]; hv[j] = (f32x4){lo_f(hw.x), hi_f(hw.x), lo_f(hw.y), hi_f(hw.y)}; }
;             ss += (mv[j][0] * mv[j][0] + mv[j][1] * mv[j][1]) + (mv[j][2] * mv[j][2] + mv[j][3] * mv[j][3]); }
;         const float rs = rsqrtf(wave_sum(ss) * (1.f / D_) + EPS);
;         float s2 = 0.f;
; #pragma unroll
;         for (int j = 0; j < 8; ++j) { const f32x4 gv = ((const f32x4*)gpost)[lane + 64 * j]; hv[j] = hv[j] + mv[j] * rs * gv;
;             if constexpr (LAST) ((f32x4*)(outf + (size_t)row * D_) + lane)[64 * j] = hv[j];
;             else { u32x2 w; w.x = pk2(hv[j][0], hv[j][1]); w.y = pk2(hv[j][2], hv[j][3]); ((u32x2*)(HB + (size_t)row * D_) + lane)[64 * j] = w; }
.LBB0_667:
	ds_read_b128 v[100:103], v118 offset:0
	s_waitcnt vmcnt(0) lgkmcnt(0)
	v_and_b32_e32 v105, 0xffff0000, v84
	v_and_b32_e32 v104, 0xffff0000, v82
	v_and_b32_e32 v109, 0xffff0000, v85
	v_and_b32_e32 v108, 0xffff0000, v83
	v_lshlrev_b32_e32 v93, 16, v84
	v_lshlrev_b32_e32 v92, 16, v82
	v_lshlrev_b32_e32 v107, 16, v85
	v_lshlrev_b32_e32 v106, 16, v83
	v_pk_mul_f32 v[66:67], v[104:105], v[104:105]
	v_pk_mul_f32 v[68:69], v[108:109], v[108:109]
	v_pk_fma_f32 v[66:67], v[92:93], v[92:93], v[66:67]
	v_pk_fma_f32 v[68:69], v[106:107], v[106:107], v[68:69]
	v_and_b32_e32 v91, 0xffff0000, v81
	v_pk_add_f32 v[66:67], v[66:67], v[68:69]
	v_and_b32_e32 v90, 0xffff0000, v80
	v_pk_add_f32 v[66:67], v[66:67], v[66:67] op_sel_hi:[0,1]
	v_lshlrev_b32_e32 v89, 16, v81
	v_lshlrev_b32_e32 v88, 16, v80
	v_pk_mul_f32 v[68:69], v[90:91], v[90:91]
	v_lshlrev_b32_e32 v82, 16, v76
	v_and_b32_e32 v83, 0xffff0000, v76
	v_lshlrev_b32_e32 v84, 16, v77
	v_lshlrev_b32_e32 v80, 16, v74
	v_pk_fma_f32 v[68:69], v[88:89], v[88:89], v[68:69]
	v_mul_f32_e32 v81, v82, v82
	v_mul_f32_e32 v79, v83, v83
	v_and_b32_e32 v85, 0xffff0000, v77
	v_mul_f32_e32 v66, v84, v84
	v_mov_b32_e32 v78, v80
	v_pk_add_f32 v[68:69], v[68:69], v[68:69] op_sel_hi:[0,1]
	v_pk_fma_f32 v[86:87], v[84:85], v[84:85], v[66:67] op_sel_hi:[1,1,0]
	v_and_b32_e32 v116, 0xffff0000, v74
	v_lshlrev_b32_e32 v76, 16, v75
	v_and_b32_e32 v77, 0xffff0000, v75
	v_pk_add_f32 v[78:79], v[80:81], v[78:79]
	v_mul_f32_e32 v86, v116, v116
	v_mul_f32_e32 v68, v76, v76
	v_mul_f32_e32 v66, v77, v77
	v_mul_f32_e32 v74, v80, v80
	v_mov_b32_e32 v75, v79
	v_pk_add_f32 v[74:75], v[74:75], v[86:87]
	v_pk_add_f32 v[66:67], v[68:69], v[66:67]
	v_lshlrev_b32_e32 v86, 16, v64
	v_pk_add_f32 v[66:67], v[74:75], v[66:67]
	v_lshlrev_b32_e32 v75, 16, v71
	v_lshlrev_b32_e32 v74, 16, v70
	v_and_b32_e32 v71, 0xffff0000, v71
	v_and_b32_e32 v70, 0xffff0000, v70
	v_pk_add_f32 v[78:79], v[66:67], v[66:67] op_sel_hi:[0,1]
	v_pk_mul_f32 v[66:67], v[70:71], v[70:71]
	v_and_b32_e32 v87, 0xffff0000, v64
	v_pk_fma_f32 v[66:67], v[74:75], v[74:75], v[66:67]
	v_lshlrev_b32_e32 v64, 16, v65
	v_pk_add_f32 v[110:111], v[66:67], v[66:67] op_sel_hi:[0,1]
	v_mul_f32_e32 v67, v86, v86
	v_and_b32_e32 v65, 0xffff0000, v65
	v_mul_f32_e32 v66, v64, v64
	v_pk_fma_f32 v[114:115], v[64:65], v[64:65], v[66:67] op_sel_hi:[1,1,0]
	v_lshlrev_b32_e32 v66, 16, v62
	v_mul_f32_e32 v113, v87, v87
	v_mov_b32_e32 v112, v66
	v_and_b32_e32 v117, 0xffff0000, v62
	v_lshlrev_b32_e32 v68, 16, v63
	v_and_b32_e32 v69, 0xffff0000, v63
	v_pk_add_f32 v[112:113], v[66:67], v[112:113]
	v_mul_f32_e32 v114, v117, v117
	v_mul_f32_e32 v110, v68, v68
	v_mul_f32_e32 v78, v69, v69
	v_mul_f32_e32 v62, v66, v66
	v_mov_b32_e32 v63, v113
	v_pk_add_f32 v[62:63], v[62:63], v[114:115]
	v_pk_add_f32 v[78:79], v[110:111], v[78:79]
	v_mov_b32_e32 v110, v93
	v_pk_add_f32 v[62:63], v[62:63], v[78:79]
	v_mov_b32_e32 v111, v105
	v_add_f32_e32 v62, v62, v63
	ds_bpermute_b32 v63, v73, v62
	v_mov_b32_e32 v112, v107
	v_mov_b32_e32 v113, v109
	v_lshl_add_u64 v[78:79], s[12:13], 0, v[2:3]
	v_mov_b32_e32 v93, v104
	s_waitcnt lgkmcnt(0)
	v_add_f32_e32 v62, v62, v63
	ds_bpermute_b32 v63, v94, v62
	v_mov_b32_e32 v107, v108
	s_add_u32 s12, s12, s14
	s_addc_u32 s13, s13, s15
	s_add_u32 s16, s16, s14
	s_waitcnt lgkmcnt(0)
	v_add_f32_e32 v62, v62, v63
	ds_bpermute_b32 v63, v95, v62
	s_addc_u32 s17, s17, s15
	s_waitcnt lgkmcnt(0)
	v_add_f32_e32 v62, v62, v63
	ds_bpermute_b32 v63, v96, v62
	s_waitcnt lgkmcnt(0)
	v_add_f32_e32 v62, v62, v63
	ds_bpermute_b32 v63, v97, v62
	s_waitcnt lgkmcnt(0)
	v_add_f32_e32 v63, v62, v63
	ds_bpermute_b32 v67, v98, v63
	v_lshlrev_b32_e32 v62, 16, v60
	s_waitcnt lgkmcnt(0)
	v_add_f32_e32 v63, v63, v67
	v_fmamk_f32 v63, v63, 0x3a000000, v99
	v_mul_f32_e32 v67, 0x4b800000, v63
	v_cmp_gt_f32_e32 vcc, s11, v63
	s_nop 1
	v_cndmask_b32_e32 v63, v63, v67, vcc
	v_rsq_f32_e32 v67, v63
	v_and_b32_e32 v63, 0xffff0000, v60
	v_lshlrev_b32_e32 v60, 16, v61
	v_and_b32_e32 v61, 0xffff0000, v61
	v_mul_f32_e32 v72, 0x45800000, v67
	v_cndmask_b32_e32 v72, v67, v72, vcc
	v_pk_mul_f32 v[110:111], v[110:111], v[72:73] op_sel_hi:[1,0]
	v_pk_mul_f32 v[112:113], v[112:113], v[72:73] op_sel_hi:[1,0]
	v_pk_fma_f32 v[62:63], v[100:101], v[110:111], v[62:63]
	v_pk_fma_f32 v[60:61], v[102:103], v[112:113], v[60:61]
	v_bfe_u32 v67, v62, 16, 1
	v_add3_u32 v62, v62, v67, s20
	v_bfe_u32 v67, v63, 16, 1
	v_lshrrev_b32_e32 v62, 16, v62
	v_add3_u32 v63, v63, v67, s20
	v_and_or_b32 v62, v63, s9, v62
	v_bfe_u32 v63, v60, 16, 1
	v_add3_u32 v60, v60, v63, s20
	v_bfe_u32 v63, v61, 16, 1
	v_lshrrev_b32_e32 v60, 16, v60
	v_add3_u32 v61, v61, v63, s20
	v_add_co_u32_e32 v78, vcc, s3, v78
	v_and_or_b32 v63, v61, s9, v60
	s_nop 0
	v_addc_co_u32_e32 v79, vcc, 0, v79, vcc
	global_store_dwordx2 v[78:79], v[62:63], off
	s_nop 0
	ds_read_b128 v[60:63], v118 offset:1024
	v_lshlrev_b32_e32 v100, 16, v58
	v_and_b32_e32 v101, 0xffff0000, v58
	v_lshlrev_b32_e32 v58, 16, v59
	v_and_b32_e32 v59, 0xffff0000, v59
	v_pk_mul_f32 v[92:93], v[92:93], v[72:73] op_sel_hi:[1,0]
	v_pk_mul_f32 v[102:103], v[106:107], v[72:73] op_sel_hi:[1,0]
	v_pk_mul_f32 v[68:69], v[68:69], v[72:73] op_sel_hi:[1,0]
	s_andn2_b64 vcc, exec, s[18:19]
	s_waitcnt lgkmcnt(0)
; DI unsigned pk2(float lo, float hi) { return f2bf(lo) | (f2bf(hi) << 16); }
; template <int MODE, bool FIRST, bool LAST>
; DI void phase_rowpass(const float* xin, const bf16_t* M, const float* gpost, float* outf, bf16_t* HB, bf16_t* XN, const float* gnext, int gw, int NGW, int lane) {
;     ...
;         for (int j = 0; j < 8; ++j) { const f32x4 gv = ((const f32x4*)gpost)[lane + 64 * j]; hv[j] = hv[j] + mv[j] * rs * gv;
;             if constexpr (LAST) ((f32x4*)(outf + (size_t)row * D_) + lane)[64 * j] = hv[j];
;             else { u32x2 w; w.x = pk2(hv[j][0], hv[j][1]); w.y = pk2(hv[j][2], hv[j][3]); ((u32x2*)(HB + (size_t)row * D_) + lane)[64 * j] = w; }
;             s2 += (hv[j][0] * hv[j][0] + hv[j][1] * hv[j][1]) + (hv[j][2] * hv[j][2] + hv[j][3] * hv[j][3]); }
;         if (MODE == 1) { const float r2 = rsqrtf(wave_sum(s2) * (1.f / D_) + EPS); u32x2* o = (u32x2*)(XN + (size_t)row * D_) + lane;
; #pragma unroll
;             for (int j = 0; j < 8; ++j) { const f32x4 gv = ((const f32x4*)gnext)[lane + 64 * j]; u32x2 w; w.x = pk2(hv[j][0] * r2 * gv[0], hv[j][1] * r2 * gv[1]); w.y = pk2(hv[j][2] * r2 * gv[2], hv[j][3] * r2 * gv[3]); o[64 * j] = w; } }
;         if (MODE == 2) { u32x2* o = (u32x2*)(XN + (size_t)row * D_) + lane;
; #pragma unroll
;             for (int j = 0; j < 8; ++j) { u32x2 w; w.x = pk2(hv[j][0], hv[j][1]); w.y = pk2(hv[j][2], hv[j][3]); o[64 * j] = w; } }
;         if (!has) break;
; #pragma unroll
;         for (int j = 0; j < 8; ++j) { hc.f[j] = hn.f[j]; mw[j] = mn[j]; }
;         row = nrow;
	v_pk_fma_f32 v[58:59], v[62:63], v[102:103], v[58:59]
	v_pk_fma_f32 v[60:61], v[60:61], v[92:93], v[100:101]
	v_bfe_u32 v67, v58, 16, 1
	v_bfe_u32 v62, v60, 16, 1
	v_bfe_u32 v63, v61, 16, 1
	v_bfe_u32 v81, v59, 16, 1
	v_add3_u32 v60, v60, v62, s20
	v_add3_u32 v58, v58, v67, s20
	v_add3_u32 v61, v61, v63, s20
	v_add3_u32 v59, v59, v81, s20
	v_lshrrev_b32_e32 v60, 16, v60
	v_lshrrev_b32_e32 v62, 16, v58
	v_and_or_b32 v58, v61, s9, v60
	v_and_or_b32 v59, v59, s9, v62
	global_store_dwordx2 v[78:79], v[58:59], off offset:512
	s_nop 0
	ds_read_b128 v[58:61], v118 offset:2048
	v_mov_b32_e32 v92, v88
	v_mov_b32_e32 v93, v90
	v_mov_b32_e32 v90, v89
	v_lshlrev_b32_e32 v62, 16, v56
	v_and_b32_e32 v63, 0xffff0000, v56
	v_lshlrev_b32_e32 v56, 16, v57
	v_and_b32_e32 v57, 0xffff0000, v57
	v_pk_mul_f32 v[88:89], v[72:73], v[92:93] op_sel_hi:[0,1]
	v_pk_mul_f32 v[90:91], v[72:73], v[90:91] op_sel_hi:[0,1]
	v_mov_b32_e32 v81, v116
	v_mov_b32_e32 v67, v117
	v_pk_mul_f32 v[66:67], v[66:67], v[72:73] op_sel_hi:[1,0]
	s_waitcnt lgkmcnt(0)
	v_pk_fma_f32 v[56:57], v[60:61], v[90:91], v[56:57]
	v_pk_fma_f32 v[58:59], v[58:59], v[88:89], v[62:63]
	v_bfe_u32 v62, v56, 16, 1
	v_bfe_u32 v60, v58, 16, 1
	v_bfe_u32 v61, v59, 16, 1
	v_bfe_u32 v63, v57, 16, 1
	v_add3_u32 v58, v58, v60, s20
	v_add3_u32 v56, v56, v62, s20
	v_add3_u32 v59, v59, v61, s20
	v_add3_u32 v57, v57, v63, s20
	v_lshrrev_b32_e32 v58, 16, v58
	v_lshrrev_b32_e32 v60, 16, v56
	v_and_or_b32 v56, v59, s9, v58
	v_and_or_b32 v57, v57, s9, v60
	global_store_dwordx2 v[78:79], v[56:57], off offset:1024
	s_nop 0
	ds_read_b128 v[56:59], v118 offset:3072
	v_lshlrev_b32_e32 v60, 16, v54
	v_and_b32_e32 v61, 0xffff0000, v54
	v_lshlrev_b32_e32 v54, 16, v55
	v_and_b32_e32 v55, 0xffff0000, v55
	v_pk_mul_f32 v[62:63], v[82:83], v[72:73] op_sel_hi:[1,0]
	v_pk_mul_f32 v[82:83], v[84:85], v[72:73] op_sel_hi:[1,0]
	v_lshlrev_b32_e32 v90, 16, v20
	v_and_b32_e32 v91, 0xffff0000, v20
	v_lshlrev_b32_e32 v20, 16, v21
	v_and_b32_e32 v21, 0xffff0000, v21
	v_mov_b64_e32 v[84:85], v[40:41]
	s_waitcnt lgkmcnt(0)
	v_pk_fma_f32 v[54:55], v[58:59], v[82:83], v[54:55]
	v_pk_fma_f32 v[56:57], v[56:57], v[62:63], v[60:61]
	v_bfe_u32 v60, v54, 16, 1
	v_bfe_u32 v58, v56, 16, 1
	v_bfe_u32 v59, v57, 16, 1
	v_bfe_u32 v61, v55, 16, 1
	v_add3_u32 v56, v56, v58, s20
	v_add3_u32 v54, v54, v60, s20
	v_add3_u32 v57, v57, v59, s20
	v_add3_u32 v55, v55, v61, s20
	v_lshrrev_b32_e32 v56, 16, v56
	v_lshrrev_b32_e32 v58, 16, v54
	v_and_or_b32 v54, v57, s9, v56
	v_and_or_b32 v55, v55, s9, v58
	global_store_dwordx2 v[78:79], v[54:55], off offset:1536
	s_nop 0
	ds_read_b128 v[54:57], v118 offset:4096
	v_lshlrev_b32_e32 v58, 16, v52
	v_and_b32_e32 v59, 0xffff0000, v52
	v_lshlrev_b32_e32 v52, 16, v53
	v_and_b32_e32 v53, 0xffff0000, v53
	v_pk_mul_f32 v[60:61], v[80:81], v[72:73] op_sel_hi:[1,0]
	v_pk_mul_f32 v[62:63], v[76:77], v[72:73] op_sel_hi:[1,0]
	v_mov_b64_e32 v[76:77], v[34:35]
	v_mov_b64_e32 v[80:81], v[36:37]
	v_mov_b64_e32 v[82:83], v[38:39]
	s_waitcnt lgkmcnt(0)
	v_pk_fma_f32 v[52:53], v[56:57], v[62:63], v[52:53]
	v_pk_fma_f32 v[54:55], v[54:55], v[60:61], v[58:59]
	v_bfe_u32 v58, v52, 16, 1
	v_bfe_u32 v56, v54, 16, 1
	v_bfe_u32 v57, v55, 16, 1
	v_bfe_u32 v59, v53, 16, 1
	v_add3_u32 v54, v54, v56, s20
	v_add3_u32 v52, v52, v58, s20
	v_add3_u32 v55, v55, v57, s20
	v_add3_u32 v53, v53, v59, s20
	v_lshrrev_b32_e32 v54, 16, v54
	v_lshrrev_b32_e32 v56, 16, v52
	v_and_or_b32 v52, v55, s9, v54
	v_and_or_b32 v53, v53, s9, v56
	global_store_dwordx2 v[78:79], v[52:53], off offset:2048
	s_nop 0
	ds_read_b128 v[52:55], v118 offset:5120
	v_mov_b32_e32 v58, v74
	v_mov_b32_e32 v59, v70
	v_mov_b32_e32 v70, v75
	v_lshlrev_b32_e32 v56, 16, v50
	v_and_b32_e32 v57, 0xffff0000, v50
	v_lshlrev_b32_e32 v50, 16, v51
	v_and_b32_e32 v51, 0xffff0000, v51
	v_pk_mul_f32 v[58:59], v[72:73], v[58:59] op_sel_hi:[0,1]
	v_pk_mul_f32 v[60:61], v[72:73], v[70:71] op_sel_hi:[0,1]
	v_mov_b64_e32 v[62:63], v[48:49]
	v_mov_b64_e32 v[70:71], v[44:45]
	v_mov_b64_e32 v[74:75], v[46:47]
	s_waitcnt lgkmcnt(0)
	v_pk_fma_f32 v[50:51], v[54:55], v[60:61], v[50:51]
	v_pk_fma_f32 v[52:53], v[52:53], v[58:59], v[56:57]
	v_bfe_u32 v56, v50, 16, 1
	v_bfe_u32 v54, v52, 16, 1
	v_bfe_u32 v55, v53, 16, 1
	v_bfe_u32 v57, v51, 16, 1
	v_add3_u32 v52, v52, v54, s20
	v_add3_u32 v50, v50, v56, s20
	v_add3_u32 v53, v53, v55, s20
	v_add3_u32 v51, v51, v57, s20
	v_lshrrev_b32_e32 v52, 16, v52
	v_lshrrev_b32_e32 v54, 16, v50
	v_and_or_b32 v50, v53, s9, v52
	v_and_or_b32 v51, v51, s9, v54
	global_store_dwordx2 v[78:79], v[50:51], off offset:2560
	s_nop 0
	ds_read_b128 v[50:53], v118 offset:6144
	v_lshlrev_b32_e32 v54, 16, v32
	v_and_b32_e32 v55, 0xffff0000, v32
	v_lshlrev_b32_e32 v32, 16, v33
	v_and_b32_e32 v33, 0xffff0000, v33
	v_pk_mul_f32 v[56:57], v[86:87], v[72:73] op_sel_hi:[1,0]
	v_pk_mul_f32 v[58:59], v[64:65], v[72:73] op_sel_hi:[1,0]
	v_mov_b64_e32 v[64:65], v[42:43]
	v_mov_b64_e32 v[60:61], v[14:15]
	s_waitcnt lgkmcnt(0)
	v_pk_fma_f32 v[32:33], v[58:59], v[52:53], v[32:33]
	v_pk_fma_f32 v[50:51], v[56:57], v[50:51], v[54:55]
	v_bfe_u32 v54, v32, 16, 1
	v_bfe_u32 v52, v50, 16, 1
	v_bfe_u32 v53, v51, 16, 1
	v_bfe_u32 v55, v33, 16, 1
	v_add3_u32 v50, v50, v52, s20
	v_add3_u32 v32, v32, v54, s20
	v_add3_u32 v51, v51, v53, s20
	v_add3_u32 v33, v33, v55, s20
	v_lshrrev_b32_e32 v50, 16, v50
	v_lshrrev_b32_e32 v52, 16, v32
	v_and_or_b32 v32, v51, s9, v50
	v_and_or_b32 v33, v33, s9, v52
	global_store_dwordx2 v[78:79], v[32:33], off offset:3072
	s_nop 0
	ds_read_b128 v[86:89], v118 offset:7168
	v_mov_b64_e32 v[58:59], v[16:17]
	v_mov_b64_e32 v[56:57], v[18:19]
	v_mov_b64_e32 v[54:55], v[22:23]
	v_mov_b64_e32 v[52:53], v[24:25]
	v_mov_b64_e32 v[50:51], v[26:27]
	v_mov_b64_e32 v[32:33], v[28:29]
	s_waitcnt lgkmcnt(0)
	v_pk_fma_f32 v[20:21], v[68:69], v[88:89], v[20:21]
	v_pk_fma_f32 v[66:67], v[66:67], v[86:87], v[90:91]
	v_bfe_u32 v72, v20, 16, 1
	v_bfe_u32 v68, v66, 16, 1
	v_bfe_u32 v69, v67, 16, 1
	v_bfe_u32 v86, v21, 16, 1
	v_add3_u32 v66, v66, v68, s20
	v_add3_u32 v20, v20, v72, s20
	v_add3_u32 v67, v67, v69, s20
	v_add3_u32 v21, v21, v86, s20
	v_lshrrev_b32_e32 v66, 16, v66
	v_lshrrev_b32_e32 v68, 16, v20
	v_and_or_b32 v20, v67, s9, v66
	v_and_or_b32 v21, v21, s9, v68
	global_store_dwordx2 v[78:79], v[20:21], off offset:3584
	v_mov_b64_e32 v[20:21], v[30:31]
	s_cbranch_vccz .LBB0_670

; DI unsigned pk2(float lo, float hi) { return f2bf(lo) | (f2bf(hi) << 16); }
; DI float lo_f(unsigned w) { return __uint_as_float(w << 16); }
; DI float hi_f(unsigned w) { return __uint_as_float(w & 0xffff0000u); }
; template <int MODE, bool FIRST, bool LAST>
; DI void phase_rowpass(const float* xin, const bf16_t* M, const float* gpost, float* outf, bf16_t* HB, bf16_t* XN, const float* gnext, int gw, int NGW, int lane) {
;     ...
;         f32x4 hv[8], mv[8]; float ss = 0.f;
; #pragma unroll
;         for (int j = 0; j < 8; ++j) { const u32x2 w = mw[j]; mv[j] = (f32x4){lo_f(w.x), hi_f(w.x), lo_f(w.y), hi_f(w.y)};
;             if constexpr (FIRST) hv[j] = hc.f[j]; else { const u32x2 hw = hc.f[j]; hv[j] = (f32x4){lo_f(hw.x), hi_f(hw.x), lo_f(hw.y), hi_f(hw.y)}; }
;             ss += (mv[j][0] * mv[j][0] + mv[j][1] * mv[j][1]) + (mv[j][2] * mv[j][2] + mv[j][3] * mv[j][3]); }
;         const float rs = rsqrtf(wave_sum(ss) * (1.f / D_) + EPS);
;         float s2 = 0.f;
; #pragma unroll
;         for (int j = 0; j < 8; ++j) { const f32x4 gv = ((const f32x4*)gpost)[lane + 64 * j]; hv[j] = hv[j] + mv[j] * rs * gv;
;             if constexpr (LAST) ((f32x4*)(outf + (size_t)row * D_) + lane)[64 * j] = hv[j];
;             else { u32x2 w; w.x = pk2(hv[j][0], hv[j][1]); w.y = pk2(hv[j][2], hv[j][3]); ((u32x2*)(HB + (size_t)row * D_) + lane)[64 * j] = w; }
.LBB0_762:
	s_waitcnt vmcnt(0)
	v_and_b32_e32 v127, 0xffff0000, v94
	v_and_b32_e32 v126, 0xffff0000, v92
	v_and_b32_e32 v129, 0xffff0000, v95
	v_and_b32_e32 v128, 0xffff0000, v93
	v_lshlrev_b32_e32 v115, 16, v94
	v_lshlrev_b32_e32 v114, 16, v92
	v_lshlrev_b32_e32 v117, 16, v95
	v_lshlrev_b32_e32 v116, 16, v93
	v_pk_mul_f32 v[88:89], v[126:127], v[126:127]
	v_pk_mul_f32 v[92:93], v[128:129], v[128:129]
	v_and_b32_e32 v113, 0xffff0000, v91
	v_and_b32_e32 v112, 0xffff0000, v90
	v_pk_fma_f32 v[88:89], v[114:115], v[114:115], v[88:89]
	v_pk_fma_f32 v[92:93], v[116:117], v[116:117], v[92:93]
	v_lshlrev_b32_e32 v111, 16, v91
	v_lshlrev_b32_e32 v110, 16, v90
	v_pk_mul_f32 v[90:91], v[112:113], v[112:113]
	v_pk_add_f32 v[88:89], v[88:89], v[92:93]
	v_pk_fma_f32 v[90:91], v[110:111], v[110:111], v[90:91]
	v_pk_add_f32 v[88:89], v[88:89], v[88:89] op_sel_hi:[0,1]
	v_pk_add_f32 v[92:93], v[90:91], v[90:91] op_sel_hi:[0,1]
	v_lshlrev_b32_e32 v108, 16, v86
	v_and_b32_e32 v109, 0xffff0000, v86
	v_lshlrev_b32_e32 v86, 16, v87
	v_lshlrev_b32_e32 v90, 16, v84
	v_mul_f32_e32 v91, v108, v108
	v_mul_f32_e32 v95, v109, v109
	v_and_b32_e32 v87, 0xffff0000, v87
	v_mul_f32_e32 v88, v86, v86
	v_mov_b32_e32 v94, v90
	v_pk_fma_f32 v[96:97], v[86:87], v[86:87], v[88:89] op_sel_hi:[1,1,0]
	v_and_b32_e32 v125, 0xffff0000, v84
	v_lshlrev_b32_e32 v100, 16, v85
	v_and_b32_e32 v101, 0xffff0000, v85
	v_pk_add_f32 v[94:95], v[90:91], v[94:95]
	v_mul_f32_e32 v96, v125, v125
	v_mul_f32_e32 v92, v100, v100
	v_mul_f32_e32 v88, v101, v101
	v_mul_f32_e32 v84, v90, v90
	v_mov_b32_e32 v85, v95
	v_pk_add_f32 v[84:85], v[84:85], v[96:97]
	v_pk_add_f32 v[88:89], v[92:93], v[88:89]
	v_lshlrev_b32_e32 v93, 16, v83
	v_pk_add_f32 v[84:85], v[84:85], v[88:89]
	v_lshlrev_b32_e32 v92, 16, v82
	v_pk_add_f32 v[98:99], v[84:85], v[84:85] op_sel_hi:[0,1]
	v_and_b32_e32 v95, 0xffff0000, v83
	v_and_b32_e32 v94, 0xffff0000, v82
	ds_read_b128 v[82:85], v135 offset:0
	v_pk_mul_f32 v[88:89], v[94:95], v[94:95]
	v_lshlrev_b32_e32 v104, 16, v80
	v_pk_fma_f32 v[88:89], v[92:93], v[92:93], v[88:89]
	v_and_b32_e32 v105, 0xffff0000, v80
	v_pk_add_f32 v[130:131], v[88:89], v[88:89] op_sel_hi:[0,1]
	v_lshlrev_b32_e32 v106, 16, v81
	v_lshlrev_b32_e32 v88, 16, v78
	v_mul_f32_e32 v89, v104, v104
	v_mul_f32_e32 v133, v105, v105
	v_and_b32_e32 v107, 0xffff0000, v81
	v_mul_f32_e32 v80, v106, v106
	v_mov_b32_e32 v132, v88
	v_pk_fma_f32 v[80:81], v[106:107], v[106:107], v[80:81] op_sel_hi:[1,1,0]
	v_and_b32_e32 v134, 0xffff0000, v78
	v_lshlrev_b32_e32 v96, 16, v79
	v_and_b32_e32 v97, 0xffff0000, v79
	v_pk_add_f32 v[132:133], v[88:89], v[132:133]
	v_mul_f32_e32 v80, v134, v134
	v_mul_f32_e32 v130, v96, v96
	v_mul_f32_e32 v98, v97, v97
	v_mul_f32_e32 v78, v88, v88
	v_mov_b32_e32 v79, v133
	v_pk_add_f32 v[78:79], v[78:79], v[80:81]
	v_pk_add_f32 v[80:81], v[130:131], v[98:99]
	v_mov_b32_e32 v130, v115
	v_pk_add_f32 v[78:79], v[78:79], v[80:81]
	v_mov_b32_e32 v131, v127
	v_add_f32_e32 v78, v78, v79
	ds_bpermute_b32 v79, v103, v78
	v_mov_b32_e32 v98, v117
	v_mov_b32_e32 v99, v129
	v_and_b32_e32 v81, 0xffff0000, v77
	v_mov_b32_e32 v115, v126
	s_waitcnt lgkmcnt(0)
	v_add_f32_e32 v78, v78, v79
	ds_bpermute_b32 v79, v118, v78
	v_mov_b32_e32 v117, v128
	v_mov_b32_e32 v126, v110
	v_mov_b32_e32 v127, v112
	v_mov_b32_e32 v112, v111
	s_waitcnt lgkmcnt(0)
	v_add_f32_e32 v78, v78, v79
	ds_bpermute_b32 v79, v119, v78
	s_waitcnt lgkmcnt(0)
	v_add_f32_e32 v78, v78, v79
	ds_bpermute_b32 v79, v120, v78
	s_waitcnt lgkmcnt(0)
	v_add_f32_e32 v78, v78, v79
	ds_bpermute_b32 v79, v121, v78
	s_waitcnt lgkmcnt(0)
	v_add_f32_e32 v79, v78, v79
	ds_bpermute_b32 v80, v122, v79
	v_lshlrev_b32_e32 v78, 16, v76
	s_waitcnt lgkmcnt(0)
	v_add_f32_e32 v79, v79, v80
	v_fmamk_f32 v79, v79, 0x3a000000, v123
	v_mul_f32_e32 v80, 0x4b800000, v79
	v_cmp_gt_f32_e32 vcc, s9, v79
	s_nop 1
	v_cndmask_b32_e32 v79, v79, v80, vcc
	v_rsq_f32_e32 v89, v79
	v_and_b32_e32 v79, 0xffff0000, v76
	v_lshlrev_b32_e32 v80, 16, v77
	v_mul_f32_e32 v76, 0x45800000, v89
	v_cndmask_b32_e32 v102, v89, v76, vcc
	v_pk_mul_f32 v[130:131], v[130:131], v[102:103] op_sel_hi:[1,0]
	v_pk_mul_f32 v[98:99], v[98:99], v[102:103] op_sel_hi:[1,0]
	v_lshl_add_u64 v[76:77], s[12:13], 0, v[2:3]
	s_waitcnt vmcnt(0) lgkmcnt(0)
	v_pk_fma_f32 v[78:79], v[82:83], v[130:131], v[78:79]
	v_pk_fma_f32 v[80:81], v[84:85], v[98:99], v[80:81]
	v_and_b32_sdwa v83, v78, v124 dst_sel:DWORD dst_unused:UNUSED_PAD src0_sel:WORD_1 src1_sel:DWORD
	v_add3_u32 v84, v78, v83, s11
	v_and_b32_sdwa v83, v81, v124 dst_sel:DWORD dst_unused:UNUSED_PAD src0_sel:WORD_1 src1_sel:DWORD
	v_and_b32_sdwa v85, v79, v124 dst_sel:DWORD dst_unused:UNUSED_PAD src0_sel:WORD_1 src1_sel:DWORD
	v_and_b32_sdwa v82, v80, v124 dst_sel:DWORD dst_unused:UNUSED_PAD src0_sel:WORD_1 src1_sel:DWORD
	v_add3_u32 v83, v81, v83, s11
	v_add3_u32 v85, v79, v85, s11
	v_add3_u32 v82, v80, v82, s11
	v_and_b32_e32 v83, 0xffff0000, v83
	v_and_b32_e32 v85, 0xffff0000, v85
	v_add_co_u32_e32 v98, vcc, s3, v76
	v_or_b32_sdwa v83, v83, v82 dst_sel:DWORD dst_unused:UNUSED_PAD src0_sel:DWORD src1_sel:WORD_1
	v_or_b32_sdwa v82, v85, v84 dst_sel:DWORD dst_unused:UNUSED_PAD src0_sel:DWORD src1_sel:WORD_1
	v_addc_co_u32_e32 v99, vcc, 0, v77, vcc
	global_store_dwordx2 v[98:99], v[82:83], off
	s_nop 0
	ds_read_b128 v[82:85], v135 offset:1024
	v_lshlrev_b32_e32 v130, 16, v74
	v_and_b32_e32 v131, 0xffff0000, v74
	v_lshlrev_b32_e32 v74, 16, v75
	v_and_b32_e32 v75, 0xffff0000, v75
	v_pk_mul_f32 v[114:115], v[114:115], v[102:103] op_sel_hi:[1,0]
	v_pk_mul_f32 v[116:117], v[116:117], v[102:103] op_sel_hi:[1,0]
	v_pk_mul_f32 v[110:111], v[102:103], v[126:127] op_sel_hi:[0,1]
	v_pk_mul_f32 v[112:113], v[102:103], v[112:113] op_sel_hi:[0,1]
	v_pk_mul_f32 v[108:109], v[108:109], v[102:103] op_sel_hi:[1,0]
	v_pk_mul_f32 v[86:87], v[86:87], v[102:103] op_sel_hi:[1,0]
	v_pk_mul_f32 v[100:101], v[100:101], v[102:103] op_sel_hi:[1,0]
	v_pk_mul_f32 v[96:97], v[96:97], v[102:103] op_sel_hi:[1,0]
	s_add_u32 s12, s12, s14
	s_addc_u32 s13, s13, s15
	s_add_u32 s16, s16, s14
	s_addc_u32 s17, s17, s15
	s_waitcnt lgkmcnt(0)
; DI unsigned pk2(float lo, float hi) { return f2bf(lo) | (f2bf(hi) << 16); }
; template <int MODE, bool FIRST, bool LAST>
; DI void phase_rowpass(const float* xin, const bf16_t* M, const float* gpost, float* outf, bf16_t* HB, bf16_t* XN, const float* gnext, int gw, int NGW, int lane) {
;     ...
;         for (int j = 0; j < 8; ++j) { const f32x4 gv = ((const f32x4*)gpost)[lane + 64 * j]; hv[j] = hv[j] + mv[j] * rs * gv;
;             if constexpr (LAST) ((f32x4*)(outf + (size_t)row * D_) + lane)[64 * j] = hv[j];
;             else { u32x2 w; w.x = pk2(hv[j][0], hv[j][1]); w.y = pk2(hv[j][2], hv[j][3]); ((u32x2*)(HB + (size_t)row * D_) + lane)[64 * j] = w; }
;             s2 += (hv[j][0] * hv[j][0] + hv[j][1] * hv[j][1]) + (hv[j][2] * hv[j][2] + hv[j][3] * hv[j][3]); }
	v_pk_fma_f32 v[74:75], v[84:85], v[116:117], v[74:75]
	v_pk_fma_f32 v[82:83], v[82:83], v[114:115], v[130:131]
	v_and_b32_sdwa v89, v75, v124 dst_sel:DWORD dst_unused:UNUSED_PAD src0_sel:WORD_1 src1_sel:DWORD
	v_and_b32_sdwa v85, v82, v124 dst_sel:DWORD dst_unused:UNUSED_PAD src0_sel:WORD_1 src1_sel:DWORD
	v_and_b32_sdwa v91, v83, v124 dst_sel:DWORD dst_unused:UNUSED_PAD src0_sel:WORD_1 src1_sel:DWORD
	v_and_b32_sdwa v84, v74, v124 dst_sel:DWORD dst_unused:UNUSED_PAD src0_sel:WORD_1 src1_sel:DWORD
	v_add3_u32 v114, v82, v85, s11
	v_add3_u32 v85, v75, v89, s11
	v_add3_u32 v89, v83, v91, s11
	v_add3_u32 v84, v74, v84, s11
	v_and_b32_e32 v85, 0xffff0000, v85
	v_and_b32_e32 v89, 0xffff0000, v89
	v_or_b32_sdwa v85, v85, v84 dst_sel:DWORD dst_unused:UNUSED_PAD src0_sel:DWORD src1_sel:WORD_1
	v_or_b32_sdwa v84, v89, v114 dst_sel:DWORD dst_unused:UNUSED_PAD src0_sel:DWORD src1_sel:WORD_1
	global_store_dwordx2 v[98:99], v[84:85], off offset:512
	s_nop 0
	ds_read_b128 v[114:117], v135 offset:2048
	v_lshlrev_b32_e32 v84, 16, v72
	v_and_b32_e32 v85, 0xffff0000, v72
	v_lshlrev_b32_e32 v72, 16, v73
	v_and_b32_e32 v73, 0xffff0000, v73
	s_waitcnt lgkmcnt(0)
	v_pk_fma_f32 v[72:73], v[116:117], v[112:113], v[72:73]
	v_pk_fma_f32 v[84:85], v[114:115], v[110:111], v[84:85]
	v_and_b32_sdwa v110, v73, v124 dst_sel:DWORD dst_unused:UNUSED_PAD src0_sel:WORD_1 src1_sel:DWORD
	v_and_b32_sdwa v111, v85, v124 dst_sel:DWORD dst_unused:UNUSED_PAD src0_sel:WORD_1 src1_sel:DWORD
	v_and_b32_sdwa v89, v72, v124 dst_sel:DWORD dst_unused:UNUSED_PAD src0_sel:WORD_1 src1_sel:DWORD
	v_and_b32_sdwa v91, v84, v124 dst_sel:DWORD dst_unused:UNUSED_PAD src0_sel:WORD_1 src1_sel:DWORD
	v_add3_u32 v110, v73, v110, s11
	v_add3_u32 v111, v85, v111, s11
	v_add3_u32 v91, v84, v91, s11
	v_add3_u32 v89, v72, v89, s11
	v_and_b32_e32 v110, 0xffff0000, v110
	v_and_b32_e32 v112, 0xffff0000, v111
	v_or_b32_sdwa v111, v110, v89 dst_sel:DWORD dst_unused:UNUSED_PAD src0_sel:DWORD src1_sel:WORD_1
	v_or_b32_sdwa v110, v112, v91 dst_sel:DWORD dst_unused:UNUSED_PAD src0_sel:DWORD src1_sel:WORD_1
	global_store_dwordx2 v[98:99], v[110:111], off offset:1024
	s_nop 0
	ds_read_b128 v[110:113], v135 offset:3072
	v_lshlrev_b32_e32 v114, 16, v70
	v_and_b32_e32 v115, 0xffff0000, v70
	v_lshlrev_b32_e32 v70, 16, v71
	v_and_b32_e32 v71, 0xffff0000, v71
	s_waitcnt lgkmcnt(0)
	v_pk_fma_f32 v[70:71], v[112:113], v[86:87], v[70:71]
	v_pk_fma_f32 v[86:87], v[110:111], v[108:109], v[114:115]
	v_and_b32_sdwa v108, v71, v124 dst_sel:DWORD dst_unused:UNUSED_PAD src0_sel:WORD_1 src1_sel:DWORD
	v_and_b32_sdwa v109, v87, v124 dst_sel:DWORD dst_unused:UNUSED_PAD src0_sel:WORD_1 src1_sel:DWORD
	v_and_b32_sdwa v89, v70, v124 dst_sel:DWORD dst_unused:UNUSED_PAD src0_sel:WORD_1 src1_sel:DWORD
	v_and_b32_sdwa v91, v86, v124 dst_sel:DWORD dst_unused:UNUSED_PAD src0_sel:WORD_1 src1_sel:DWORD
	v_add3_u32 v108, v71, v108, s11
	v_add3_u32 v109, v87, v109, s11
	v_add3_u32 v91, v86, v91, s11
	v_add3_u32 v89, v70, v89, s11
	v_and_b32_e32 v108, 0xffff0000, v108
	v_and_b32_e32 v110, 0xffff0000, v109
	v_or_b32_sdwa v109, v108, v89 dst_sel:DWORD dst_unused:UNUSED_PAD src0_sel:DWORD src1_sel:WORD_1
	v_or_b32_sdwa v108, v110, v91 dst_sel:DWORD dst_unused:UNUSED_PAD src0_sel:DWORD src1_sel:WORD_1
	global_store_dwordx2 v[98:99], v[108:109], off offset:1536
	s_nop 0
	ds_read_b128 v[108:111], v135 offset:4096
	v_mov_b32_e32 v91, v125
	v_lshlrev_b32_e32 v112, 16, v68
	v_and_b32_e32 v113, 0xffff0000, v68
	v_lshlrev_b32_e32 v68, 16, v69
	v_and_b32_e32 v69, 0xffff0000, v69
	v_pk_mul_f32 v[90:91], v[90:91], v[102:103] op_sel_hi:[1,0]
	s_waitcnt lgkmcnt(0)
	v_pk_fma_f32 v[68:69], v[110:111], v[100:101], v[68:69]
	v_pk_fma_f32 v[90:91], v[108:109], v[90:91], v[112:113]
	v_and_b32_sdwa v101, v69, v124 dst_sel:DWORD dst_unused:UNUSED_PAD src0_sel:WORD_1 src1_sel:DWORD
	v_and_b32_sdwa v108, v91, v124 dst_sel:DWORD dst_unused:UNUSED_PAD src0_sel:WORD_1 src1_sel:DWORD
	v_and_b32_sdwa v89, v68, v124 dst_sel:DWORD dst_unused:UNUSED_PAD src0_sel:WORD_1 src1_sel:DWORD
	v_and_b32_sdwa v100, v90, v124 dst_sel:DWORD dst_unused:UNUSED_PAD src0_sel:WORD_1 src1_sel:DWORD
	v_add3_u32 v101, v69, v101, s11
	v_add3_u32 v108, v91, v108, s11
	v_add3_u32 v100, v90, v100, s11
	v_add3_u32 v89, v68, v89, s11
	v_and_b32_e32 v101, 0xffff0000, v101
	v_and_b32_e32 v108, 0xffff0000, v108
	v_or_b32_sdwa v101, v101, v89 dst_sel:DWORD dst_unused:UNUSED_PAD src0_sel:DWORD src1_sel:WORD_1
	v_or_b32_sdwa v100, v108, v100 dst_sel:DWORD dst_unused:UNUSED_PAD src0_sel:DWORD src1_sel:WORD_1
	global_store_dwordx2 v[98:99], v[100:101], off offset:2048
	s_nop 0
	ds_read_b128 v[108:111], v135 offset:5120
	v_mov_b32_e32 v112, v92
	v_mov_b32_e32 v113, v94
	v_mov_b32_e32 v94, v93
	v_lshlrev_b32_e32 v100, 16, v66
	v_and_b32_e32 v101, 0xffff0000, v66
	v_lshlrev_b32_e32 v66, 16, v67
	v_and_b32_e32 v67, 0xffff0000, v67
	v_pk_mul_f32 v[92:93], v[102:103], v[112:113] op_sel_hi:[0,1]
	v_pk_mul_f32 v[94:95], v[102:103], v[94:95] op_sel_hi:[0,1]
	v_mov_b32_e32 v112, v82
	v_mov_b32_e32 v113, v74
	s_waitcnt lgkmcnt(0)
; DI unsigned pk2(float lo, float hi) { return f2bf(lo) | (f2bf(hi) << 16); }
; template <int MODE, bool FIRST, bool LAST>
; DI void phase_rowpass(const float* xin, const bf16_t* M, const float* gpost, float* outf, bf16_t* HB, bf16_t* XN, const float* gnext, int gw, int NGW, int lane) {
;     ...
;         for (int j = 0; j < 8; ++j) { const f32x4 gv = ((const f32x4*)gpost)[lane + 64 * j]; hv[j] = hv[j] + mv[j] * rs * gv;
;             if constexpr (LAST) ((f32x4*)(outf + (size_t)row * D_) + lane)[64 * j] = hv[j];
;             else { u32x2 w; w.x = pk2(hv[j][0], hv[j][1]); w.y = pk2(hv[j][2], hv[j][3]); ((u32x2*)(HB + (size_t)row * D_) + lane)[64 * j] = w; }
;             s2 += (hv[j][0] * hv[j][0] + hv[j][1] * hv[j][1]) + (hv[j][2] * hv[j][2] + hv[j][3] * hv[j][3]); }
;         if (MODE == 1) { const float r2 = rsqrtf(wave_sum(s2) * (1.f / D_) + EPS); u32x2* o = (u32x2*)(XN + (size_t)row * D_) + lane;
	v_pk_fma_f32 v[66:67], v[110:111], v[94:95], v[66:67]
	v_pk_fma_f32 v[92:93], v[108:109], v[92:93], v[100:101]
	v_and_b32_sdwa v95, v67, v124 dst_sel:DWORD dst_unused:UNUSED_PAD src0_sel:WORD_1 src1_sel:DWORD
	v_and_b32_sdwa v100, v93, v124 dst_sel:DWORD dst_unused:UNUSED_PAD src0_sel:WORD_1 src1_sel:DWORD
	v_and_b32_sdwa v89, v66, v124 dst_sel:DWORD dst_unused:UNUSED_PAD src0_sel:WORD_1 src1_sel:DWORD
	v_and_b32_sdwa v94, v92, v124 dst_sel:DWORD dst_unused:UNUSED_PAD src0_sel:WORD_1 src1_sel:DWORD
	v_add3_u32 v95, v67, v95, s11
	v_add3_u32 v100, v93, v100, s11
	v_add3_u32 v94, v92, v94, s11
	v_add3_u32 v89, v66, v89, s11
	v_and_b32_e32 v95, 0xffff0000, v95
	v_and_b32_e32 v100, 0xffff0000, v100
	v_or_b32_sdwa v95, v95, v89 dst_sel:DWORD dst_unused:UNUSED_PAD src0_sel:DWORD src1_sel:WORD_1
	v_or_b32_sdwa v94, v100, v94 dst_sel:DWORD dst_unused:UNUSED_PAD src0_sel:DWORD src1_sel:WORD_1
	global_store_dwordx2 v[98:99], v[94:95], off offset:2560
	s_nop 0
	ds_read_b128 v[108:111], v135 offset:6144
	v_lshlrev_b32_e32 v94, 16, v64
	v_and_b32_e32 v95, 0xffff0000, v64
	v_lshlrev_b32_e32 v64, 16, v65
	v_and_b32_e32 v65, 0xffff0000, v65
	v_pk_mul_f32 v[100:101], v[104:105], v[102:103] op_sel_hi:[1,0]
	v_pk_mul_f32 v[104:105], v[106:107], v[102:103] op_sel_hi:[1,0]
	s_waitcnt lgkmcnt(0)
	v_pk_fma_f32 v[94:95], v[100:101], v[108:109], v[94:95]
	v_pk_fma_f32 v[64:65], v[104:105], v[110:111], v[64:65]
	v_and_b32_sdwa v104, v95, v124 dst_sel:DWORD dst_unused:UNUSED_PAD src0_sel:WORD_1 src1_sel:DWORD
	v_and_b32_sdwa v101, v65, v124 dst_sel:DWORD dst_unused:UNUSED_PAD src0_sel:WORD_1 src1_sel:DWORD
	v_and_b32_sdwa v89, v64, v124 dst_sel:DWORD dst_unused:UNUSED_PAD src0_sel:WORD_1 src1_sel:DWORD
	v_and_b32_sdwa v100, v94, v124 dst_sel:DWORD dst_unused:UNUSED_PAD src0_sel:WORD_1 src1_sel:DWORD
	v_add3_u32 v101, v65, v101, s11
	v_add3_u32 v104, v95, v104, s11
	v_add3_u32 v100, v94, v100, s11
	v_add3_u32 v89, v64, v89, s11
	v_and_b32_e32 v101, 0xffff0000, v101
	v_and_b32_e32 v104, 0xffff0000, v104
	v_or_b32_sdwa v101, v101, v89 dst_sel:DWORD dst_unused:UNUSED_PAD src0_sel:DWORD src1_sel:WORD_1
	v_or_b32_sdwa v100, v104, v100 dst_sel:DWORD dst_unused:UNUSED_PAD src0_sel:DWORD src1_sel:WORD_1
	global_store_dwordx2 v[98:99], v[100:101], off offset:3072
	s_nop 0
	ds_read_b128 v[104:107], v135 offset:7168
	v_mov_b32_e32 v89, v134
	v_lshlrev_b32_e32 v100, 16, v62
	v_and_b32_e32 v101, 0xffff0000, v62
	v_lshlrev_b32_e32 v62, 16, v63
	v_and_b32_e32 v63, 0xffff0000, v63
	v_pk_mul_f32 v[88:89], v[88:89], v[102:103] op_sel_hi:[1,0]
	v_mov_b32_e32 v110, v80
	v_mov_b32_e32 v111, v74
	v_mov_b32_e32 v109, v82
	v_mov_b32_e32 v82, v79
	v_pk_mul_f32 v[110:111], v[110:111], v[110:111]
	v_mov_b32_e32 v74, v81
	v_pk_mul_f32 v[114:115], v[82:83], v[82:83]
	v_pk_fma_f32 v[110:111], v[74:75], v[74:75], v[110:111]
	v_mov_b32_e32 v108, v78
	v_pk_fma_f32 v[108:109], v[108:109], v[108:109], v[114:115]
	v_pk_mul_f32 v[114:115], v[72:73], v[72:73]
	v_pk_add_f32 v[108:109], v[108:109], v[110:111]
	v_pk_mul_f32 v[110:111], v[84:85], v[84:85]
	v_pk_add_f32 v[108:109], v[108:109], v[108:109] op_sel_hi:[0,1]
	v_pk_mov_b32 v[116:117], v[110:111], v[114:115] op_sel:[1,0]
	v_mov_b32_e32 v111, v115
	v_pk_add_f32 v[110:111], v[110:111], v[116:117]
	v_mul_f32_e32 v108, v68, v68
	v_pk_add_f32 v[110:111], v[110:111], v[110:111] op_sel_hi:[0,1]
	v_mul_f32_e32 v110, v69, v69
	s_waitcnt lgkmcnt(0)
	v_pk_fma_f32 v[62:63], v[96:97], v[106:107], v[62:63]
	v_pk_fma_f32 v[88:89], v[88:89], v[104:105], v[100:101]
	v_and_b32_sdwa v96, v63, v124 dst_sel:DWORD dst_unused:UNUSED_PAD src0_sel:WORD_1 src1_sel:DWORD
	v_and_b32_sdwa v97, v89, v124 dst_sel:DWORD dst_unused:UNUSED_PAD src0_sel:WORD_1 src1_sel:DWORD
	v_and_b32_sdwa v74, v62, v124 dst_sel:DWORD dst_unused:UNUSED_PAD src0_sel:WORD_1 src1_sel:DWORD
	v_and_b32_sdwa v82, v88, v124 dst_sel:DWORD dst_unused:UNUSED_PAD src0_sel:WORD_1 src1_sel:DWORD
	v_add3_u32 v96, v63, v96, s11
	v_add3_u32 v97, v89, v97, s11
	v_add3_u32 v82, v88, v82, s11
	v_add3_u32 v74, v62, v74, s11
	v_and_b32_e32 v96, 0xffff0000, v96
	v_and_b32_e32 v100, 0xffff0000, v97
	v_or_b32_sdwa v97, v96, v74 dst_sel:DWORD dst_unused:UNUSED_PAD src0_sel:DWORD src1_sel:WORD_1
	v_or_b32_sdwa v96, v100, v82 dst_sel:DWORD dst_unused:UNUSED_PAD src0_sel:DWORD src1_sel:WORD_1
	global_store_dwordx2 v[98:99], v[96:97], off offset:3584
	s_nop 0
	ds_read_b128 v[104:107], v135 offset:8192
	v_mul_f32_e32 v74, v86, v86
	v_mul_f32_e32 v82, v70, v70
	v_pk_fma_f32 v[96:97], v[86:87], v[86:87], v[74:75] op_sel_hi:[1,1,0]
	v_pk_fma_f32 v[98:99], v[70:71], v[70:71], v[82:83] op_sel_hi:[1,1,0]
	v_mul_f32_e32 v96, v90, v90
	v_mul_f32_e32 v98, v91, v91
	v_pk_add_f32 v[96:97], v[96:97], v[98:99]
	v_pk_add_f32 v[98:99], v[110:111], v[108:109]
	v_pk_mul_f32 v[100:101], v[66:67], v[66:67]
	v_pk_add_f32 v[96:97], v[96:97], v[98:99]
	v_pk_mul_f32 v[98:99], v[92:93], v[92:93]
	v_mul_f32_e32 v74, v94, v94
	v_pk_mov_b32 v[108:109], v[98:99], v[100:101] op_sel:[1,0]
	v_mov_b32_e32 v99, v101
	v_pk_add_f32 v[98:99], v[98:99], v[108:109]
	v_mul_f32_e32 v82, v64, v64
	v_pk_add_f32 v[96:97], v[96:97], v[96:97] op_sel_hi:[0,1]
	v_pk_add_f32 v[98:99], v[98:99], v[98:99] op_sel_hi:[0,1]
	v_pk_fma_f32 v[100:101], v[94:95], v[94:95], v[74:75] op_sel_hi:[1,1,0]
	v_pk_fma_f32 v[108:109], v[64:65], v[64:65], v[82:83] op_sel_hi:[1,1,0]
	v_mul_f32_e32 v100, v88, v88
	v_mul_f32_e32 v108, v89, v89
	v_mul_f32_e32 v96, v62, v62
	v_mul_f32_e32 v98, v63, v63
	v_pk_add_f32 v[100:101], v[100:101], v[108:109]
	v_pk_add_f32 v[96:97], v[98:99], v[96:97]
	s_nop 0
	v_pk_add_f32 v[96:97], v[100:101], v[96:97]
	v_mov_b32_e32 v100, v88
	v_add_f32_e32 v74, v96, v97
	ds_bpermute_b32 v82, v103, v74
	v_add_co_u32_e32 v96, vcc, s20, v76
	v_mov_b32_e32 v76, v78
	s_nop 0
	v_addc_co_u32_e32 v97, vcc, 0, v77, vcc
	s_waitcnt lgkmcnt(0)
; DI unsigned pk2(float lo, float hi) { return f2bf(lo) | (f2bf(hi) << 16); }
; template <int MODE, bool FIRST, bool LAST>
; DI void phase_rowpass(const float* xin, const bf16_t* M, const float* gpost, float* outf, bf16_t* HB, bf16_t* XN, const float* gnext, int gw, int NGW, int lane) {
;     ...
;         if (MODE == 1) { const float r2 = rsqrtf(wave_sum(s2) * (1.f / D_) + EPS); u32x2* o = (u32x2*)(XN + (size_t)row * D_) + lane;
; #pragma unroll
;             for (int j = 0; j < 8; ++j) { const f32x4 gv = ((const f32x4*)gnext)[lane + 64 * j]; u32x2 w; w.x = pk2(hv[j][0] * r2 * gv[0], hv[j][1] * r2 * gv[1]); w.y = pk2(hv[j][2] * r2 * gv[2], hv[j][3] * r2 * gv[3]); o[64 * j] = w; } }
	v_add_f32_e32 v74, v74, v82
	ds_bpermute_b32 v82, v118, v74
	v_mov_b32_e32 v101, v62
	v_mov_b32_e32 v62, v89
	s_waitcnt lgkmcnt(0)
	v_add_f32_e32 v74, v74, v82
	ds_bpermute_b32 v82, v119, v74
	s_waitcnt lgkmcnt(0)
	v_add_f32_e32 v74, v74, v82
	ds_bpermute_b32 v82, v120, v74
	s_waitcnt lgkmcnt(0)
	v_add_f32_e32 v74, v74, v82
	ds_bpermute_b32 v82, v121, v74
	s_waitcnt lgkmcnt(0)
	v_add_f32_e32 v74, v74, v82
	ds_bpermute_b32 v82, v122, v74
	s_waitcnt lgkmcnt(0)
	v_add_f32_e32 v74, v74, v82
	v_fmamk_f32 v74, v74, 0x3a000000, v123
	v_mul_f32_e32 v77, 0x4b800000, v74
	v_cmp_gt_f32_e32 vcc, s9, v74
	s_nop 1
	v_cndmask_b32_e32 v74, v74, v77, vcc
	v_rsq_f32_e32 v74, v74
	v_mov_b32_e32 v77, v80
	v_mov_b32_e32 v80, v79
	v_mul_f32_e32 v78, 0x45800000, v74
	v_cndmask_b32_e32 v98, v74, v78, vcc
	v_pk_mul_f32 v[76:77], v[76:77], v[98:99] op_sel_hi:[1,0]
	v_pk_mul_f32 v[78:79], v[80:81], v[98:99] op_sel_hi:[1,0]
	s_waitcnt lgkmcnt(0)
	v_mov_b32_e32 v80, v104
	v_mov_b32_e32 v81, v106
	v_mov_b32_e32 v106, v105
	v_pk_mul_f32 v[76:77], v[80:81], v[76:77]
	v_pk_mul_f32 v[78:79], v[106:107], v[78:79]
	v_and_b32_sdwa v74, v77, v124 dst_sel:DWORD dst_unused:UNUSED_PAD src0_sel:WORD_1 src1_sel:DWORD
	v_and_b32_sdwa v81, v79, v124 dst_sel:DWORD dst_unused:UNUSED_PAD src0_sel:WORD_1 src1_sel:DWORD
	v_and_b32_sdwa v82, v78, v124 dst_sel:DWORD dst_unused:UNUSED_PAD src0_sel:WORD_1 src1_sel:DWORD
	v_and_b32_sdwa v80, v76, v124 dst_sel:DWORD dst_unused:UNUSED_PAD src0_sel:WORD_1 src1_sel:DWORD
	v_add3_u32 v74, v77, v74, s11
	v_add3_u32 v77, v79, v81, s11
	v_add3_u32 v78, v78, v82, s11
	v_add3_u32 v76, v76, v80, s11
	v_and_b32_e32 v77, 0xffff0000, v77
	v_and_b32_e32 v78, 0xffff0000, v78
	v_or_b32_sdwa v77, v77, v74 dst_sel:DWORD dst_unused:UNUSED_PAD src0_sel:DWORD src1_sel:WORD_1
	v_or_b32_sdwa v76, v78, v76 dst_sel:DWORD dst_unused:UNUSED_PAD src0_sel:DWORD src1_sel:WORD_1
	global_store_dwordx2 v[96:97], v[76:77], off
	s_nop 0
	ds_read_b128 v[76:79], v135 offset:9216
	v_mov_b32_e32 v74, v83
	v_pk_mul_f32 v[74:75], v[74:75], v[98:99] op_sel_hi:[1,0]
	v_pk_mul_f32 v[80:81], v[112:113], v[98:99] op_sel_hi:[1,0]
	v_pk_mul_f32 v[88:89], v[100:101], v[98:99] op_sel_hi:[1,0]
	v_pk_mul_f32 v[62:63], v[62:63], v[98:99] op_sel_hi:[1,0]
	s_andn2_b64 vcc, exec, s[18:19]
	s_waitcnt lgkmcnt(0)
	v_mov_b32_e32 v83, v78
	v_mov_b32_e32 v78, v77
	v_mov_b32_e32 v82, v76
	v_pk_mul_f32 v[74:75], v[78:79], v[74:75]
	v_pk_mul_f32 v[76:77], v[82:83], v[80:81]
	v_and_b32_sdwa v80, v75, v124 dst_sel:DWORD dst_unused:UNUSED_PAD src0_sel:WORD_1 src1_sel:DWORD
	v_and_b32_sdwa v81, v74, v124 dst_sel:DWORD dst_unused:UNUSED_PAD src0_sel:WORD_1 src1_sel:DWORD
	v_and_b32_sdwa v78, v77, v124 dst_sel:DWORD dst_unused:UNUSED_PAD src0_sel:WORD_1 src1_sel:DWORD
	v_and_b32_sdwa v79, v76, v124 dst_sel:DWORD dst_unused:UNUSED_PAD src0_sel:WORD_1 src1_sel:DWORD
	v_add3_u32 v75, v75, v80, s11
	v_add3_u32 v74, v74, v81, s11
	v_add3_u32 v76, v76, v79, s11
	v_add3_u32 v77, v77, v78, s11
	v_and_b32_e32 v75, 0xffff0000, v75
	v_and_b32_e32 v74, 0xffff0000, v74
	v_or_b32_sdwa v75, v75, v77 dst_sel:DWORD dst_unused:UNUSED_PAD src0_sel:DWORD src1_sel:WORD_1
	v_or_b32_sdwa v74, v74, v76 dst_sel:DWORD dst_unused:UNUSED_PAD src0_sel:DWORD src1_sel:WORD_1
	global_store_dwordx2 v[96:97], v[74:75], off offset:512
	s_nop 0
	ds_read_b128 v[74:77], v135 offset:10240
	v_mov_b32_e32 v79, v72
	v_mov_b32_e32 v72, v85
	v_mov_b32_e32 v78, v84
	v_pk_mul_f32 v[72:73], v[72:73], v[98:99] op_sel_hi:[1,0]
	v_pk_mul_f32 v[78:79], v[78:79], v[98:99] op_sel_hi:[1,0]
	v_mov_b64_e32 v[82:83], v[56:57]
	v_mov_b64_e32 v[84:85], v[58:59]
	s_waitcnt lgkmcnt(0)
	v_mov_b32_e32 v81, v76
	v_mov_b32_e32 v76, v75
	v_mov_b32_e32 v80, v74
	v_pk_mul_f32 v[72:73], v[76:77], v[72:73]
	v_pk_mul_f32 v[74:75], v[80:81], v[78:79]
	v_and_b32_sdwa v78, v73, v124 dst_sel:DWORD dst_unused:UNUSED_PAD src0_sel:WORD_1 src1_sel:DWORD
	v_and_b32_sdwa v79, v72, v124 dst_sel:DWORD dst_unused:UNUSED_PAD src0_sel:WORD_1 src1_sel:DWORD
	v_and_b32_sdwa v76, v75, v124 dst_sel:DWORD dst_unused:UNUSED_PAD src0_sel:WORD_1 src1_sel:DWORD
	v_and_b32_sdwa v77, v74, v124 dst_sel:DWORD dst_unused:UNUSED_PAD src0_sel:WORD_1 src1_sel:DWORD
	v_add3_u32 v73, v73, v78, s11
	v_add3_u32 v72, v72, v79, s11
	v_add3_u32 v74, v74, v77, s11
	v_add3_u32 v75, v75, v76, s11
	v_and_b32_e32 v73, 0xffff0000, v73
	v_and_b32_e32 v72, 0xffff0000, v72
	v_or_b32_sdwa v73, v73, v75 dst_sel:DWORD dst_unused:UNUSED_PAD src0_sel:DWORD src1_sel:WORD_1
	v_or_b32_sdwa v72, v72, v74 dst_sel:DWORD dst_unused:UNUSED_PAD src0_sel:DWORD src1_sel:WORD_1
	global_store_dwordx2 v[96:97], v[72:73], off offset:1024
	s_nop 0
	ds_read_b128 v[72:75], v135 offset:11264
	v_mov_b32_e32 v77, v70
	v_mov_b32_e32 v70, v87
	v_mov_b32_e32 v76, v86
	v_pk_mul_f32 v[70:71], v[70:71], v[98:99] op_sel_hi:[1,0]
	v_pk_mul_f32 v[76:77], v[76:77], v[98:99] op_sel_hi:[1,0]
	v_mov_b64_e32 v[80:81], v[54:55]
	v_mov_b64_e32 v[86:87], v[46:47]
	s_waitcnt lgkmcnt(0)
	v_mov_b32_e32 v79, v74
	v_mov_b32_e32 v74, v73
	v_mov_b32_e32 v78, v72
	v_pk_mul_f32 v[70:71], v[74:75], v[70:71]
	v_pk_mul_f32 v[72:73], v[78:79], v[76:77]
	v_and_b32_sdwa v76, v71, v124 dst_sel:DWORD dst_unused:UNUSED_PAD src0_sel:WORD_1 src1_sel:DWORD
	v_and_b32_sdwa v77, v70, v124 dst_sel:DWORD dst_unused:UNUSED_PAD src0_sel:WORD_1 src1_sel:DWORD
	v_and_b32_sdwa v74, v73, v124 dst_sel:DWORD dst_unused:UNUSED_PAD src0_sel:WORD_1 src1_sel:DWORD
	v_and_b32_sdwa v75, v72, v124 dst_sel:DWORD dst_unused:UNUSED_PAD src0_sel:WORD_1 src1_sel:DWORD
	v_add3_u32 v71, v71, v76, s11
	v_add3_u32 v70, v70, v77, s11
	v_add3_u32 v72, v72, v75, s11
	v_add3_u32 v73, v73, v74, s11
	v_and_b32_e32 v71, 0xffff0000, v71
	v_and_b32_e32 v70, 0xffff0000, v70
	v_or_b32_sdwa v71, v71, v73 dst_sel:DWORD dst_unused:UNUSED_PAD src0_sel:DWORD src1_sel:WORD_1
	v_or_b32_sdwa v70, v70, v72 dst_sel:DWORD dst_unused:UNUSED_PAD src0_sel:DWORD src1_sel:WORD_1
	global_store_dwordx2 v[96:97], v[70:71], off offset:1536
	s_nop 0
	ds_read_b128 v[70:73], v135 offset:12288
	v_mov_b32_e32 v75, v68
	v_mov_b32_e32 v68, v91
	v_mov_b32_e32 v74, v90
	v_pk_mul_f32 v[68:69], v[68:69], v[98:99] op_sel_hi:[1,0]
	v_pk_mul_f32 v[74:75], v[74:75], v[98:99] op_sel_hi:[1,0]
	v_mov_b64_e32 v[78:79], v[60:61]
	v_mov_b64_e32 v[90:91], v[48:49]
	s_waitcnt lgkmcnt(0)
; DI unsigned pk2(float lo, float hi) { return f2bf(lo) | (f2bf(hi) << 16); }
; template <int MODE, bool FIRST, bool LAST>
; DI void phase_rowpass(const float* xin, const bf16_t* M, const float* gpost, float* outf, bf16_t* HB, bf16_t* XN, const float* gnext, int gw, int NGW, int lane) {
;     ...
;             for (int j = 0; j < 8; ++j) { const f32x4 gv = ((const f32x4*)gnext)[lane + 64 * j]; u32x2 w; w.x = pk2(hv[j][0] * r2 * gv[0], hv[j][1] * r2 * gv[1]); w.y = pk2(hv[j][2] * r2 * gv[2], hv[j][3] * r2 * gv[3]); o[64 * j] = w; } }
;         if (MODE == 2) { u32x2* o = (u32x2*)(XN + (size_t)row * D_) + lane;
; #pragma unroll
;             for (int j = 0; j < 8; ++j) { u32x2 w; w.x = pk2(hv[j][0], hv[j][1]); w.y = pk2(hv[j][2], hv[j][3]); o[64 * j] = w; } }
;         if (!has) break;
; #pragma unroll
;         for (int j = 0; j < 8; ++j) { hc.f[j] = hn.f[j]; mw[j] = mn[j]; }
;         row = nrow;
	v_mov_b32_e32 v77, v72
	v_mov_b32_e32 v72, v71
	v_mov_b32_e32 v76, v70
	v_pk_mul_f32 v[68:69], v[72:73], v[68:69]
	v_pk_mul_f32 v[70:71], v[76:77], v[74:75]
	v_and_b32_sdwa v74, v69, v124 dst_sel:DWORD dst_unused:UNUSED_PAD src0_sel:WORD_1 src1_sel:DWORD
	v_and_b32_sdwa v75, v68, v124 dst_sel:DWORD dst_unused:UNUSED_PAD src0_sel:WORD_1 src1_sel:DWORD
	v_and_b32_sdwa v72, v71, v124 dst_sel:DWORD dst_unused:UNUSED_PAD src0_sel:WORD_1 src1_sel:DWORD
	v_and_b32_sdwa v73, v70, v124 dst_sel:DWORD dst_unused:UNUSED_PAD src0_sel:WORD_1 src1_sel:DWORD
	v_add3_u32 v69, v69, v74, s11
	v_add3_u32 v68, v68, v75, s11
	v_add3_u32 v70, v70, v73, s11
	v_add3_u32 v71, v71, v72, s11
	v_and_b32_e32 v69, 0xffff0000, v69
	v_and_b32_e32 v68, 0xffff0000, v68
	v_or_b32_sdwa v69, v69, v71 dst_sel:DWORD dst_unused:UNUSED_PAD src0_sel:DWORD src1_sel:WORD_1
	v_or_b32_sdwa v68, v68, v70 dst_sel:DWORD dst_unused:UNUSED_PAD src0_sel:DWORD src1_sel:WORD_1
	global_store_dwordx2 v[96:97], v[68:69], off offset:2048
	s_nop 0
	ds_read_b128 v[68:71], v135 offset:13312
	v_mov_b32_e32 v73, v66
	v_mov_b32_e32 v66, v93
	v_mov_b32_e32 v72, v92
	v_pk_mul_f32 v[66:67], v[66:67], v[98:99] op_sel_hi:[1,0]
	v_pk_mul_f32 v[72:73], v[72:73], v[98:99] op_sel_hi:[1,0]
	v_mov_b64_e32 v[92:93], v[50:51]
	v_mov_b64_e32 v[76:77], v[30:31]
	s_waitcnt lgkmcnt(0)
	v_mov_b32_e32 v75, v70
	v_mov_b32_e32 v70, v69
	v_mov_b32_e32 v74, v68
	v_pk_mul_f32 v[66:67], v[70:71], v[66:67]
	v_pk_mul_f32 v[68:69], v[74:75], v[72:73]
	v_and_b32_sdwa v72, v67, v124 dst_sel:DWORD dst_unused:UNUSED_PAD src0_sel:WORD_1 src1_sel:DWORD
	v_and_b32_sdwa v73, v66, v124 dst_sel:DWORD dst_unused:UNUSED_PAD src0_sel:WORD_1 src1_sel:DWORD
	v_and_b32_sdwa v70, v69, v124 dst_sel:DWORD dst_unused:UNUSED_PAD src0_sel:WORD_1 src1_sel:DWORD
	v_and_b32_sdwa v71, v68, v124 dst_sel:DWORD dst_unused:UNUSED_PAD src0_sel:WORD_1 src1_sel:DWORD
	v_add3_u32 v67, v67, v72, s11
	v_add3_u32 v66, v66, v73, s11
	v_add3_u32 v68, v68, v71, s11
	v_add3_u32 v69, v69, v70, s11
	v_and_b32_e32 v67, 0xffff0000, v67
	v_and_b32_e32 v66, 0xffff0000, v66
	v_or_b32_sdwa v67, v67, v69 dst_sel:DWORD dst_unused:UNUSED_PAD src0_sel:DWORD src1_sel:WORD_1
	v_or_b32_sdwa v66, v66, v68 dst_sel:DWORD dst_unused:UNUSED_PAD src0_sel:DWORD src1_sel:WORD_1
	global_store_dwordx2 v[96:97], v[66:67], off offset:2560
	s_nop 0
	ds_read_b128 v[66:69], v135 offset:14336
	v_mov_b32_e32 v71, v64
	v_mov_b32_e32 v64, v95
	v_mov_b32_e32 v70, v94
	v_pk_mul_f32 v[64:65], v[64:65], v[98:99] op_sel_hi:[1,0]
	v_pk_mul_f32 v[70:71], v[70:71], v[98:99] op_sel_hi:[1,0]
	v_mov_b64_e32 v[94:95], v[52:53]
	v_mov_b64_e32 v[74:75], v[32:33]
	s_waitcnt lgkmcnt(0)
	v_mov_b32_e32 v73, v68
	v_mov_b32_e32 v68, v67
	v_mov_b32_e32 v72, v66
	v_pk_mul_f32 v[64:65], v[68:69], v[64:65]
	v_pk_mul_f32 v[66:67], v[72:73], v[70:71]
	v_and_b32_sdwa v70, v65, v124 dst_sel:DWORD dst_unused:UNUSED_PAD src0_sel:WORD_1 src1_sel:DWORD
	v_and_b32_sdwa v71, v64, v124 dst_sel:DWORD dst_unused:UNUSED_PAD src0_sel:WORD_1 src1_sel:DWORD
	v_and_b32_sdwa v68, v67, v124 dst_sel:DWORD dst_unused:UNUSED_PAD src0_sel:WORD_1 src1_sel:DWORD
	v_and_b32_sdwa v69, v66, v124 dst_sel:DWORD dst_unused:UNUSED_PAD src0_sel:WORD_1 src1_sel:DWORD
	v_add3_u32 v65, v65, v70, s11
	v_add3_u32 v64, v64, v71, s11
	v_add3_u32 v66, v66, v69, s11
	v_add3_u32 v67, v67, v68, s11
	v_and_b32_e32 v65, 0xffff0000, v65
	v_and_b32_e32 v64, 0xffff0000, v64
	v_or_b32_sdwa v65, v65, v67 dst_sel:DWORD dst_unused:UNUSED_PAD src0_sel:DWORD src1_sel:WORD_1
	v_or_b32_sdwa v64, v64, v66 dst_sel:DWORD dst_unused:UNUSED_PAD src0_sel:DWORD src1_sel:WORD_1
	global_store_dwordx2 v[96:97], v[64:65], off offset:3072
	s_nop 0
	ds_read_b128 v[104:107], v135 offset:15360
	v_mov_b64_e32 v[72:73], v[34:35]
	v_mov_b64_e32 v[70:71], v[36:37]
	v_mov_b64_e32 v[68:69], v[38:39]
	v_mov_b64_e32 v[66:67], v[40:41]
	v_mov_b64_e32 v[64:65], v[42:43]
	s_waitcnt lgkmcnt(0)
	v_mov_b32_e32 v99, v106
	v_mov_b32_e32 v106, v105
	v_mov_b32_e32 v98, v104
	v_pk_mul_f32 v[62:63], v[106:107], v[62:63]
	v_pk_mul_f32 v[88:89], v[98:99], v[88:89]
	v_and_b32_sdwa v100, v63, v124 dst_sel:DWORD dst_unused:UNUSED_PAD src0_sel:WORD_1 src1_sel:DWORD
	v_and_b32_sdwa v101, v62, v124 dst_sel:DWORD dst_unused:UNUSED_PAD src0_sel:WORD_1 src1_sel:DWORD
	v_and_b32_sdwa v98, v89, v124 dst_sel:DWORD dst_unused:UNUSED_PAD src0_sel:WORD_1 src1_sel:DWORD
	v_and_b32_sdwa v99, v88, v124 dst_sel:DWORD dst_unused:UNUSED_PAD src0_sel:WORD_1 src1_sel:DWORD
	v_add3_u32 v63, v63, v100, s11
	v_add3_u32 v62, v62, v101, s11
	v_add3_u32 v88, v88, v99, s11
	v_add3_u32 v89, v89, v98, s11
	v_and_b32_e32 v63, 0xffff0000, v63
	v_and_b32_e32 v62, 0xffff0000, v62
	v_or_b32_sdwa v63, v63, v89 dst_sel:DWORD dst_unused:UNUSED_PAD src0_sel:DWORD src1_sel:WORD_1
	v_or_b32_sdwa v62, v62, v88 dst_sel:DWORD dst_unused:UNUSED_PAD src0_sel:DWORD src1_sel:WORD_1
	global_store_dwordx2 v[96:97], v[62:63], off offset:3584
	v_mov_b64_e32 v[62:63], v[44:45]
	s_cbranch_vccz .LBB0_765

; DI unsigned pk2(float lo, float hi) { return f2bf(lo) | (f2bf(hi) << 16); }
; DI float lo_f(unsigned w) { return __uint_as_float(w << 16); }
; DI float hi_f(unsigned w) { return __uint_as_float(w & 0xffff0000u); }
; template <int MODE, bool FIRST, bool LAST>
; DI void phase_rowpass(const float* xin, const bf16_t* M, const float* gpost, float* outf, bf16_t* HB, bf16_t* XN, const float* gnext, int gw, int NGW, int lane) {
;     ...
;         f32x4 hv[8], mv[8]; float ss = 0.f;
; #pragma unroll
;         for (int j = 0; j < 8; ++j) { const u32x2 w = mw[j]; mv[j] = (f32x4){lo_f(w.x), hi_f(w.x), lo_f(w.y), hi_f(w.y)};
;             if constexpr (FIRST) hv[j] = hc.f[j]; else { const u32x2 hw = hc.f[j]; hv[j] = (f32x4){lo_f(hw.x), hi_f(hw.x), lo_f(hw.y), hi_f(hw.y)}; }
;             ss += (mv[j][0] * mv[j][0] + mv[j][1] * mv[j][1]) + (mv[j][2] * mv[j][2] + mv[j][3] * mv[j][3]); }
;         const float rs = rsqrtf(wave_sum(ss) * (1.f / D_) + EPS);
;         float s2 = 0.f;
; #pragma unroll
;         for (int j = 0; j < 8; ++j) { const f32x4 gv = ((const f32x4*)gpost)[lane + 64 * j]; hv[j] = hv[j] + mv[j] * rs * gv;
;             if constexpr (LAST) ((f32x4*)(outf + (size_t)row * D_) + lane)[64 * j] = hv[j];
;             else { u32x2 w; w.x = pk2(hv[j][0], hv[j][1]); w.y = pk2(hv[j][2], hv[j][3]); ((u32x2*)(HB + (size_t)row * D_) + lane)[64 * j] = w; }
.LBB0_1132:
	v_and_b32_e32 v133, 0xffff0000, v100
	v_and_b32_e32 v132, 0xffff0000, v98
	v_and_b32_e32 v135, 0xffff0000, v101
	v_and_b32_e32 v134, 0xffff0000, v99
	v_lshlrev_b32_e32 v121, 16, v100
	v_lshlrev_b32_e32 v120, 16, v98
	v_lshlrev_b32_e32 v123, 16, v101
	v_lshlrev_b32_e32 v122, 16, v99
	v_pk_mul_f32 v[94:95], v[132:133], v[132:133]
	v_pk_mul_f32 v[98:99], v[134:135], v[134:135]
	v_and_b32_e32 v119, 0xffff0000, v97
	v_and_b32_e32 v118, 0xffff0000, v96
	v_pk_fma_f32 v[94:95], v[120:121], v[120:121], v[94:95]
	v_pk_fma_f32 v[98:99], v[122:123], v[122:123], v[98:99]
	v_lshlrev_b32_e32 v117, 16, v97
	v_lshlrev_b32_e32 v116, 16, v96
	v_pk_mul_f32 v[96:97], v[118:119], v[118:119]
	v_pk_add_f32 v[94:95], v[94:95], v[98:99]
	v_pk_fma_f32 v[96:97], v[116:117], v[116:117], v[96:97]
	v_pk_add_f32 v[94:95], v[94:95], v[94:95] op_sel_hi:[0,1]
	v_pk_add_f32 v[98:99], v[96:97], v[96:97] op_sel_hi:[0,1]
	v_lshlrev_b32_e32 v114, 16, v92
	v_and_b32_e32 v115, 0xffff0000, v92
	v_lshlrev_b32_e32 v92, 16, v93
	v_lshlrev_b32_e32 v96, 16, v90
	v_mul_f32_e32 v97, v114, v114
	v_mul_f32_e32 v101, v115, v115
	v_and_b32_e32 v93, 0xffff0000, v93
	v_mul_f32_e32 v94, v92, v92
	v_mov_b32_e32 v100, v96
	v_pk_fma_f32 v[102:103], v[92:93], v[92:93], v[94:95] op_sel_hi:[1,1,0]
	v_and_b32_e32 v131, 0xffff0000, v90
	v_lshlrev_b32_e32 v106, 16, v91
	v_and_b32_e32 v107, 0xffff0000, v91
	v_pk_add_f32 v[100:101], v[96:97], v[100:101]
	v_mul_f32_e32 v102, v131, v131
	v_mul_f32_e32 v98, v106, v106
	v_mul_f32_e32 v94, v107, v107
	v_mul_f32_e32 v90, v96, v96
	v_mov_b32_e32 v91, v101
	v_pk_add_f32 v[90:91], v[90:91], v[102:103]
	v_pk_add_f32 v[94:95], v[98:99], v[94:95]
	v_lshlrev_b32_e32 v99, 16, v89
	v_pk_add_f32 v[90:91], v[90:91], v[94:95]
	v_lshlrev_b32_e32 v98, 16, v88
	v_pk_add_f32 v[104:105], v[90:91], v[90:91] op_sel_hi:[0,1]
	v_and_b32_e32 v101, 0xffff0000, v89
	v_and_b32_e32 v100, 0xffff0000, v88
	ds_read_b128 v[88:91], v141 offset:0
	v_pk_mul_f32 v[94:95], v[100:101], v[100:101]
	v_lshlrev_b32_e32 v110, 16, v86
	v_pk_fma_f32 v[94:95], v[98:99], v[98:99], v[94:95]
	v_and_b32_e32 v111, 0xffff0000, v86
	v_pk_add_f32 v[136:137], v[94:95], v[94:95] op_sel_hi:[0,1]
	v_lshlrev_b32_e32 v112, 16, v87
	v_lshlrev_b32_e32 v94, 16, v84
	v_mul_f32_e32 v95, v110, v110
	v_mul_f32_e32 v139, v111, v111
	v_and_b32_e32 v113, 0xffff0000, v87
	v_mul_f32_e32 v86, v112, v112
	v_mov_b32_e32 v138, v94
	v_pk_fma_f32 v[86:87], v[112:113], v[112:113], v[86:87] op_sel_hi:[1,1,0]
	v_and_b32_e32 v140, 0xffff0000, v84
	v_lshlrev_b32_e32 v102, 16, v85
	v_and_b32_e32 v103, 0xffff0000, v85
	v_pk_add_f32 v[138:139], v[94:95], v[138:139]
	v_mul_f32_e32 v86, v140, v140
	v_mul_f32_e32 v136, v102, v102
	v_mul_f32_e32 v104, v103, v103
	v_mul_f32_e32 v84, v94, v94
	v_mov_b32_e32 v85, v139
	v_pk_add_f32 v[84:85], v[84:85], v[86:87]
	v_pk_add_f32 v[86:87], v[136:137], v[104:105]
	v_mov_b32_e32 v136, v121
	v_pk_add_f32 v[84:85], v[84:85], v[86:87]
	v_mov_b32_e32 v137, v133
	v_add_f32_e32 v84, v84, v85
	ds_bpermute_b32 v85, v109, v84
	v_mov_b32_e32 v104, v123
	v_mov_b32_e32 v105, v135
	v_and_b32_e32 v87, 0xffff0000, v83
	v_mov_b32_e32 v121, v132
	s_waitcnt lgkmcnt(0)
	v_add_f32_e32 v84, v84, v85
	ds_bpermute_b32 v85, v124, v84
	v_mov_b32_e32 v123, v134
	v_mov_b32_e32 v132, v116
	v_mov_b32_e32 v133, v118
	v_mov_b32_e32 v118, v117
	s_waitcnt lgkmcnt(0)
	v_add_f32_e32 v84, v84, v85
	ds_bpermute_b32 v85, v125, v84
	s_waitcnt lgkmcnt(0)
	v_add_f32_e32 v84, v84, v85
	ds_bpermute_b32 v85, v126, v84
	s_waitcnt lgkmcnt(0)
	v_add_f32_e32 v84, v84, v85
	ds_bpermute_b32 v85, v127, v84
	s_waitcnt lgkmcnt(0)
	v_add_f32_e32 v85, v84, v85
	ds_bpermute_b32 v86, v128, v85
	v_lshlrev_b32_e32 v84, 16, v82
	s_waitcnt lgkmcnt(0)
	v_add_f32_e32 v85, v85, v86
	v_fmamk_f32 v85, v85, 0x3a000000, v129
	v_mul_f32_e32 v86, 0x4b800000, v85
	v_cmp_gt_f32_e32 vcc, s9, v85
	s_nop 1
	v_cndmask_b32_e32 v85, v85, v86, vcc
	v_rsq_f32_e32 v95, v85
	v_and_b32_e32 v85, 0xffff0000, v82
	v_lshlrev_b32_e32 v86, 16, v83
	v_mul_f32_e32 v82, 0x45800000, v95
	v_cndmask_b32_e32 v108, v95, v82, vcc
	v_pk_mul_f32 v[136:137], v[136:137], v[108:109] op_sel_hi:[1,0]
	v_pk_mul_f32 v[104:105], v[104:105], v[108:109] op_sel_hi:[1,0]
	v_lshl_add_u64 v[82:83], s[12:13], 0, v[2:3]
	s_waitcnt vmcnt(0) lgkmcnt(0)
	v_pk_fma_f32 v[84:85], v[88:89], v[136:137], v[84:85]
	v_pk_fma_f32 v[86:87], v[90:91], v[104:105], v[86:87]
	v_and_b32_sdwa v89, v84, v130 dst_sel:DWORD dst_unused:UNUSED_PAD src0_sel:WORD_1 src1_sel:DWORD
	v_add3_u32 v90, v84, v89, s11
	v_and_b32_sdwa v89, v87, v130 dst_sel:DWORD dst_unused:UNUSED_PAD src0_sel:WORD_1 src1_sel:DWORD
	v_and_b32_sdwa v91, v85, v130 dst_sel:DWORD dst_unused:UNUSED_PAD src0_sel:WORD_1 src1_sel:DWORD
	v_and_b32_sdwa v88, v86, v130 dst_sel:DWORD dst_unused:UNUSED_PAD src0_sel:WORD_1 src1_sel:DWORD
	v_add3_u32 v89, v87, v89, s11
	v_add3_u32 v91, v85, v91, s11
	v_add3_u32 v88, v86, v88, s11
	v_and_b32_e32 v89, 0xffff0000, v89
	v_and_b32_e32 v91, 0xffff0000, v91
	v_add_co_u32_e32 v104, vcc, s3, v82
	v_or_b32_sdwa v89, v89, v88 dst_sel:DWORD dst_unused:UNUSED_PAD src0_sel:DWORD src1_sel:WORD_1
	v_or_b32_sdwa v88, v91, v90 dst_sel:DWORD dst_unused:UNUSED_PAD src0_sel:DWORD src1_sel:WORD_1
	v_addc_co_u32_e32 v105, vcc, 0, v83, vcc
	global_store_dwordx2 v[104:105], v[88:89], off
	s_nop 0
	ds_read_b128 v[88:91], v141 offset:1024
	v_lshlrev_b32_e32 v136, 16, v80
	v_and_b32_e32 v137, 0xffff0000, v80
	v_lshlrev_b32_e32 v80, 16, v81
	v_and_b32_e32 v81, 0xffff0000, v81
	v_pk_mul_f32 v[120:121], v[120:121], v[108:109] op_sel_hi:[1,0]
	v_pk_mul_f32 v[122:123], v[122:123], v[108:109] op_sel_hi:[1,0]
	v_pk_mul_f32 v[116:117], v[108:109], v[132:133] op_sel_hi:[0,1]
	v_pk_mul_f32 v[118:119], v[108:109], v[118:119] op_sel_hi:[0,1]
	v_pk_mul_f32 v[114:115], v[114:115], v[108:109] op_sel_hi:[1,0]
	v_pk_mul_f32 v[92:93], v[92:93], v[108:109] op_sel_hi:[1,0]
	v_pk_mul_f32 v[106:107], v[106:107], v[108:109] op_sel_hi:[1,0]
	v_pk_mul_f32 v[102:103], v[102:103], v[108:109] op_sel_hi:[1,0]
	s_add_u32 s12, s12, s14
	s_addc_u32 s13, s13, s15
	s_add_u32 s16, s16, s14
	s_addc_u32 s17, s17, s15
	s_waitcnt lgkmcnt(0)
; DI unsigned pk2(float lo, float hi) { return f2bf(lo) | (f2bf(hi) << 16); }
; template <int MODE, bool FIRST, bool LAST>
; DI void phase_rowpass(const float* xin, const bf16_t* M, const float* gpost, float* outf, bf16_t* HB, bf16_t* XN, const float* gnext, int gw, int NGW, int lane) {
;     ...
;         for (int j = 0; j < 8; ++j) { const f32x4 gv = ((const f32x4*)gpost)[lane + 64 * j]; hv[j] = hv[j] + mv[j] * rs * gv;
;             if constexpr (LAST) ((f32x4*)(outf + (size_t)row * D_) + lane)[64 * j] = hv[j];
;             else { u32x2 w; w.x = pk2(hv[j][0], hv[j][1]); w.y = pk2(hv[j][2], hv[j][3]); ((u32x2*)(HB + (size_t)row * D_) + lane)[64 * j] = w; }
;             s2 += (hv[j][0] * hv[j][0] + hv[j][1] * hv[j][1]) + (hv[j][2] * hv[j][2] + hv[j][3] * hv[j][3]); }
	v_pk_fma_f32 v[80:81], v[90:91], v[122:123], v[80:81]
	v_pk_fma_f32 v[88:89], v[88:89], v[120:121], v[136:137]
	v_and_b32_sdwa v95, v81, v130 dst_sel:DWORD dst_unused:UNUSED_PAD src0_sel:WORD_1 src1_sel:DWORD
	v_and_b32_sdwa v91, v88, v130 dst_sel:DWORD dst_unused:UNUSED_PAD src0_sel:WORD_1 src1_sel:DWORD
	v_and_b32_sdwa v97, v89, v130 dst_sel:DWORD dst_unused:UNUSED_PAD src0_sel:WORD_1 src1_sel:DWORD
	v_and_b32_sdwa v90, v80, v130 dst_sel:DWORD dst_unused:UNUSED_PAD src0_sel:WORD_1 src1_sel:DWORD
	v_add3_u32 v120, v88, v91, s11
	v_add3_u32 v91, v81, v95, s11
	v_add3_u32 v95, v89, v97, s11
	v_add3_u32 v90, v80, v90, s11
	v_and_b32_e32 v91, 0xffff0000, v91
	v_and_b32_e32 v95, 0xffff0000, v95
	v_or_b32_sdwa v91, v91, v90 dst_sel:DWORD dst_unused:UNUSED_PAD src0_sel:DWORD src1_sel:WORD_1
	v_or_b32_sdwa v90, v95, v120 dst_sel:DWORD dst_unused:UNUSED_PAD src0_sel:DWORD src1_sel:WORD_1
	global_store_dwordx2 v[104:105], v[90:91], off offset:512
	s_nop 0
	ds_read_b128 v[120:123], v141 offset:2048
	v_lshlrev_b32_e32 v90, 16, v78
	v_and_b32_e32 v91, 0xffff0000, v78
	v_lshlrev_b32_e32 v78, 16, v79
	v_and_b32_e32 v79, 0xffff0000, v79
	s_waitcnt lgkmcnt(0)
	v_pk_fma_f32 v[78:79], v[122:123], v[118:119], v[78:79]
	v_pk_fma_f32 v[90:91], v[120:121], v[116:117], v[90:91]
	v_and_b32_sdwa v116, v79, v130 dst_sel:DWORD dst_unused:UNUSED_PAD src0_sel:WORD_1 src1_sel:DWORD
	v_and_b32_sdwa v117, v91, v130 dst_sel:DWORD dst_unused:UNUSED_PAD src0_sel:WORD_1 src1_sel:DWORD
	v_and_b32_sdwa v95, v78, v130 dst_sel:DWORD dst_unused:UNUSED_PAD src0_sel:WORD_1 src1_sel:DWORD
	v_and_b32_sdwa v97, v90, v130 dst_sel:DWORD dst_unused:UNUSED_PAD src0_sel:WORD_1 src1_sel:DWORD
	v_add3_u32 v116, v79, v116, s11
	v_add3_u32 v117, v91, v117, s11
	v_add3_u32 v97, v90, v97, s11
	v_add3_u32 v95, v78, v95, s11
	v_and_b32_e32 v116, 0xffff0000, v116
	v_and_b32_e32 v118, 0xffff0000, v117
	v_or_b32_sdwa v117, v116, v95 dst_sel:DWORD dst_unused:UNUSED_PAD src0_sel:DWORD src1_sel:WORD_1
	v_or_b32_sdwa v116, v118, v97 dst_sel:DWORD dst_unused:UNUSED_PAD src0_sel:DWORD src1_sel:WORD_1
	global_store_dwordx2 v[104:105], v[116:117], off offset:1024
	s_nop 0
	ds_read_b128 v[116:119], v141 offset:3072
	v_lshlrev_b32_e32 v120, 16, v76
	v_and_b32_e32 v121, 0xffff0000, v76
	v_lshlrev_b32_e32 v76, 16, v77
	v_and_b32_e32 v77, 0xffff0000, v77
	s_waitcnt lgkmcnt(0)
	v_pk_fma_f32 v[76:77], v[118:119], v[92:93], v[76:77]
	v_pk_fma_f32 v[92:93], v[116:117], v[114:115], v[120:121]
	v_and_b32_sdwa v114, v77, v130 dst_sel:DWORD dst_unused:UNUSED_PAD src0_sel:WORD_1 src1_sel:DWORD
	v_and_b32_sdwa v115, v93, v130 dst_sel:DWORD dst_unused:UNUSED_PAD src0_sel:WORD_1 src1_sel:DWORD
	v_and_b32_sdwa v95, v76, v130 dst_sel:DWORD dst_unused:UNUSED_PAD src0_sel:WORD_1 src1_sel:DWORD
	v_and_b32_sdwa v97, v92, v130 dst_sel:DWORD dst_unused:UNUSED_PAD src0_sel:WORD_1 src1_sel:DWORD
	v_add3_u32 v114, v77, v114, s11
	v_add3_u32 v115, v93, v115, s11
	v_add3_u32 v97, v92, v97, s11
	v_add3_u32 v95, v76, v95, s11
	v_and_b32_e32 v114, 0xffff0000, v114
	v_and_b32_e32 v116, 0xffff0000, v115
	v_or_b32_sdwa v115, v114, v95 dst_sel:DWORD dst_unused:UNUSED_PAD src0_sel:DWORD src1_sel:WORD_1
	v_or_b32_sdwa v114, v116, v97 dst_sel:DWORD dst_unused:UNUSED_PAD src0_sel:DWORD src1_sel:WORD_1
	global_store_dwordx2 v[104:105], v[114:115], off offset:1536
	s_nop 0
	ds_read_b128 v[114:117], v141 offset:4096
	v_mov_b32_e32 v97, v131
	v_lshlrev_b32_e32 v118, 16, v74
	v_and_b32_e32 v119, 0xffff0000, v74
	v_lshlrev_b32_e32 v74, 16, v75
	v_and_b32_e32 v75, 0xffff0000, v75
	v_pk_mul_f32 v[96:97], v[96:97], v[108:109] op_sel_hi:[1,0]
	s_waitcnt lgkmcnt(0)
	v_pk_fma_f32 v[74:75], v[116:117], v[106:107], v[74:75]
	v_pk_fma_f32 v[96:97], v[114:115], v[96:97], v[118:119]
	v_and_b32_sdwa v107, v75, v130 dst_sel:DWORD dst_unused:UNUSED_PAD src0_sel:WORD_1 src1_sel:DWORD
	v_and_b32_sdwa v114, v97, v130 dst_sel:DWORD dst_unused:UNUSED_PAD src0_sel:WORD_1 src1_sel:DWORD
	v_and_b32_sdwa v95, v74, v130 dst_sel:DWORD dst_unused:UNUSED_PAD src0_sel:WORD_1 src1_sel:DWORD
	v_and_b32_sdwa v106, v96, v130 dst_sel:DWORD dst_unused:UNUSED_PAD src0_sel:WORD_1 src1_sel:DWORD
	v_add3_u32 v107, v75, v107, s11
	v_add3_u32 v114, v97, v114, s11
	v_add3_u32 v106, v96, v106, s11
	v_add3_u32 v95, v74, v95, s11
	v_and_b32_e32 v107, 0xffff0000, v107
	v_and_b32_e32 v114, 0xffff0000, v114
	v_or_b32_sdwa v107, v107, v95 dst_sel:DWORD dst_unused:UNUSED_PAD src0_sel:DWORD src1_sel:WORD_1
	v_or_b32_sdwa v106, v114, v106 dst_sel:DWORD dst_unused:UNUSED_PAD src0_sel:DWORD src1_sel:WORD_1
	global_store_dwordx2 v[104:105], v[106:107], off offset:2048
	s_nop 0
	ds_read_b128 v[114:117], v141 offset:5120
	v_mov_b32_e32 v118, v98
	v_mov_b32_e32 v119, v100
	v_mov_b32_e32 v100, v99
	v_lshlrev_b32_e32 v106, 16, v72
	v_and_b32_e32 v107, 0xffff0000, v72
	v_lshlrev_b32_e32 v72, 16, v73
	v_and_b32_e32 v73, 0xffff0000, v73
	v_pk_mul_f32 v[98:99], v[108:109], v[118:119] op_sel_hi:[0,1]
	v_pk_mul_f32 v[100:101], v[108:109], v[100:101] op_sel_hi:[0,1]
	v_mov_b32_e32 v118, v88
	v_mov_b32_e32 v119, v80
	s_waitcnt lgkmcnt(0)
; DI unsigned pk2(float lo, float hi) { return f2bf(lo) | (f2bf(hi) << 16); }
; template <int MODE, bool FIRST, bool LAST>
; DI void phase_rowpass(const float* xin, const bf16_t* M, const float* gpost, float* outf, bf16_t* HB, bf16_t* XN, const float* gnext, int gw, int NGW, int lane) {
;     ...
;         for (int j = 0; j < 8; ++j) { const f32x4 gv = ((const f32x4*)gpost)[lane + 64 * j]; hv[j] = hv[j] + mv[j] * rs * gv;
;             if constexpr (LAST) ((f32x4*)(outf + (size_t)row * D_) + lane)[64 * j] = hv[j];
;             else { u32x2 w; w.x = pk2(hv[j][0], hv[j][1]); w.y = pk2(hv[j][2], hv[j][3]); ((u32x2*)(HB + (size_t)row * D_) + lane)[64 * j] = w; }
;             s2 += (hv[j][0] * hv[j][0] + hv[j][1] * hv[j][1]) + (hv[j][2] * hv[j][2] + hv[j][3] * hv[j][3]); }
;         if (MODE == 1) { const float r2 = rsqrtf(wave_sum(s2) * (1.f / D_) + EPS); u32x2* o = (u32x2*)(XN + (size_t)row * D_) + lane;
	v_pk_fma_f32 v[72:73], v[116:117], v[100:101], v[72:73]
	v_pk_fma_f32 v[98:99], v[114:115], v[98:99], v[106:107]
	v_and_b32_sdwa v101, v73, v130 dst_sel:DWORD dst_unused:UNUSED_PAD src0_sel:WORD_1 src1_sel:DWORD
	v_and_b32_sdwa v106, v99, v130 dst_sel:DWORD dst_unused:UNUSED_PAD src0_sel:WORD_1 src1_sel:DWORD
	v_and_b32_sdwa v95, v72, v130 dst_sel:DWORD dst_unused:UNUSED_PAD src0_sel:WORD_1 src1_sel:DWORD
	v_and_b32_sdwa v100, v98, v130 dst_sel:DWORD dst_unused:UNUSED_PAD src0_sel:WORD_1 src1_sel:DWORD
	v_add3_u32 v101, v73, v101, s11
	v_add3_u32 v106, v99, v106, s11
	v_add3_u32 v100, v98, v100, s11
	v_add3_u32 v95, v72, v95, s11
	v_and_b32_e32 v101, 0xffff0000, v101
	v_and_b32_e32 v106, 0xffff0000, v106
	v_or_b32_sdwa v101, v101, v95 dst_sel:DWORD dst_unused:UNUSED_PAD src0_sel:DWORD src1_sel:WORD_1
	v_or_b32_sdwa v100, v106, v100 dst_sel:DWORD dst_unused:UNUSED_PAD src0_sel:DWORD src1_sel:WORD_1
	global_store_dwordx2 v[104:105], v[100:101], off offset:2560
	s_nop 0
	ds_read_b128 v[114:117], v141 offset:6144
	v_lshlrev_b32_e32 v100, 16, v70
	v_and_b32_e32 v101, 0xffff0000, v70
	v_lshlrev_b32_e32 v70, 16, v71
	v_and_b32_e32 v71, 0xffff0000, v71
	v_pk_mul_f32 v[106:107], v[110:111], v[108:109] op_sel_hi:[1,0]
	v_pk_mul_f32 v[110:111], v[112:113], v[108:109] op_sel_hi:[1,0]
	s_waitcnt lgkmcnt(0)
	v_pk_fma_f32 v[100:101], v[106:107], v[114:115], v[100:101]
	v_pk_fma_f32 v[70:71], v[110:111], v[116:117], v[70:71]
	v_and_b32_sdwa v110, v101, v130 dst_sel:DWORD dst_unused:UNUSED_PAD src0_sel:WORD_1 src1_sel:DWORD
	v_and_b32_sdwa v107, v71, v130 dst_sel:DWORD dst_unused:UNUSED_PAD src0_sel:WORD_1 src1_sel:DWORD
	v_and_b32_sdwa v95, v70, v130 dst_sel:DWORD dst_unused:UNUSED_PAD src0_sel:WORD_1 src1_sel:DWORD
	v_and_b32_sdwa v106, v100, v130 dst_sel:DWORD dst_unused:UNUSED_PAD src0_sel:WORD_1 src1_sel:DWORD
	v_add3_u32 v107, v71, v107, s11
	v_add3_u32 v110, v101, v110, s11
	v_add3_u32 v106, v100, v106, s11
	v_add3_u32 v95, v70, v95, s11
	v_and_b32_e32 v107, 0xffff0000, v107
	v_and_b32_e32 v110, 0xffff0000, v110
	v_or_b32_sdwa v107, v107, v95 dst_sel:DWORD dst_unused:UNUSED_PAD src0_sel:DWORD src1_sel:WORD_1
	v_or_b32_sdwa v106, v110, v106 dst_sel:DWORD dst_unused:UNUSED_PAD src0_sel:DWORD src1_sel:WORD_1
	global_store_dwordx2 v[104:105], v[106:107], off offset:3072
	s_nop 0
	ds_read_b128 v[110:113], v141 offset:7168
	v_mov_b32_e32 v95, v140
	v_lshlrev_b32_e32 v106, 16, v68
	v_and_b32_e32 v107, 0xffff0000, v68
	v_lshlrev_b32_e32 v68, 16, v69
	v_and_b32_e32 v69, 0xffff0000, v69
	v_pk_mul_f32 v[94:95], v[94:95], v[108:109] op_sel_hi:[1,0]
	v_mov_b32_e32 v116, v86
	v_mov_b32_e32 v117, v80
	v_mov_b32_e32 v115, v88
	v_mov_b32_e32 v88, v85
	v_pk_mul_f32 v[116:117], v[116:117], v[116:117]
	v_mov_b32_e32 v80, v87
	v_pk_mul_f32 v[120:121], v[88:89], v[88:89]
	v_pk_fma_f32 v[116:117], v[80:81], v[80:81], v[116:117]
	v_mov_b32_e32 v114, v84
	v_pk_fma_f32 v[114:115], v[114:115], v[114:115], v[120:121]
	v_pk_mul_f32 v[120:121], v[78:79], v[78:79]
	v_pk_add_f32 v[114:115], v[114:115], v[116:117]
	v_pk_mul_f32 v[116:117], v[90:91], v[90:91]
	v_pk_add_f32 v[114:115], v[114:115], v[114:115] op_sel_hi:[0,1]
	v_pk_mov_b32 v[122:123], v[116:117], v[120:121] op_sel:[1,0]
	v_mov_b32_e32 v117, v121
	v_pk_add_f32 v[116:117], v[116:117], v[122:123]
	v_mul_f32_e32 v114, v74, v74
	v_pk_add_f32 v[116:117], v[116:117], v[116:117] op_sel_hi:[0,1]
	v_mul_f32_e32 v116, v75, v75
	s_waitcnt lgkmcnt(0)
	v_pk_fma_f32 v[68:69], v[102:103], v[112:113], v[68:69]
	v_pk_fma_f32 v[94:95], v[94:95], v[110:111], v[106:107]
	v_and_b32_sdwa v102, v69, v130 dst_sel:DWORD dst_unused:UNUSED_PAD src0_sel:WORD_1 src1_sel:DWORD
	v_and_b32_sdwa v103, v95, v130 dst_sel:DWORD dst_unused:UNUSED_PAD src0_sel:WORD_1 src1_sel:DWORD
	v_and_b32_sdwa v80, v68, v130 dst_sel:DWORD dst_unused:UNUSED_PAD src0_sel:WORD_1 src1_sel:DWORD
	v_and_b32_sdwa v88, v94, v130 dst_sel:DWORD dst_unused:UNUSED_PAD src0_sel:WORD_1 src1_sel:DWORD
	v_add3_u32 v102, v69, v102, s11
	v_add3_u32 v103, v95, v103, s11
	v_add3_u32 v88, v94, v88, s11
	v_add3_u32 v80, v68, v80, s11
	v_and_b32_e32 v102, 0xffff0000, v102
	v_and_b32_e32 v106, 0xffff0000, v103
	v_or_b32_sdwa v103, v102, v80 dst_sel:DWORD dst_unused:UNUSED_PAD src0_sel:DWORD src1_sel:WORD_1
	v_or_b32_sdwa v102, v106, v88 dst_sel:DWORD dst_unused:UNUSED_PAD src0_sel:DWORD src1_sel:WORD_1
	global_store_dwordx2 v[104:105], v[102:103], off offset:3584
	s_nop 0
	ds_read_b128 v[110:113], v141 offset:8192
	v_mul_f32_e32 v80, v92, v92
	v_mul_f32_e32 v88, v76, v76
	v_pk_fma_f32 v[102:103], v[92:93], v[92:93], v[80:81] op_sel_hi:[1,1,0]
	v_pk_fma_f32 v[104:105], v[76:77], v[76:77], v[88:89] op_sel_hi:[1,1,0]
	v_mul_f32_e32 v102, v96, v96
	v_mul_f32_e32 v104, v97, v97
	v_pk_add_f32 v[102:103], v[102:103], v[104:105]
	v_pk_add_f32 v[104:105], v[116:117], v[114:115]
	v_pk_mul_f32 v[106:107], v[72:73], v[72:73]
	v_pk_add_f32 v[102:103], v[102:103], v[104:105]
	v_pk_mul_f32 v[104:105], v[98:99], v[98:99]
	v_mul_f32_e32 v80, v100, v100
	v_pk_mov_b32 v[114:115], v[104:105], v[106:107] op_sel:[1,0]
	v_mov_b32_e32 v105, v107
	v_pk_add_f32 v[104:105], v[104:105], v[114:115]
	v_mul_f32_e32 v88, v70, v70
	v_pk_add_f32 v[102:103], v[102:103], v[102:103] op_sel_hi:[0,1]
	v_pk_add_f32 v[104:105], v[104:105], v[104:105] op_sel_hi:[0,1]
	v_pk_fma_f32 v[106:107], v[100:101], v[100:101], v[80:81] op_sel_hi:[1,1,0]
	v_pk_fma_f32 v[114:115], v[70:71], v[70:71], v[88:89] op_sel_hi:[1,1,0]
	v_mul_f32_e32 v106, v94, v94
	v_mul_f32_e32 v114, v95, v95
	v_mul_f32_e32 v102, v68, v68
	v_mul_f32_e32 v104, v69, v69
	v_pk_add_f32 v[106:107], v[106:107], v[114:115]
	v_pk_add_f32 v[102:103], v[104:105], v[102:103]
	s_nop 0
	v_pk_add_f32 v[102:103], v[106:107], v[102:103]
	v_mov_b32_e32 v106, v94
	v_add_f32_e32 v80, v102, v103
	ds_bpermute_b32 v88, v109, v80
	v_add_co_u32_e32 v102, vcc, s20, v82
	v_mov_b32_e32 v82, v84
	s_nop 0
	v_addc_co_u32_e32 v103, vcc, 0, v83, vcc
	s_waitcnt lgkmcnt(0)
; DI unsigned pk2(float lo, float hi) { return f2bf(lo) | (f2bf(hi) << 16); }
; template <int MODE, bool FIRST, bool LAST>
; DI void phase_rowpass(const float* xin, const bf16_t* M, const float* gpost, float* outf, bf16_t* HB, bf16_t* XN, const float* gnext, int gw, int NGW, int lane) {
;     ...
;         if (MODE == 1) { const float r2 = rsqrtf(wave_sum(s2) * (1.f / D_) + EPS); u32x2* o = (u32x2*)(XN + (size_t)row * D_) + lane;
; #pragma unroll
;             for (int j = 0; j < 8; ++j) { const f32x4 gv = ((const f32x4*)gnext)[lane + 64 * j]; u32x2 w; w.x = pk2(hv[j][0] * r2 * gv[0], hv[j][1] * r2 * gv[1]); w.y = pk2(hv[j][2] * r2 * gv[2], hv[j][3] * r2 * gv[3]); o[64 * j] = w; } }
	v_add_f32_e32 v80, v80, v88
	ds_bpermute_b32 v88, v124, v80
	v_mov_b32_e32 v107, v68
	v_mov_b32_e32 v68, v95
	s_waitcnt lgkmcnt(0)
	v_add_f32_e32 v80, v80, v88
	ds_bpermute_b32 v88, v125, v80
	s_waitcnt lgkmcnt(0)
	v_add_f32_e32 v80, v80, v88
	ds_bpermute_b32 v88, v126, v80
	s_waitcnt lgkmcnt(0)
	v_add_f32_e32 v80, v80, v88
	ds_bpermute_b32 v88, v127, v80
	s_waitcnt lgkmcnt(0)
	v_add_f32_e32 v80, v80, v88
	ds_bpermute_b32 v88, v128, v80
	s_waitcnt lgkmcnt(0)
	v_add_f32_e32 v80, v80, v88
	v_fmamk_f32 v80, v80, 0x3a000000, v129
	v_mul_f32_e32 v83, 0x4b800000, v80
	v_cmp_gt_f32_e32 vcc, s9, v80
	s_nop 1
	v_cndmask_b32_e32 v80, v80, v83, vcc
	v_rsq_f32_e32 v80, v80
	v_mov_b32_e32 v83, v86
	v_mov_b32_e32 v86, v85
	v_mul_f32_e32 v84, 0x45800000, v80
	v_cndmask_b32_e32 v104, v80, v84, vcc
	v_pk_mul_f32 v[82:83], v[82:83], v[104:105] op_sel_hi:[1,0]
	v_pk_mul_f32 v[84:85], v[86:87], v[104:105] op_sel_hi:[1,0]
	s_waitcnt lgkmcnt(0)
	v_mov_b32_e32 v86, v110
	v_mov_b32_e32 v87, v112
	v_mov_b32_e32 v112, v111
	v_pk_mul_f32 v[82:83], v[86:87], v[82:83]
	v_pk_mul_f32 v[84:85], v[112:113], v[84:85]
	v_and_b32_sdwa v80, v83, v130 dst_sel:DWORD dst_unused:UNUSED_PAD src0_sel:WORD_1 src1_sel:DWORD
	v_and_b32_sdwa v87, v85, v130 dst_sel:DWORD dst_unused:UNUSED_PAD src0_sel:WORD_1 src1_sel:DWORD
	v_and_b32_sdwa v88, v84, v130 dst_sel:DWORD dst_unused:UNUSED_PAD src0_sel:WORD_1 src1_sel:DWORD
	v_and_b32_sdwa v86, v82, v130 dst_sel:DWORD dst_unused:UNUSED_PAD src0_sel:WORD_1 src1_sel:DWORD
	v_add3_u32 v80, v83, v80, s11
	v_add3_u32 v83, v85, v87, s11
	v_add3_u32 v84, v84, v88, s11
	v_add3_u32 v82, v82, v86, s11
	v_and_b32_e32 v83, 0xffff0000, v83
	v_and_b32_e32 v84, 0xffff0000, v84
	v_or_b32_sdwa v83, v83, v80 dst_sel:DWORD dst_unused:UNUSED_PAD src0_sel:DWORD src1_sel:WORD_1
	v_or_b32_sdwa v82, v84, v82 dst_sel:DWORD dst_unused:UNUSED_PAD src0_sel:DWORD src1_sel:WORD_1
	global_store_dwordx2 v[102:103], v[82:83], off
	s_nop 0
	ds_read_b128 v[82:85], v141 offset:9216
	v_mov_b32_e32 v80, v89
	v_pk_mul_f32 v[80:81], v[80:81], v[104:105] op_sel_hi:[1,0]
	v_pk_mul_f32 v[86:87], v[118:119], v[104:105] op_sel_hi:[1,0]
	v_pk_mul_f32 v[94:95], v[106:107], v[104:105] op_sel_hi:[1,0]
	v_pk_mul_f32 v[68:69], v[68:69], v[104:105] op_sel_hi:[1,0]
	s_andn2_b64 vcc, exec, s[18:19]
	s_waitcnt lgkmcnt(0)
	v_mov_b32_e32 v89, v84
	v_mov_b32_e32 v84, v83
	v_mov_b32_e32 v88, v82
	v_pk_mul_f32 v[80:81], v[84:85], v[80:81]
	v_pk_mul_f32 v[82:83], v[88:89], v[86:87]
	v_and_b32_sdwa v86, v81, v130 dst_sel:DWORD dst_unused:UNUSED_PAD src0_sel:WORD_1 src1_sel:DWORD
	v_and_b32_sdwa v87, v80, v130 dst_sel:DWORD dst_unused:UNUSED_PAD src0_sel:WORD_1 src1_sel:DWORD
	v_and_b32_sdwa v84, v83, v130 dst_sel:DWORD dst_unused:UNUSED_PAD src0_sel:WORD_1 src1_sel:DWORD
	v_and_b32_sdwa v85, v82, v130 dst_sel:DWORD dst_unused:UNUSED_PAD src0_sel:WORD_1 src1_sel:DWORD
	v_add3_u32 v81, v81, v86, s11
	v_add3_u32 v80, v80, v87, s11
	v_add3_u32 v82, v82, v85, s11
	v_add3_u32 v83, v83, v84, s11
	v_and_b32_e32 v81, 0xffff0000, v81
	v_and_b32_e32 v80, 0xffff0000, v80
	v_or_b32_sdwa v81, v81, v83 dst_sel:DWORD dst_unused:UNUSED_PAD src0_sel:DWORD src1_sel:WORD_1
	v_or_b32_sdwa v80, v80, v82 dst_sel:DWORD dst_unused:UNUSED_PAD src0_sel:DWORD src1_sel:WORD_1
	global_store_dwordx2 v[102:103], v[80:81], off offset:512
	s_nop 0
	ds_read_b128 v[80:83], v141 offset:10240
	v_mov_b32_e32 v85, v78
	v_mov_b32_e32 v78, v91
	v_mov_b32_e32 v84, v90
	v_pk_mul_f32 v[78:79], v[78:79], v[104:105] op_sel_hi:[1,0]
	v_pk_mul_f32 v[84:85], v[84:85], v[104:105] op_sel_hi:[1,0]
	v_mov_b64_e32 v[88:89], v[62:63]
	v_mov_b64_e32 v[90:91], v[64:65]
	s_waitcnt lgkmcnt(0)
	v_mov_b32_e32 v87, v82
	v_mov_b32_e32 v82, v81
	v_mov_b32_e32 v86, v80
	v_pk_mul_f32 v[78:79], v[82:83], v[78:79]
	v_pk_mul_f32 v[80:81], v[86:87], v[84:85]
	v_and_b32_sdwa v84, v79, v130 dst_sel:DWORD dst_unused:UNUSED_PAD src0_sel:WORD_1 src1_sel:DWORD
	v_and_b32_sdwa v85, v78, v130 dst_sel:DWORD dst_unused:UNUSED_PAD src0_sel:WORD_1 src1_sel:DWORD
	v_and_b32_sdwa v82, v81, v130 dst_sel:DWORD dst_unused:UNUSED_PAD src0_sel:WORD_1 src1_sel:DWORD
	v_and_b32_sdwa v83, v80, v130 dst_sel:DWORD dst_unused:UNUSED_PAD src0_sel:WORD_1 src1_sel:DWORD
	v_add3_u32 v79, v79, v84, s11
	v_add3_u32 v78, v78, v85, s11
	v_add3_u32 v80, v80, v83, s11
	v_add3_u32 v81, v81, v82, s11
	v_and_b32_e32 v79, 0xffff0000, v79
	v_and_b32_e32 v78, 0xffff0000, v78
	v_or_b32_sdwa v79, v79, v81 dst_sel:DWORD dst_unused:UNUSED_PAD src0_sel:DWORD src1_sel:WORD_1
	v_or_b32_sdwa v78, v78, v80 dst_sel:DWORD dst_unused:UNUSED_PAD src0_sel:DWORD src1_sel:WORD_1
	global_store_dwordx2 v[102:103], v[78:79], off offset:1024
	s_nop 0
	ds_read_b128 v[78:81], v141 offset:11264
	v_mov_b32_e32 v83, v76
	v_mov_b32_e32 v76, v93
	v_mov_b32_e32 v82, v92
	v_pk_mul_f32 v[76:77], v[76:77], v[104:105] op_sel_hi:[1,0]
	v_pk_mul_f32 v[82:83], v[82:83], v[104:105] op_sel_hi:[1,0]
	v_mov_b64_e32 v[86:87], v[60:61]
	v_mov_b64_e32 v[92:93], v[52:53]
	s_waitcnt lgkmcnt(0)
	v_mov_b32_e32 v85, v80
	v_mov_b32_e32 v80, v79
	v_mov_b32_e32 v84, v78
	v_pk_mul_f32 v[76:77], v[80:81], v[76:77]
	v_pk_mul_f32 v[78:79], v[84:85], v[82:83]
	v_and_b32_sdwa v82, v77, v130 dst_sel:DWORD dst_unused:UNUSED_PAD src0_sel:WORD_1 src1_sel:DWORD
	v_and_b32_sdwa v83, v76, v130 dst_sel:DWORD dst_unused:UNUSED_PAD src0_sel:WORD_1 src1_sel:DWORD
	v_and_b32_sdwa v80, v79, v130 dst_sel:DWORD dst_unused:UNUSED_PAD src0_sel:WORD_1 src1_sel:DWORD
	v_and_b32_sdwa v81, v78, v130 dst_sel:DWORD dst_unused:UNUSED_PAD src0_sel:WORD_1 src1_sel:DWORD
	v_add3_u32 v77, v77, v82, s11
	v_add3_u32 v76, v76, v83, s11
	v_add3_u32 v78, v78, v81, s11
	v_add3_u32 v79, v79, v80, s11
	v_and_b32_e32 v77, 0xffff0000, v77
	v_and_b32_e32 v76, 0xffff0000, v76
	v_or_b32_sdwa v77, v77, v79 dst_sel:DWORD dst_unused:UNUSED_PAD src0_sel:DWORD src1_sel:WORD_1
	v_or_b32_sdwa v76, v76, v78 dst_sel:DWORD dst_unused:UNUSED_PAD src0_sel:DWORD src1_sel:WORD_1
	global_store_dwordx2 v[102:103], v[76:77], off offset:1536
	s_nop 0
	ds_read_b128 v[76:79], v141 offset:12288
	v_mov_b32_e32 v81, v74
	v_mov_b32_e32 v74, v97
	v_mov_b32_e32 v80, v96
	v_pk_mul_f32 v[74:75], v[74:75], v[104:105] op_sel_hi:[1,0]
	v_pk_mul_f32 v[80:81], v[80:81], v[104:105] op_sel_hi:[1,0]
	v_mov_b64_e32 v[84:85], v[66:67]
	v_mov_b64_e32 v[96:97], v[54:55]
	s_waitcnt lgkmcnt(0)
; DI unsigned pk2(float lo, float hi) { return f2bf(lo) | (f2bf(hi) << 16); }
; template <int MODE, bool FIRST, bool LAST>
; DI void phase_rowpass(const float* xin, const bf16_t* M, const float* gpost, float* outf, bf16_t* HB, bf16_t* XN, const float* gnext, int gw, int NGW, int lane) {
;     ...
;             for (int j = 0; j < 8; ++j) { const f32x4 gv = ((const f32x4*)gnext)[lane + 64 * j]; u32x2 w; w.x = pk2(hv[j][0] * r2 * gv[0], hv[j][1] * r2 * gv[1]); w.y = pk2(hv[j][2] * r2 * gv[2], hv[j][3] * r2 * gv[3]); o[64 * j] = w; } }
;         if (MODE == 2) { u32x2* o = (u32x2*)(XN + (size_t)row * D_) + lane;
; #pragma unroll
;             for (int j = 0; j < 8; ++j) { u32x2 w; w.x = pk2(hv[j][0], hv[j][1]); w.y = pk2(hv[j][2], hv[j][3]); o[64 * j] = w; } }
;         if (!has) break;
; #pragma unroll
;         for (int j = 0; j < 8; ++j) { hc.f[j] = hn.f[j]; mw[j] = mn[j]; }
;         row = nrow;
	v_mov_b32_e32 v83, v78
	v_mov_b32_e32 v78, v77
	v_mov_b32_e32 v82, v76
	v_pk_mul_f32 v[74:75], v[78:79], v[74:75]
	v_pk_mul_f32 v[76:77], v[82:83], v[80:81]
	v_and_b32_sdwa v80, v75, v130 dst_sel:DWORD dst_unused:UNUSED_PAD src0_sel:WORD_1 src1_sel:DWORD
	v_and_b32_sdwa v81, v74, v130 dst_sel:DWORD dst_unused:UNUSED_PAD src0_sel:WORD_1 src1_sel:DWORD
	v_and_b32_sdwa v78, v77, v130 dst_sel:DWORD dst_unused:UNUSED_PAD src0_sel:WORD_1 src1_sel:DWORD
	v_and_b32_sdwa v79, v76, v130 dst_sel:DWORD dst_unused:UNUSED_PAD src0_sel:WORD_1 src1_sel:DWORD
	v_add3_u32 v75, v75, v80, s11
	v_add3_u32 v74, v74, v81, s11
	v_add3_u32 v76, v76, v79, s11
	v_add3_u32 v77, v77, v78, s11
	v_and_b32_e32 v75, 0xffff0000, v75
	v_and_b32_e32 v74, 0xffff0000, v74
	v_or_b32_sdwa v75, v75, v77 dst_sel:DWORD dst_unused:UNUSED_PAD src0_sel:DWORD src1_sel:WORD_1
	v_or_b32_sdwa v74, v74, v76 dst_sel:DWORD dst_unused:UNUSED_PAD src0_sel:DWORD src1_sel:WORD_1
	global_store_dwordx2 v[102:103], v[74:75], off offset:2048
	s_nop 0
	ds_read_b128 v[74:77], v141 offset:13312
	v_mov_b32_e32 v79, v72
	v_mov_b32_e32 v72, v99
	v_mov_b32_e32 v78, v98
	v_pk_mul_f32 v[72:73], v[72:73], v[104:105] op_sel_hi:[1,0]
	v_pk_mul_f32 v[78:79], v[78:79], v[104:105] op_sel_hi:[1,0]
	v_mov_b64_e32 v[98:99], v[56:57]
	v_mov_b64_e32 v[82:83], v[36:37]
	s_waitcnt lgkmcnt(0)
	v_mov_b32_e32 v81, v76
	v_mov_b32_e32 v76, v75
	v_mov_b32_e32 v80, v74
	v_pk_mul_f32 v[72:73], v[76:77], v[72:73]
	v_pk_mul_f32 v[74:75], v[80:81], v[78:79]
	v_and_b32_sdwa v78, v73, v130 dst_sel:DWORD dst_unused:UNUSED_PAD src0_sel:WORD_1 src1_sel:DWORD
	v_and_b32_sdwa v79, v72, v130 dst_sel:DWORD dst_unused:UNUSED_PAD src0_sel:WORD_1 src1_sel:DWORD
	v_and_b32_sdwa v76, v75, v130 dst_sel:DWORD dst_unused:UNUSED_PAD src0_sel:WORD_1 src1_sel:DWORD
	v_and_b32_sdwa v77, v74, v130 dst_sel:DWORD dst_unused:UNUSED_PAD src0_sel:WORD_1 src1_sel:DWORD
	v_add3_u32 v73, v73, v78, s11
	v_add3_u32 v72, v72, v79, s11
	v_add3_u32 v74, v74, v77, s11
	v_add3_u32 v75, v75, v76, s11
	v_and_b32_e32 v73, 0xffff0000, v73
	v_and_b32_e32 v72, 0xffff0000, v72
	v_or_b32_sdwa v73, v73, v75 dst_sel:DWORD dst_unused:UNUSED_PAD src0_sel:DWORD src1_sel:WORD_1
	v_or_b32_sdwa v72, v72, v74 dst_sel:DWORD dst_unused:UNUSED_PAD src0_sel:DWORD src1_sel:WORD_1
	global_store_dwordx2 v[102:103], v[72:73], off offset:2560
	s_nop 0
	ds_read_b128 v[72:75], v141 offset:14336
	v_mov_b32_e32 v77, v70
	v_mov_b32_e32 v70, v101
	v_mov_b32_e32 v76, v100
	v_pk_mul_f32 v[70:71], v[70:71], v[104:105] op_sel_hi:[1,0]
	v_pk_mul_f32 v[76:77], v[76:77], v[104:105] op_sel_hi:[1,0]
	v_mov_b64_e32 v[100:101], v[58:59]
	v_mov_b64_e32 v[80:81], v[38:39]
	s_waitcnt lgkmcnt(0)
	v_mov_b32_e32 v79, v74
	v_mov_b32_e32 v74, v73
	v_mov_b32_e32 v78, v72
	v_pk_mul_f32 v[70:71], v[74:75], v[70:71]
	v_pk_mul_f32 v[72:73], v[78:79], v[76:77]
	v_and_b32_sdwa v76, v71, v130 dst_sel:DWORD dst_unused:UNUSED_PAD src0_sel:WORD_1 src1_sel:DWORD
	v_and_b32_sdwa v77, v70, v130 dst_sel:DWORD dst_unused:UNUSED_PAD src0_sel:WORD_1 src1_sel:DWORD
	v_and_b32_sdwa v74, v73, v130 dst_sel:DWORD dst_unused:UNUSED_PAD src0_sel:WORD_1 src1_sel:DWORD
	v_and_b32_sdwa v75, v72, v130 dst_sel:DWORD dst_unused:UNUSED_PAD src0_sel:WORD_1 src1_sel:DWORD
	v_add3_u32 v71, v71, v76, s11
	v_add3_u32 v70, v70, v77, s11
	v_add3_u32 v72, v72, v75, s11
	v_add3_u32 v73, v73, v74, s11
	v_and_b32_e32 v71, 0xffff0000, v71
	v_and_b32_e32 v70, 0xffff0000, v70
	v_or_b32_sdwa v71, v71, v73 dst_sel:DWORD dst_unused:UNUSED_PAD src0_sel:DWORD src1_sel:WORD_1
	v_or_b32_sdwa v70, v70, v72 dst_sel:DWORD dst_unused:UNUSED_PAD src0_sel:DWORD src1_sel:WORD_1
	global_store_dwordx2 v[102:103], v[70:71], off offset:3072
	s_nop 0
	ds_read_b128 v[110:113], v141 offset:15360
	v_mov_b64_e32 v[78:79], v[40:41]
	v_mov_b64_e32 v[76:77], v[42:43]
	v_mov_b64_e32 v[74:75], v[44:45]
	v_mov_b64_e32 v[72:73], v[46:47]
	v_mov_b64_e32 v[70:71], v[48:49]
	s_waitcnt lgkmcnt(0)
	v_mov_b32_e32 v105, v112
	v_mov_b32_e32 v112, v111
	v_mov_b32_e32 v104, v110
	v_pk_mul_f32 v[68:69], v[112:113], v[68:69]
	v_pk_mul_f32 v[94:95], v[104:105], v[94:95]
	v_and_b32_sdwa v106, v69, v130 dst_sel:DWORD dst_unused:UNUSED_PAD src0_sel:WORD_1 src1_sel:DWORD
	v_and_b32_sdwa v107, v68, v130 dst_sel:DWORD dst_unused:UNUSED_PAD src0_sel:WORD_1 src1_sel:DWORD
	v_and_b32_sdwa v104, v95, v130 dst_sel:DWORD dst_unused:UNUSED_PAD src0_sel:WORD_1 src1_sel:DWORD
	v_and_b32_sdwa v105, v94, v130 dst_sel:DWORD dst_unused:UNUSED_PAD src0_sel:WORD_1 src1_sel:DWORD
	v_add3_u32 v69, v69, v106, s11
	v_add3_u32 v68, v68, v107, s11
	v_add3_u32 v94, v94, v105, s11
	v_add3_u32 v95, v95, v104, s11
	v_and_b32_e32 v69, 0xffff0000, v69
	v_and_b32_e32 v68, 0xffff0000, v68
	v_or_b32_sdwa v69, v69, v95 dst_sel:DWORD dst_unused:UNUSED_PAD src0_sel:DWORD src1_sel:WORD_1
	v_or_b32_sdwa v68, v68, v94 dst_sel:DWORD dst_unused:UNUSED_PAD src0_sel:DWORD src1_sel:WORD_1
	global_store_dwordx2 v[102:103], v[68:69], off offset:3584
	v_mov_b64_e32 v[68:69], v[50:51]
	s_cbranch_vccz .LBB0_1135

; DI unsigned pk2(float lo, float hi) { return f2bf(lo) | (f2bf(hi) << 16); }
; DI float lo_f(unsigned w) { return __uint_as_float(w << 16); }
; DI float hi_f(unsigned w) { return __uint_as_float(w & 0xffff0000u); }
; template <int MODE, bool FIRST, bool LAST>
; DI void phase_rowpass(const float* xin, const bf16_t* M, const float* gpost, float* outf, bf16_t* HB, bf16_t* XN, const float* gnext, int gw, int NGW, int lane) {
;     ...
;         f32x4 hv[8], mv[8]; float ss = 0.f;
; #pragma unroll
;         for (int j = 0; j < 8; ++j) { const u32x2 w = mw[j]; mv[j] = (f32x4){lo_f(w.x), hi_f(w.x), lo_f(w.y), hi_f(w.y)};
;             if constexpr (FIRST) hv[j] = hc.f[j]; else { const u32x2 hw = hc.f[j]; hv[j] = (f32x4){lo_f(hw.x), hi_f(hw.x), lo_f(hw.y), hi_f(hw.y)}; }
;             ss += (mv[j][0] * mv[j][0] + mv[j][1] * mv[j][1]) + (mv[j][2] * mv[j][2] + mv[j][3] * mv[j][3]); }
;         const float rs = rsqrtf(wave_sum(ss) * (1.f / D_) + EPS);
;         float s2 = 0.f;
; #pragma unroll
;         for (int j = 0; j < 8; ++j) { const f32x4 gv = ((const f32x4*)gpost)[lane + 64 * j]; hv[j] = hv[j] + mv[j] * rs * gv;
;             if constexpr (LAST) ((f32x4*)(outf + (size_t)row * D_) + lane)[64 * j] = hv[j];
;             else { u32x2 w; w.x = pk2(hv[j][0], hv[j][1]); w.y = pk2(hv[j][2], hv[j][3]); ((u32x2*)(HB + (size_t)row * D_) + lane)[64 * j] = w; }
.LBB0_1364:
	ds_read_b128 v[100:103], v118 offset:0
	v_and_b32_e32 v105, 0xffff0000, v84
	v_and_b32_e32 v104, 0xffff0000, v82
	v_and_b32_e32 v109, 0xffff0000, v85
	v_and_b32_e32 v108, 0xffff0000, v83
	v_lshlrev_b32_e32 v93, 16, v84
	v_lshlrev_b32_e32 v92, 16, v82
	v_lshlrev_b32_e32 v107, 16, v85
	v_lshlrev_b32_e32 v106, 16, v83
	v_pk_mul_f32 v[66:67], v[104:105], v[104:105]
	v_pk_mul_f32 v[68:69], v[108:109], v[108:109]
	v_pk_fma_f32 v[66:67], v[92:93], v[92:93], v[66:67]
	v_pk_fma_f32 v[68:69], v[106:107], v[106:107], v[68:69]
	v_and_b32_e32 v91, 0xffff0000, v81
	v_pk_add_f32 v[66:67], v[66:67], v[68:69]
	v_and_b32_e32 v90, 0xffff0000, v80
	v_pk_add_f32 v[66:67], v[66:67], v[66:67] op_sel_hi:[0,1]
	v_lshlrev_b32_e32 v89, 16, v81
	v_lshlrev_b32_e32 v88, 16, v80
	v_pk_mul_f32 v[68:69], v[90:91], v[90:91]
	v_lshlrev_b32_e32 v82, 16, v76
	v_and_b32_e32 v83, 0xffff0000, v76
	v_lshlrev_b32_e32 v84, 16, v77
	v_lshlrev_b32_e32 v80, 16, v74
	v_pk_fma_f32 v[68:69], v[88:89], v[88:89], v[68:69]
	v_mul_f32_e32 v81, v82, v82
	v_mul_f32_e32 v79, v83, v83
	v_and_b32_e32 v85, 0xffff0000, v77
	v_mul_f32_e32 v66, v84, v84
	v_mov_b32_e32 v78, v80
	v_pk_add_f32 v[68:69], v[68:69], v[68:69] op_sel_hi:[0,1]
	v_pk_fma_f32 v[86:87], v[84:85], v[84:85], v[66:67] op_sel_hi:[1,1,0]
	v_and_b32_e32 v116, 0xffff0000, v74
	v_lshlrev_b32_e32 v76, 16, v75
	v_and_b32_e32 v77, 0xffff0000, v75
	v_pk_add_f32 v[78:79], v[80:81], v[78:79]
	v_mul_f32_e32 v86, v116, v116
	v_mul_f32_e32 v68, v76, v76
	v_mul_f32_e32 v66, v77, v77
	v_mul_f32_e32 v74, v80, v80
	v_mov_b32_e32 v75, v79
	v_pk_add_f32 v[74:75], v[74:75], v[86:87]
	v_pk_add_f32 v[66:67], v[68:69], v[66:67]
	v_lshlrev_b32_e32 v86, 16, v64
	v_pk_add_f32 v[66:67], v[74:75], v[66:67]
	v_lshlrev_b32_e32 v75, 16, v71
	v_lshlrev_b32_e32 v74, 16, v70
	v_and_b32_e32 v71, 0xffff0000, v71
	v_and_b32_e32 v70, 0xffff0000, v70
	v_pk_add_f32 v[78:79], v[66:67], v[66:67] op_sel_hi:[0,1]
	v_pk_mul_f32 v[66:67], v[70:71], v[70:71]
	v_and_b32_e32 v87, 0xffff0000, v64
	v_pk_fma_f32 v[66:67], v[74:75], v[74:75], v[66:67]
	v_lshlrev_b32_e32 v64, 16, v65
	v_pk_add_f32 v[110:111], v[66:67], v[66:67] op_sel_hi:[0,1]
	v_mul_f32_e32 v67, v86, v86
	v_and_b32_e32 v65, 0xffff0000, v65
	v_mul_f32_e32 v66, v64, v64
	v_pk_fma_f32 v[114:115], v[64:65], v[64:65], v[66:67] op_sel_hi:[1,1,0]
	v_lshlrev_b32_e32 v66, 16, v62
	v_mul_f32_e32 v113, v87, v87
	v_mov_b32_e32 v112, v66
	v_and_b32_e32 v117, 0xffff0000, v62
	v_lshlrev_b32_e32 v68, 16, v63
	v_and_b32_e32 v69, 0xffff0000, v63
	v_pk_add_f32 v[112:113], v[66:67], v[112:113]
	v_mul_f32_e32 v114, v117, v117
	v_mul_f32_e32 v110, v68, v68
	v_mul_f32_e32 v78, v69, v69
	v_mul_f32_e32 v62, v66, v66
	v_mov_b32_e32 v63, v113
	v_pk_add_f32 v[62:63], v[62:63], v[114:115]
	v_pk_add_f32 v[78:79], v[110:111], v[78:79]
	v_mov_b32_e32 v110, v93
	v_pk_add_f32 v[62:63], v[62:63], v[78:79]
	v_mov_b32_e32 v111, v105
	v_add_f32_e32 v62, v62, v63
	ds_bpermute_b32 v63, v73, v62
	v_mov_b32_e32 v112, v107
	v_mov_b32_e32 v113, v109
	v_lshl_add_u64 v[78:79], s[12:13], 0, v[2:3]
	v_mov_b32_e32 v93, v104
	s_waitcnt lgkmcnt(0)
	v_add_f32_e32 v62, v62, v63
	ds_bpermute_b32 v63, v94, v62
	v_mov_b32_e32 v107, v108
	s_add_u32 s12, s12, s14
	s_addc_u32 s13, s13, s15
	s_add_u32 s16, s16, s14
	s_waitcnt lgkmcnt(0)
	v_add_f32_e32 v62, v62, v63
	ds_bpermute_b32 v63, v95, v62
	s_addc_u32 s17, s17, s15
	s_waitcnt lgkmcnt(0)
	v_add_f32_e32 v62, v62, v63
	ds_bpermute_b32 v63, v96, v62
	s_waitcnt lgkmcnt(0)
	v_add_f32_e32 v62, v62, v63
	ds_bpermute_b32 v63, v97, v62
	s_waitcnt lgkmcnt(0)
	v_add_f32_e32 v63, v62, v63
	ds_bpermute_b32 v67, v98, v63
	v_lshlrev_b32_e32 v62, 16, v60
	s_waitcnt lgkmcnt(0)
	v_add_f32_e32 v63, v63, v67
	v_fmamk_f32 v63, v63, 0x3a000000, v99
	v_mul_f32_e32 v67, 0x4b800000, v63
	v_cmp_gt_f32_e32 vcc, s11, v63
	s_nop 1
	v_cndmask_b32_e32 v63, v63, v67, vcc
	v_rsq_f32_e32 v67, v63
	v_and_b32_e32 v63, 0xffff0000, v60
	v_lshlrev_b32_e32 v60, 16, v61
	v_and_b32_e32 v61, 0xffff0000, v61
	v_mul_f32_e32 v72, 0x45800000, v67
	v_cndmask_b32_e32 v72, v67, v72, vcc
	v_pk_mul_f32 v[110:111], v[110:111], v[72:73] op_sel_hi:[1,0]
	v_pk_mul_f32 v[112:113], v[112:113], v[72:73] op_sel_hi:[1,0]
	s_waitcnt vmcnt(0) lgkmcnt(0)
	v_pk_fma_f32 v[62:63], v[100:101], v[110:111], v[62:63]
	v_pk_fma_f32 v[60:61], v[102:103], v[112:113], v[60:61]
	v_bfe_u32 v67, v62, 16, 1
	v_add3_u32 v62, v62, v67, s20
	v_bfe_u32 v67, v63, 16, 1
	v_lshrrev_b32_e32 v62, 16, v62
	v_add3_u32 v63, v63, v67, s20
	v_and_or_b32 v62, v63, s9, v62
	v_bfe_u32 v63, v60, 16, 1
	v_add3_u32 v60, v60, v63, s20
	v_bfe_u32 v63, v61, 16, 1
	v_lshrrev_b32_e32 v60, 16, v60
	v_add3_u32 v61, v61, v63, s20
	v_add_co_u32_e32 v78, vcc, s3, v78
	v_and_or_b32 v63, v61, s9, v60
	s_nop 0
	v_addc_co_u32_e32 v79, vcc, 0, v79, vcc
	global_store_dwordx2 v[78:79], v[62:63], off
	s_nop 0
	ds_read_b128 v[60:63], v118 offset:1024
	v_lshlrev_b32_e32 v100, 16, v58
	v_and_b32_e32 v101, 0xffff0000, v58
	v_lshlrev_b32_e32 v58, 16, v59
	v_and_b32_e32 v59, 0xffff0000, v59
	v_pk_mul_f32 v[92:93], v[92:93], v[72:73] op_sel_hi:[1,0]
	v_pk_mul_f32 v[102:103], v[106:107], v[72:73] op_sel_hi:[1,0]
	v_pk_mul_f32 v[68:69], v[68:69], v[72:73] op_sel_hi:[1,0]
	s_andn2_b64 vcc, exec, s[18:19]
	s_waitcnt lgkmcnt(0)
; DI unsigned pk2(float lo, float hi) { return f2bf(lo) | (f2bf(hi) << 16); }
; template <int MODE, bool FIRST, bool LAST>
; DI void phase_rowpass(const float* xin, const bf16_t* M, const float* gpost, float* outf, bf16_t* HB, bf16_t* XN, const float* gnext, int gw, int NGW, int lane) {
;     ...
;         for (int j = 0; j < 8; ++j) { const f32x4 gv = ((const f32x4*)gpost)[lane + 64 * j]; hv[j] = hv[j] + mv[j] * rs * gv;
;             if constexpr (LAST) ((f32x4*)(outf + (size_t)row * D_) + lane)[64 * j] = hv[j];
;             else { u32x2 w; w.x = pk2(hv[j][0], hv[j][1]); w.y = pk2(hv[j][2], hv[j][3]); ((u32x2*)(HB + (size_t)row * D_) + lane)[64 * j] = w; }
;             s2 += (hv[j][0] * hv[j][0] + hv[j][1] * hv[j][1]) + (hv[j][2] * hv[j][2] + hv[j][3] * hv[j][3]); }
;         if (MODE == 1) { const float r2 = rsqrtf(wave_sum(s2) * (1.f / D_) + EPS); u32x2* o = (u32x2*)(XN + (size_t)row * D_) + lane;
; #pragma unroll
;             for (int j = 0; j < 8; ++j) { const f32x4 gv = ((const f32x4*)gnext)[lane + 64 * j]; u32x2 w; w.x = pk2(hv[j][0] * r2 * gv[0], hv[j][1] * r2 * gv[1]); w.y = pk2(hv[j][2] * r2 * gv[2], hv[j][3] * r2 * gv[3]); o[64 * j] = w; } }
;         if (MODE == 2) { u32x2* o = (u32x2*)(XN + (size_t)row * D_) + lane;
; #pragma unroll
;             for (int j = 0; j < 8; ++j) { u32x2 w; w.x = pk2(hv[j][0], hv[j][1]); w.y = pk2(hv[j][2], hv[j][3]); o[64 * j] = w; } }
;         if (!has) break;
; #pragma unroll
;         for (int j = 0; j < 8; ++j) { hc.f[j] = hn.f[j]; mw[j] = mn[j]; }
;         row = nrow;
	v_pk_fma_f32 v[58:59], v[62:63], v[102:103], v[58:59]
	v_pk_fma_f32 v[60:61], v[60:61], v[92:93], v[100:101]
	v_bfe_u32 v67, v58, 16, 1
	v_bfe_u32 v62, v60, 16, 1
	v_bfe_u32 v63, v61, 16, 1
	v_bfe_u32 v81, v59, 16, 1
	v_add3_u32 v60, v60, v62, s20
	v_add3_u32 v58, v58, v67, s20
	v_add3_u32 v61, v61, v63, s20
	v_add3_u32 v59, v59, v81, s20
	v_lshrrev_b32_e32 v60, 16, v60
	v_lshrrev_b32_e32 v62, 16, v58
	v_and_or_b32 v58, v61, s9, v60
	v_and_or_b32 v59, v59, s9, v62
	global_store_dwordx2 v[78:79], v[58:59], off offset:512
	s_nop 0
	ds_read_b128 v[58:61], v118 offset:2048
	v_mov_b32_e32 v92, v88
	v_mov_b32_e32 v93, v90
	v_mov_b32_e32 v90, v89
	v_lshlrev_b32_e32 v62, 16, v56
	v_and_b32_e32 v63, 0xffff0000, v56
	v_lshlrev_b32_e32 v56, 16, v57
	v_and_b32_e32 v57, 0xffff0000, v57
	v_pk_mul_f32 v[88:89], v[72:73], v[92:93] op_sel_hi:[0,1]
	v_pk_mul_f32 v[90:91], v[72:73], v[90:91] op_sel_hi:[0,1]
	v_mov_b32_e32 v81, v116
	v_mov_b32_e32 v67, v117
	v_pk_mul_f32 v[66:67], v[66:67], v[72:73] op_sel_hi:[1,0]
	s_waitcnt lgkmcnt(0)
	v_pk_fma_f32 v[56:57], v[60:61], v[90:91], v[56:57]
	v_pk_fma_f32 v[58:59], v[58:59], v[88:89], v[62:63]
	v_bfe_u32 v62, v56, 16, 1
	v_bfe_u32 v60, v58, 16, 1
	v_bfe_u32 v61, v59, 16, 1
	v_bfe_u32 v63, v57, 16, 1
	v_add3_u32 v58, v58, v60, s20
	v_add3_u32 v56, v56, v62, s20
	v_add3_u32 v59, v59, v61, s20
	v_add3_u32 v57, v57, v63, s20
	v_lshrrev_b32_e32 v58, 16, v58
	v_lshrrev_b32_e32 v60, 16, v56
	v_and_or_b32 v56, v59, s9, v58
	v_and_or_b32 v57, v57, s9, v60
	global_store_dwordx2 v[78:79], v[56:57], off offset:1024
	s_nop 0
	ds_read_b128 v[56:59], v118 offset:3072
	v_lshlrev_b32_e32 v60, 16, v54
	v_and_b32_e32 v61, 0xffff0000, v54
	v_lshlrev_b32_e32 v54, 16, v55
	v_and_b32_e32 v55, 0xffff0000, v55
	v_pk_mul_f32 v[62:63], v[82:83], v[72:73] op_sel_hi:[1,0]
	v_pk_mul_f32 v[82:83], v[84:85], v[72:73] op_sel_hi:[1,0]
	v_lshlrev_b32_e32 v90, 16, v16
	v_and_b32_e32 v91, 0xffff0000, v16
	v_lshlrev_b32_e32 v16, 16, v17
	v_and_b32_e32 v17, 0xffff0000, v17
	v_mov_b64_e32 v[84:85], v[40:41]
	s_waitcnt lgkmcnt(0)
	v_pk_fma_f32 v[54:55], v[58:59], v[82:83], v[54:55]
	v_pk_fma_f32 v[56:57], v[56:57], v[62:63], v[60:61]
	v_bfe_u32 v60, v54, 16, 1
	v_bfe_u32 v58, v56, 16, 1
	v_bfe_u32 v59, v57, 16, 1
	v_bfe_u32 v61, v55, 16, 1
	v_add3_u32 v56, v56, v58, s20
	v_add3_u32 v54, v54, v60, s20
	v_add3_u32 v57, v57, v59, s20
	v_add3_u32 v55, v55, v61, s20
	v_lshrrev_b32_e32 v56, 16, v56
	v_lshrrev_b32_e32 v58, 16, v54
	v_and_or_b32 v54, v57, s9, v56
	v_and_or_b32 v55, v55, s9, v58
	global_store_dwordx2 v[78:79], v[54:55], off offset:1536
	s_nop 0
	ds_read_b128 v[54:57], v118 offset:4096
	v_lshlrev_b32_e32 v58, 16, v52
	v_and_b32_e32 v59, 0xffff0000, v52
	v_lshlrev_b32_e32 v52, 16, v53
	v_and_b32_e32 v53, 0xffff0000, v53
	v_pk_mul_f32 v[60:61], v[80:81], v[72:73] op_sel_hi:[1,0]
	v_pk_mul_f32 v[62:63], v[76:77], v[72:73] op_sel_hi:[1,0]
	v_mov_b64_e32 v[76:77], v[34:35]
	v_mov_b64_e32 v[80:81], v[36:37]
	v_mov_b64_e32 v[82:83], v[38:39]
	s_waitcnt lgkmcnt(0)
	v_pk_fma_f32 v[52:53], v[56:57], v[62:63], v[52:53]
	v_pk_fma_f32 v[54:55], v[54:55], v[60:61], v[58:59]
	v_bfe_u32 v58, v52, 16, 1
	v_bfe_u32 v56, v54, 16, 1
	v_bfe_u32 v57, v55, 16, 1
	v_bfe_u32 v59, v53, 16, 1
	v_add3_u32 v54, v54, v56, s20
	v_add3_u32 v52, v52, v58, s20
	v_add3_u32 v55, v55, v57, s20
	v_add3_u32 v53, v53, v59, s20
	v_lshrrev_b32_e32 v54, 16, v54
	v_lshrrev_b32_e32 v56, 16, v52
	v_and_or_b32 v52, v55, s9, v54
	v_and_or_b32 v53, v53, s9, v56
	global_store_dwordx2 v[78:79], v[52:53], off offset:2048
	s_nop 0
	ds_read_b128 v[52:55], v118 offset:5120
	v_mov_b32_e32 v58, v74
	v_mov_b32_e32 v59, v70
	v_mov_b32_e32 v70, v75
	v_lshlrev_b32_e32 v56, 16, v50
	v_and_b32_e32 v57, 0xffff0000, v50
	v_lshlrev_b32_e32 v50, 16, v51
	v_and_b32_e32 v51, 0xffff0000, v51
	v_pk_mul_f32 v[58:59], v[72:73], v[58:59] op_sel_hi:[0,1]
	v_pk_mul_f32 v[60:61], v[72:73], v[70:71] op_sel_hi:[0,1]
	v_mov_b64_e32 v[62:63], v[48:49]
	v_mov_b64_e32 v[70:71], v[44:45]
	v_mov_b64_e32 v[74:75], v[46:47]
	s_waitcnt lgkmcnt(0)
	v_pk_fma_f32 v[50:51], v[54:55], v[60:61], v[50:51]
	v_pk_fma_f32 v[52:53], v[52:53], v[58:59], v[56:57]
	v_bfe_u32 v56, v50, 16, 1
	v_bfe_u32 v54, v52, 16, 1
	v_bfe_u32 v55, v53, 16, 1
	v_bfe_u32 v57, v51, 16, 1
	v_add3_u32 v52, v52, v54, s20
	v_add3_u32 v50, v50, v56, s20
	v_add3_u32 v53, v53, v55, s20
	v_add3_u32 v51, v51, v57, s20
	v_lshrrev_b32_e32 v52, 16, v52
	v_lshrrev_b32_e32 v54, 16, v50
	v_and_or_b32 v50, v53, s9, v52
	v_and_or_b32 v51, v51, s9, v54
	global_store_dwordx2 v[78:79], v[50:51], off offset:2560
	s_nop 0
	ds_read_b128 v[50:53], v118 offset:6144
	v_lshlrev_b32_e32 v54, 16, v32
	v_and_b32_e32 v55, 0xffff0000, v32
	v_lshlrev_b32_e32 v32, 16, v33
	v_and_b32_e32 v33, 0xffff0000, v33
	v_pk_mul_f32 v[56:57], v[86:87], v[72:73] op_sel_hi:[1,0]
	v_pk_mul_f32 v[58:59], v[64:65], v[72:73] op_sel_hi:[1,0]
	v_mov_b64_e32 v[64:65], v[42:43]
	v_mov_b64_e32 v[60:61], v[14:15]
	s_waitcnt lgkmcnt(0)
	v_pk_fma_f32 v[32:33], v[58:59], v[52:53], v[32:33]
	v_pk_fma_f32 v[50:51], v[56:57], v[50:51], v[54:55]
	v_bfe_u32 v54, v32, 16, 1
	v_bfe_u32 v52, v50, 16, 1
	v_bfe_u32 v53, v51, 16, 1
	v_bfe_u32 v55, v33, 16, 1
	v_add3_u32 v50, v50, v52, s20
	v_add3_u32 v32, v32, v54, s20
	v_add3_u32 v51, v51, v53, s20
	v_add3_u32 v33, v33, v55, s20
	v_lshrrev_b32_e32 v50, 16, v50
	v_lshrrev_b32_e32 v52, 16, v32
	v_and_or_b32 v32, v51, s9, v50
	v_and_or_b32 v33, v33, s9, v52
	global_store_dwordx2 v[78:79], v[32:33], off offset:3072
	s_nop 0
	ds_read_b128 v[86:89], v118 offset:7168
	v_mov_b64_e32 v[58:59], v[18:19]
	v_mov_b64_e32 v[56:57], v[20:21]
	v_mov_b64_e32 v[54:55], v[22:23]
	v_mov_b64_e32 v[52:53], v[24:25]
	v_mov_b64_e32 v[50:51], v[26:27]
	v_mov_b64_e32 v[32:33], v[28:29]
	s_waitcnt lgkmcnt(0)
	v_pk_fma_f32 v[16:17], v[68:69], v[88:89], v[16:17]
	v_pk_fma_f32 v[66:67], v[66:67], v[86:87], v[90:91]
	v_bfe_u32 v72, v16, 16, 1
	v_bfe_u32 v68, v66, 16, 1
	v_bfe_u32 v69, v67, 16, 1
	v_bfe_u32 v86, v17, 16, 1
	v_add3_u32 v66, v66, v68, s20
	v_add3_u32 v16, v16, v72, s20
	v_add3_u32 v67, v67, v69, s20
	v_add3_u32 v17, v17, v86, s20
	v_lshrrev_b32_e32 v66, 16, v66
	v_lshrrev_b32_e32 v68, 16, v16
	v_and_or_b32 v16, v67, s9, v66
	v_and_or_b32 v17, v17, s9, v68
	global_store_dwordx2 v[78:79], v[16:17], off offset:3584
	v_mov_b64_e32 v[16:17], v[30:31]
	s_cbranch_vccz .LBB0_1367

; DI float lo_f(unsigned w) { return __uint_as_float(w << 16); }
; DI float hi_f(unsigned w) { return __uint_as_float(w & 0xffff0000u); }
; template <int MODE, bool FIRST, bool LAST>
; DI void phase_rowpass(const float* xin, const bf16_t* M, const float* gpost, float* outf, bf16_t* HB, bf16_t* XN, const float* gnext, int gw, int NGW, int lane) {
;     ...
;         f32x4 hv[8], mv[8]; float ss = 0.f;
; #pragma unroll
;         for (int j = 0; j < 8; ++j) { const u32x2 w = mw[j]; mv[j] = (f32x4){lo_f(w.x), hi_f(w.x), lo_f(w.y), hi_f(w.y)};
;             if constexpr (FIRST) hv[j] = hc.f[j]; else { const u32x2 hw = hc.f[j]; hv[j] = (f32x4){lo_f(hw.x), hi_f(hw.x), lo_f(hw.y), hi_f(hw.y)}; }
;             ss += (mv[j][0] * mv[j][0] + mv[j][1] * mv[j][1]) + (mv[j][2] * mv[j][2] + mv[j][3] * mv[j][3]); }
;         const float rs = rsqrtf(wave_sum(ss) * (1.f / D_) + EPS);
;         float s2 = 0.f;
; #pragma unroll
;         for (int j = 0; j < 8; ++j) { const f32x4 gv = ((const f32x4*)gpost)[lane + 64 * j]; hv[j] = hv[j] + mv[j] * rs * gv;
.LBB0_1459:
	s_waitcnt vmcnt(0)
	v_and_b32_e32 v95, 0xffff0000, v78
	v_and_b32_e32 v94, 0xffff0000, v76
	v_and_b32_e32 v99, 0xffff0000, v79
	v_and_b32_e32 v98, 0xffff0000, v77
	v_and_b32_e32 v103, 0xffff0000, v75
	v_and_b32_e32 v102, 0xffff0000, v74
	v_lshlrev_b32_e32 v93, 16, v78
	v_lshlrev_b32_e32 v92, 16, v76
	v_lshlrev_b32_e32 v97, 16, v79
	v_lshlrev_b32_e32 v96, 16, v77
	v_pk_mul_f32 v[76:77], v[94:95], v[94:95]
	v_pk_mul_f32 v[78:79], v[98:99], v[98:99]
	v_lshlrev_b32_e32 v101, 16, v75
	v_lshlrev_b32_e32 v100, 16, v74
	v_pk_mul_f32 v[74:75], v[102:103], v[102:103]
	v_pk_fma_f32 v[76:77], v[92:93], v[92:93], v[76:77]
	v_pk_fma_f32 v[78:79], v[96:97], v[96:97], v[78:79]
	v_pk_fma_f32 v[74:75], v[100:101], v[100:101], v[74:75]
	v_lshlrev_b32_e32 v104, 16, v72
	v_and_b32_e32 v105, 0xffff0000, v72
	v_lshlrev_b32_e32 v72, 16, v73
	v_pk_add_f32 v[76:77], v[76:77], v[78:79]
	v_pk_add_f32 v[78:79], v[74:75], v[74:75] op_sel_hi:[0,1]
	v_mul_f32_e32 v75, v104, v104
	v_and_b32_e32 v73, 0xffff0000, v73
	v_mul_f32_e32 v74, v72, v72
	v_pk_fma_f32 v[82:83], v[72:73], v[72:73], v[74:75] op_sel_hi:[1,1,0]
	v_lshlrev_b32_e32 v74, 16, v70
	v_mul_f32_e32 v81, v105, v105
	v_mov_b32_e32 v80, v74
	v_pk_add_f32 v[76:77], v[76:77], v[76:77] op_sel_hi:[0,1]
	v_and_b32_e32 v91, 0xffff0000, v70
	v_lshlrev_b32_e32 v70, 16, v71
	v_and_b32_e32 v71, 0xffff0000, v71
	v_pk_add_f32 v[80:81], v[74:75], v[80:81]
	v_mul_f32_e32 v82, v91, v91
	v_mul_f32_e32 v78, v70, v70
	v_mul_f32_e32 v76, v71, v71
	v_mul_f32_e32 v106, v74, v74
	v_mov_b32_e32 v107, v81
	v_pk_add_f32 v[80:81], v[106:107], v[82:83]
	v_pk_add_f32 v[76:77], v[78:79], v[76:77]
	v_lshlrev_b32_e32 v109, 16, v69
	v_pk_add_f32 v[76:77], v[80:81], v[76:77]
	v_lshlrev_b32_e32 v108, 16, v68
	v_pk_add_f32 v[106:107], v[76:77], v[76:77] op_sel_hi:[0,1]
	ds_read_b128 v[76:79], v119 offset:0
	v_and_b32_e32 v69, 0xffff0000, v69
	v_and_b32_e32 v68, 0xffff0000, v68
	v_pk_mul_f32 v[80:81], v[68:69], v[68:69]
	v_lshlrev_b32_e32 v112, 16, v66
	v_pk_fma_f32 v[80:81], v[108:109], v[108:109], v[80:81]
	v_and_b32_e32 v113, 0xffff0000, v66
	v_lshlrev_b32_e32 v66, 16, v67
	v_pk_add_f32 v[110:111], v[80:81], v[80:81] op_sel_hi:[0,1]
	v_mul_f32_e32 v81, v112, v112
	v_and_b32_e32 v67, 0xffff0000, v67
	v_mul_f32_e32 v80, v66, v66
	v_pk_fma_f32 v[116:117], v[66:67], v[66:67], v[80:81] op_sel_hi:[1,1,0]
	v_lshlrev_b32_e32 v80, 16, v64
	v_mul_f32_e32 v115, v113, v113
	v_mov_b32_e32 v114, v80
	v_and_b32_e32 v118, 0xffff0000, v64
	v_lshlrev_b32_e32 v82, 16, v65
	v_and_b32_e32 v83, 0xffff0000, v65
	v_pk_add_f32 v[114:115], v[80:81], v[114:115]
	v_mul_f32_e32 v116, v118, v118
	v_mul_f32_e32 v110, v82, v82
	v_mul_f32_e32 v106, v83, v83
	v_mul_f32_e32 v64, v80, v80
	v_mov_b32_e32 v65, v115
	v_pk_add_f32 v[64:65], v[64:65], v[116:117]
	v_pk_add_f32 v[106:107], v[110:111], v[106:107]
	v_mov_b32_e32 v75, v91
	v_pk_add_f32 v[64:65], v[64:65], v[106:107]
	v_lshlrev_b32_e32 v106, 16, v62
	v_add_f32_e32 v64, v64, v65
	ds_bpermute_b32 v65, v84, v64
	v_and_b32_e32 v107, 0xffff0000, v62
	v_lshlrev_b32_e32 v62, 16, v63
	v_and_b32_e32 v63, 0xffff0000, v63
	v_mov_b32_e32 v81, v118
	s_waitcnt lgkmcnt(0)
	v_add_f32_e32 v64, v64, v65
	ds_bpermute_b32 v65, v85, v64
	v_lshl_add_u64 v[16:17], v[16:17], 0, s[4:5]
	s_waitcnt lgkmcnt(0)
	v_add_f32_e32 v64, v64, v65
	ds_bpermute_b32 v65, v86, v64
	s_waitcnt lgkmcnt(0)
	v_add_f32_e32 v64, v64, v65
	ds_bpermute_b32 v65, v87, v64
	s_waitcnt lgkmcnt(0)
	v_add_f32_e32 v64, v64, v65
	ds_bpermute_b32 v65, v88, v64
	s_waitcnt lgkmcnt(0)
	v_add_f32_e32 v64, v64, v65
	ds_bpermute_b32 v65, v89, v64
	s_waitcnt lgkmcnt(0)
	v_add_f32_e32 v64, v64, v65
	v_fmamk_f32 v64, v64, 0x3a000000, v90
	v_mul_f32_e32 v65, 0x4b800000, v64
	v_cmp_gt_f32_e32 vcc, s3, v64
	s_nop 1
	v_cndmask_b32_e32 v64, v64, v65, vcc
	v_rsq_f32_e32 v64, v64
	s_nop 0
	v_mul_f32_e32 v65, 0x45800000, v64
	v_cndmask_b32_e32 v110, v64, v65, vcc
	v_mov_b32_e32 v64, v93
	v_mov_b32_e32 v65, v95
	v_pk_mul_f32 v[114:115], v[64:65], v[110:111] op_sel_hi:[1,0]
	v_mov_b32_e32 v64, v97
	v_mov_b32_e32 v65, v99
	v_pk_mul_f32 v[64:65], v[64:65], v[110:111] op_sel_hi:[1,0]
	v_mov_b32_e32 v97, v98
	s_waitcnt vmcnt(0) lgkmcnt(0)
; DI unsigned pk2(float lo, float hi) { return f2bf(lo) | (f2bf(hi) << 16); }
; DI float lo_f(unsigned w) { return __uint_as_float(w << 16); }
; DI float hi_f(unsigned w) { return __uint_as_float(w & 0xffff0000u); }
; template <int MODE, bool FIRST, bool LAST>
; DI void phase_rowpass(const float* xin, const bf16_t* M, const float* gpost, float* outf, bf16_t* HB, bf16_t* XN, const float* gnext, int gw, int NGW, int lane) {
;     ...
;         for (int j = 0; j < 8; ++j) { const u32x2 w = mw[j]; mv[j] = (f32x4){lo_f(w.x), hi_f(w.x), lo_f(w.y), hi_f(w.y)};
;             if constexpr (FIRST) hv[j] = hc.f[j]; else { const u32x2 hw = hc.f[j]; hv[j] = (f32x4){lo_f(hw.x), hi_f(hw.x), lo_f(hw.y), hi_f(hw.y)}; }
;             ss += (mv[j][0] * mv[j][0] + mv[j][1] * mv[j][1]) + (mv[j][2] * mv[j][2] + mv[j][3] * mv[j][3]); }
;         const float rs = rsqrtf(wave_sum(ss) * (1.f / D_) + EPS);
;         float s2 = 0.f;
; #pragma unroll
;         for (int j = 0; j < 8; ++j) { const f32x4 gv = ((const f32x4*)gpost)[lane + 64 * j]; hv[j] = hv[j] + mv[j] * rs * gv;
;             if constexpr (LAST) ((f32x4*)(outf + (size_t)row * D_) + lane)[64 * j] = hv[j];
;             else { u32x2 w; w.x = pk2(hv[j][0], hv[j][1]); w.y = pk2(hv[j][2], hv[j][3]); ((u32x2*)(HB + (size_t)row * D_) + lane)[64 * j] = w; }
;             s2 += (hv[j][0] * hv[j][0] + hv[j][1] * hv[j][1]) + (hv[j][2] * hv[j][2] + hv[j][3] * hv[j][3]); }
;         if (MODE == 1) { const float r2 = rsqrtf(wave_sum(s2) * (1.f / D_) + EPS); u32x2* o = (u32x2*)(XN + (size_t)row * D_) + lane;
; #pragma unroll
;             for (int j = 0; j < 8; ++j) { const f32x4 gv = ((const f32x4*)gnext)[lane + 64 * j]; u32x2 w; w.x = pk2(hv[j][0] * r2 * gv[0], hv[j][1] * r2 * gv[1]); w.y = pk2(hv[j][2] * r2 * gv[2], hv[j][3] * r2 * gv[3]); o[64 * j] = w; } }
;         if (MODE == 2) { u32x2* o = (u32x2*)(XN + (size_t)row * D_) + lane;
; #pragma unroll
;             for (int j = 0; j < 8; ++j) { u32x2 w; w.x = pk2(hv[j][0], hv[j][1]); w.y = pk2(hv[j][2], hv[j][3]); o[64 * j] = w; } }
;         if (!has) break;
; #pragma unroll
;         for (int j = 0; j < 8; ++j) { hc.f[j] = hn.f[j]; mw[j] = mn[j]; }
	v_pk_fma_f32 v[64:65], v[78:79], v[64:65], v[62:63]
	v_pk_fma_f32 v[62:63], v[76:77], v[114:115], v[106:107]
	global_store_dwordx4 v[12:13], v[62:65], off offset:-4096
	s_nop 0
	ds_read_b128 v[62:65], v119 offset:1024
	v_mov_b32_e32 v93, v94
	v_lshlrev_b32_e32 v76, 16, v60
	v_and_b32_e32 v77, 0xffff0000, v60
	v_lshlrev_b32_e32 v78, 16, v61
	v_and_b32_e32 v79, 0xffff0000, v61
	v_pk_mul_f32 v[94:95], v[96:97], v[110:111] op_sel_hi:[1,0]
	v_pk_mul_f32 v[60:61], v[92:93], v[110:111] op_sel_hi:[1,0]
	v_pk_mul_f32 v[72:73], v[72:73], v[110:111] op_sel_hi:[1,0]
	v_lshlrev_b32_e32 v96, 16, v14
	v_and_b32_e32 v97, 0xffff0000, v14
	v_lshlrev_b32_e32 v14, 16, v15
	v_and_b32_e32 v15, 0xffff0000, v15
	v_pk_mul_f32 v[82:83], v[82:83], v[110:111] op_sel_hi:[1,0]
	v_pk_mul_f32 v[80:81], v[80:81], v[110:111] op_sel_hi:[1,0]
	s_andn2_b64 vcc, exec, s[6:7]
	s_waitcnt lgkmcnt(0)
	v_pk_fma_f32 v[60:61], v[62:63], v[60:61], v[76:77]
	v_pk_fma_f32 v[62:63], v[64:65], v[94:95], v[78:79]
	global_store_dwordx4 v[12:13], v[60:63], off offset:-3072
	s_nop 0
	ds_read_b128 v[60:63], v119 offset:2048
	v_lshlrev_b32_e32 v64, 16, v58
	v_and_b32_e32 v65, 0xffff0000, v58
	v_lshlrev_b32_e32 v76, 16, v59
	v_and_b32_e32 v77, 0xffff0000, v59
	v_mov_b32_e32 v58, v101
	v_mov_b32_e32 v59, v103
	v_mov_b32_e32 v101, v102
	v_pk_mul_f32 v[78:79], v[110:111], v[58:59] op_sel_hi:[0,1]
	v_pk_mul_f32 v[58:59], v[110:111], v[100:101] op_sel_hi:[0,1]
	s_waitcnt lgkmcnt(0)
	v_pk_fma_f32 v[58:59], v[60:61], v[58:59], v[64:65]
	v_pk_fma_f32 v[60:61], v[62:63], v[78:79], v[76:77]
	global_store_dwordx4 v[12:13], v[58:61], off offset:-2048
	s_nop 0
	ds_read_b128 v[58:61], v119 offset:3072
	v_lshlrev_b32_e32 v62, 16, v56
	v_and_b32_e32 v63, 0xffff0000, v56
	v_lshlrev_b32_e32 v64, 16, v57
	v_and_b32_e32 v65, 0xffff0000, v57
	v_pk_mul_f32 v[56:57], v[104:105], v[110:111] op_sel_hi:[1,0]
	v_mov_b64_e32 v[76:77], v[44:45]
	v_mov_b64_e32 v[78:79], v[46:47]
	s_waitcnt lgkmcnt(0)
	v_pk_fma_f32 v[56:57], v[58:59], v[56:57], v[62:63]
	v_pk_fma_f32 v[58:59], v[60:61], v[72:73], v[64:65]
	global_store_dwordx4 v[12:13], v[56:59], off offset:-1024
	s_nop 0
	ds_read_b128 v[56:59], v119 offset:4096
	v_lshlrev_b32_e32 v60, 16, v38
	v_and_b32_e32 v61, 0xffff0000, v38
	v_lshlrev_b32_e32 v38, 16, v39
	v_and_b32_e32 v39, 0xffff0000, v39
	v_pk_mul_f32 v[62:63], v[70:71], v[110:111] op_sel_hi:[1,0]
	v_pk_mul_f32 v[64:65], v[74:75], v[110:111] op_sel_hi:[1,0]
	v_mov_b64_e32 v[70:71], v[52:53]
	v_mov_b64_e32 v[72:73], v[40:41]
	v_mov_b64_e32 v[74:75], v[42:43]
	s_waitcnt lgkmcnt(0)
	v_pk_fma_f32 v[56:57], v[56:57], v[64:65], v[60:61]
	v_pk_fma_f32 v[58:59], v[58:59], v[62:63], v[38:39]
	global_store_dwordx4 v[12:13], v[56:59], off
	s_nop 0
	ds_read_b128 v[56:59], v119 offset:5120
	v_mov_b32_e32 v60, v109
	v_mov_b32_e32 v61, v69
	v_mov_b32_e32 v109, v68
	v_lshlrev_b32_e32 v38, 16, v20
	v_and_b32_e32 v39, 0xffff0000, v20
	v_lshlrev_b32_e32 v20, 16, v21
	v_and_b32_e32 v21, 0xffff0000, v21
	v_pk_mul_f32 v[60:61], v[110:111], v[60:61] op_sel_hi:[0,1]
	v_pk_mul_f32 v[62:63], v[110:111], v[108:109] op_sel_hi:[0,1]
	v_mov_b64_e32 v[64:65], v[54:55]
	v_mov_b64_e32 v[68:69], v[50:51]
	s_waitcnt lgkmcnt(0)
	v_pk_fma_f32 v[56:57], v[56:57], v[62:63], v[38:39]
	v_pk_fma_f32 v[58:59], v[58:59], v[60:61], v[20:21]
	global_store_dwordx4 v[12:13], v[56:59], off offset:1024
	s_nop 0
	ds_read_b128 v[56:59], v119 offset:6144
	v_lshlrev_b32_e32 v20, 16, v18
	v_and_b32_e32 v21, 0xffff0000, v18
	v_lshlrev_b32_e32 v38, 16, v19
	v_and_b32_e32 v39, 0xffff0000, v19
	v_pk_mul_f32 v[60:61], v[66:67], v[110:111] op_sel_hi:[1,0]
	v_pk_mul_f32 v[18:19], v[112:113], v[110:111] op_sel_hi:[1,0]
	v_mov_b64_e32 v[66:67], v[48:49]
	v_mov_b64_e32 v[62:63], v[22:23]
	s_waitcnt lgkmcnt(0)
	v_pk_fma_f32 v[18:19], v[18:19], v[56:57], v[20:21]
	v_pk_fma_f32 v[20:21], v[60:61], v[58:59], v[38:39]
	global_store_dwordx4 v[12:13], v[18:21], off offset:2048
	s_nop 0
	ds_read_b128 v[92:95], v119 offset:7168
	v_mov_b64_e32 v[60:61], v[24:25]
	v_mov_b64_e32 v[58:59], v[26:27]
	v_mov_b64_e32 v[56:57], v[28:29]
	v_mov_b64_e32 v[38:39], v[30:31]
	v_mov_b64_e32 v[20:21], v[32:33]
	v_mov_b64_e32 v[18:19], v[34:35]
	s_waitcnt lgkmcnt(0)
	v_pk_fma_f32 v[80:81], v[80:81], v[92:93], v[96:97]
	v_pk_fma_f32 v[82:83], v[82:83], v[94:95], v[14:15]
	global_store_dwordx4 v[12:13], v[80:83], off offset:3072
	v_lshl_add_u64 v[12:13], v[12:13], 0, s[0:1]
	v_mov_b64_e32 v[14:15], v[36:37]
	s_cbranch_vccz .LBB0_1462
